# v20: v9 with all 32 value-row loads of a sample-attention item issued after the softmax (none before it)
# speedup vs baseline: 1.0044x; 1.0032x over previous
; #define LAS __attribute__((address_space(3)))
; DI void lbar() { asm volatile("s_waitcnt lgkmcnt(0)" ::: "memory"); __builtin_amdgcn_s_barrier(); asm volatile("" ::: "memory"); }
; DI float wave_sum(float v) { for (int o = 32; o >= 1; o >>= 1) v += __shfl_xor(v, o); return v; }
; DI void attn_sample_item(const Params& p, int item, ldsp lds, int tid_) {
;     ...
;   for (int j = 0; j < 16; ++j) vvA[j] = __builtin_nontemporal_load((const f32x4*)(cv + (size_t)(wid * 32 + j) * 1024 + lane * 4));
;   lbar();
;   if (wid < 4) {
;     float v[4]; float mx = -1e30f;
; #pragma unroll
;     for (int j = 0; j < 4; ++j) { v[j] = SC[wid * 256 + j * 64 + lane]; mx = fmaxf(mx, v[j]); }
;     for (int o = 32; o >= 1; o >>= 1) mx = fmaxf(mx, __shfl_xor(mx, o));
;     float s = 0.f;
; #pragma unroll
;     for (int j = 0; j < 4; ++j) { v[j] = __expf(v[j] - mx); s += v[j]; }
;     s = wave_sum(s); const float inv = 1.f / s;
; #pragma unroll
;     for (int j = 0; j < 4; ++j) SC[wid * 256 + j * 64 + lane] = v[j] * inv;
;   }
; #pragma unroll
;   for (int j = 0; j < 16; ++j) vvB[j] = __builtin_nontemporal_load((const f32x4*)(cv + (size_t)(wid * 32 + 16 + j) * 1024 + lane * 4));
;   lbar();
;   {
;     f32x4 acc[4];
; #pragma unroll
;     for (int t = 0; t < 4; ++t) acc[t] = (f32x4){0.f, 0.f, 0.f, 0.f};
; #pragma unroll
;     for (int t = 0; t < 4; ++t)
; #pragma unroll
;       for (int j4 = 0; j4 < 4; ++j4) { const f32x4 pp = *(const LAS f32x4*)(SC + t * 256 + wid * 32 + j4 * 4);
; #pragma unroll
;         for (int e = 0; e < 4; ++e) acc[t] += pp[e] * vvA[j4 * 4 + e]; }
.LBB0_1603:
	s_or_b64 exec, exec, s[4:5]
	s_add_u32 s4, s14, s30
	s_addc_u32 s5, s15, s31
	v_lshlrev_b32_e32 v0, 4, v223
	v_mov_b32_e32 v1, v145
	v_lshl_add_u64 v[0:1], s[4:5], 0, v[0:1]
	v_lshl_add_u64 v[4:5], v[0:1], 0, v[162:163]
	v_lshl_add_u64 v[6:7], v[0:1], 0, v[166:167]
	global_load_dwordx4 v[100:103], v[4:5], off nt
	global_load_dwordx4 v[92:95], v[6:7], off nt
	v_lshl_add_u64 v[4:5], v[0:1], 0, v[168:169]
	v_lshl_add_u64 v[6:7], v[0:1], 0, v[172:173]
	global_load_dwordx4 v[112:115], v[4:5], off nt
	global_load_dwordx4 v[108:111], v[6:7], off nt
	v_lshl_add_u64 v[4:5], v[0:1], 0, v[176:177]
	v_lshl_add_u64 v[6:7], v[0:1], 0, v[180:181]
	global_load_dwordx4 v[120:123], v[4:5], off nt
	global_load_dwordx4 v[116:119], v[6:7], off nt
	v_lshl_add_u64 v[4:5], v[0:1], 0, v[182:183]
	v_lshl_add_u64 v[6:7], v[0:1], 0, v[186:187]
	global_load_dwordx4 v[124:127], v[4:5], off nt
	global_load_dwordx4 v[104:107], v[6:7], off nt
	v_lshl_add_u64 v[4:5], v[0:1], 0, v[190:191]
	v_lshl_add_u64 v[6:7], v[0:1], 0, v[194:195]
	global_load_dwordx4 v[68:71], v[4:5], off nt
	global_load_dwordx4 v[64:67], v[6:7], off nt
	v_lshl_add_u64 v[4:5], v[0:1], 0, v[198:199]
	v_lshl_add_u64 v[6:7], v[0:1], 0, v[200:201]
	global_load_dwordx4 v[80:83], v[4:5], off nt
	global_load_dwordx4 v[76:79], v[6:7], off nt
	v_lshl_add_u64 v[4:5], v[0:1], 0, v[202:203]
	v_lshl_add_u64 v[6:7], v[0:1], 0, v[204:205]
	global_load_dwordx4 v[88:91], v[4:5], off nt
	global_load_dwordx4 v[84:87], v[6:7], off nt
	v_lshl_add_u64 v[4:5], v[0:1], 0, v[206:207]
	v_lshl_add_u64 v[6:7], v[0:1], 0, v[208:209]
	global_load_dwordx4 v[96:99], v[4:5], off nt
	global_load_dwordx4 v[72:75], v[6:7], off nt
	v_lshl_add_u64 v[2:3], v[0:1], 0, v[146:147]
	v_lshl_add_u64 v[4:5], v[0:1], 0, v[148:149]
	global_load_dwordx4 v[40:43], v[2:3], off nt
	global_load_dwordx4 v[36:39], v[4:5], off nt
	v_lshl_add_u64 v[2:3], v[0:1], 0, v[150:151]
	v_lshl_add_u64 v[4:5], v[0:1], 0, v[152:153]
	global_load_dwordx4 v[48:51], v[2:3], off nt
	global_load_dwordx4 v[44:47], v[4:5], off nt
	v_lshl_add_u64 v[2:3], v[0:1], 0, v[154:155]
	v_lshl_add_u64 v[4:5], v[0:1], 0, v[156:157]
	global_load_dwordx4 v[56:59], v[2:3], off nt
	global_load_dwordx4 v[52:55], v[4:5], off nt
	v_lshl_add_u64 v[2:3], v[0:1], 0, v[158:159]
	v_lshl_add_u64 v[4:5], v[0:1], 0, v[160:161]
	global_load_dwordx4 v[60:63], v[2:3], off nt
	global_load_dwordx4 v[32:35], v[4:5], off nt
	v_lshl_add_u64 v[2:3], v[0:1], 0, v[164:165]
	v_lshl_add_u64 v[4:5], v[0:1], 0, v[170:171]
	global_load_dwordx4 v[12:15], v[2:3], off nt
	s_nop 0
	global_load_dwordx4 v[4:7], v[4:5], off nt
	v_lshl_add_u64 v[2:3], v[0:1], 0, v[174:175]
	v_lshl_add_u64 v[8:9], v[0:1], 0, v[178:179]
	global_load_dwordx4 v[20:23], v[2:3], off nt
	s_nop 0
	global_load_dwordx4 v[8:11], v[8:9], off nt
	v_lshl_add_u64 v[2:3], v[0:1], 0, v[184:185]
	v_lshl_add_u64 v[16:17], v[0:1], 0, v[188:189]
	global_load_dwordx4 v[24:27], v[2:3], off nt
	s_nop 0
	global_load_dwordx4 v[16:19], v[16:17], off nt
	v_lshl_add_u64 v[2:3], v[0:1], 0, v[192:193]
	v_lshl_add_u64 v[0:1], v[0:1], 0, v[196:197]
	global_load_dwordx4 v[28:31], v[2:3], off nt
	s_nop 0
	global_load_dwordx4 v[0:3], v[0:1], off nt
	s_waitcnt lgkmcnt(0)
	s_barrier
	ds_read_b128 v[128:131], v136
	ds_read_b128 v[132:135], v136 offset:16
	ds_read_b128 v[138:141], v136 offset:32
	ds_read_b128 v[146:149], v136 offset:48
	s_add_i32 s4, s28, 0x4000
	s_waitcnt vmcnt(31) lgkmcnt(3)
	v_pk_fma_f32 v[142:143], v[100:101], v[128:129], 0 op_sel_hi:[1,0,0]
	v_pk_fma_f32 v[150:151], v[102:103], v[128:129], 0 op_sel_hi:[1,0,0]
	s_lshl_b32 s26, s26, 1
	s_waitcnt vmcnt(30)
	v_pk_fma_f32 v[150:151], v[94:95], v[128:129], v[150:151] op_sel:[0,1,0]
	v_pk_fma_f32 v[128:129], v[92:93], v[128:129], v[142:143] op_sel:[0,1,0]
	s_waitcnt vmcnt(29)
	v_pk_fma_f32 v[142:143], v[114:115], v[130:131], v[150:151] op_sel_hi:[1,0,1]
	v_pk_fma_f32 v[128:129], v[112:113], v[130:131], v[128:129] op_sel_hi:[1,0,1]
	v_mov_b32_e32 v130, v131
	s_waitcnt vmcnt(28)
	v_pk_fma_f32 v[128:129], v[108:109], v[130:131], v[128:129] op_sel_hi:[1,0,1]
	v_pk_fma_f32 v[130:131], v[110:111], v[130:131], v[142:143] op_sel_hi:[1,0,1]
	s_waitcnt vmcnt(27) lgkmcnt(2)
	v_pk_fma_f32 v[128:129], v[120:121], v[132:133], v[128:129] op_sel_hi:[1,0,1]
	v_pk_fma_f32 v[130:131], v[122:123], v[132:133], v[130:131] op_sel_hi:[1,0,1]
	s_waitcnt vmcnt(26)
	v_pk_fma_f32 v[128:129], v[116:117], v[132:133], v[128:129] op_sel:[0,1,0]
	v_pk_fma_f32 v[130:131], v[118:119], v[132:133], v[130:131] op_sel:[0,1,0]
	s_waitcnt vmcnt(25)
	v_pk_fma_f32 v[128:129], v[124:125], v[134:135], v[128:129] op_sel_hi:[1,0,1]
	v_pk_fma_f32 v[130:131], v[126:127], v[134:135], v[130:131] op_sel_hi:[1,0,1]
	v_mov_b32_e32 v132, v135
	s_waitcnt vmcnt(24)
	v_pk_fma_f32 v[128:129], v[104:105], v[132:133], v[128:129] op_sel_hi:[1,0,1]
	v_pk_fma_f32 v[130:131], v[106:107], v[132:133], v[130:131] op_sel_hi:[1,0,1]
	s_waitcnt vmcnt(23) lgkmcnt(1)
	v_pk_fma_f32 v[128:129], v[68:69], v[138:139], v[128:129] op_sel_hi:[1,0,1]
	v_pk_fma_f32 v[130:131], v[70:71], v[138:139], v[130:131] op_sel_hi:[1,0,1]
	s_waitcnt vmcnt(22)
	v_pk_fma_f32 v[128:129], v[64:65], v[138:139], v[128:129] op_sel:[0,1,0]
	v_pk_fma_f32 v[130:131], v[66:67], v[138:139], v[130:131] op_sel:[0,1,0]
	s_waitcnt vmcnt(21)
	v_pk_fma_f32 v[128:129], v[80:81], v[140:141], v[128:129] op_sel_hi:[1,0,1]
	v_pk_fma_f32 v[130:131], v[82:83], v[140:141], v[130:131] op_sel_hi:[1,0,1]
	v_mov_b32_e32 v132, v141
	s_waitcnt vmcnt(20)
	v_pk_fma_f32 v[128:129], v[76:77], v[132:133], v[128:129] op_sel_hi:[1,0,1]
	v_pk_fma_f32 v[130:131], v[78:79], v[132:133], v[130:131] op_sel_hi:[1,0,1]
	s_waitcnt vmcnt(19) lgkmcnt(0)
; #define LAS __attribute__((address_space(3)))
; DI void attn_sample_item(const Params& p, int item, ldsp lds, int tid_) {
;     ...
; #pragma unroll
;     for (int t = 0; t < 4; ++t)
; #pragma unroll
;       for (int j4 = 0; j4 < 4; ++j4) { const f32x4 pp = *(const LAS f32x4*)(SC + t * 256 + wid * 32 + j4 * 4);
; #pragma unroll
;         for (int e = 0; e < 4; ++e) acc[t] += pp[e] * vvA[j4 * 4 + e]; }
; #pragma unroll
;     for (int t = 0; t < 4; ++t)
; #pragma unroll
;       for (int j4 = 0; j4 < 4; ++j4) { const f32x4 pp = *(const LAS f32x4*)(SC + t * 256 + wid * 32 + 16 + j4 * 4);
; #pragma unroll
;         for (int e = 0; e < 4; ++e) acc[t] += pp[e] * vvB[j4 * 4 + e]; }
	v_pk_fma_f32 v[128:129], v[88:89], v[146:147], v[128:129] op_sel_hi:[1,0,1]
	v_pk_fma_f32 v[130:131], v[90:91], v[146:147], v[130:131] op_sel_hi:[1,0,1]
	s_waitcnt vmcnt(18)
	v_pk_fma_f32 v[128:129], v[84:85], v[146:147], v[128:129] op_sel:[0,1,0]
	v_pk_fma_f32 v[130:131], v[86:87], v[146:147], v[130:131] op_sel:[0,1,0]
	s_waitcnt vmcnt(17)
	v_pk_fma_f32 v[134:135], v[96:97], v[148:149], v[128:129] op_sel_hi:[1,0,1]
	v_pk_fma_f32 v[132:133], v[98:99], v[148:149], v[130:131] op_sel_hi:[1,0,1]
	ds_read_b128 v[128:131], v136 offset:1024
	v_mov_b32_e32 v138, v149
	s_waitcnt vmcnt(16)
	v_pk_fma_f32 v[142:143], v[72:73], v[138:139], v[134:135] op_sel_hi:[1,0,1]
	v_pk_fma_f32 v[150:151], v[74:75], v[138:139], v[132:133] op_sel_hi:[1,0,1]
	ds_read_b128 v[132:135], v136 offset:1040
	s_waitcnt lgkmcnt(1)
	v_pk_fma_f32 v[138:139], v[100:101], v[128:129], 0 op_sel_hi:[1,0,0]
	v_pk_fma_f32 v[140:141], v[102:103], v[128:129], 0 op_sel_hi:[1,0,0]
	ds_read_b128 v[146:149], v136 offset:2064
	v_pk_fma_f32 v[140:141], v[94:95], v[128:129], v[140:141] op_sel:[0,1,0]
	v_pk_fma_f32 v[128:129], v[92:93], v[128:129], v[138:139] op_sel:[0,1,0]
	v_pk_fma_f32 v[138:139], v[114:115], v[130:131], v[140:141] op_sel_hi:[1,0,1]
	v_pk_fma_f32 v[128:129], v[112:113], v[130:131], v[128:129] op_sel_hi:[1,0,1]
	v_mov_b32_e32 v130, v131
	v_pk_fma_f32 v[128:129], v[108:109], v[130:131], v[128:129] op_sel_hi:[1,0,1]
	v_pk_fma_f32 v[130:131], v[110:111], v[130:131], v[138:139] op_sel_hi:[1,0,1]
	s_waitcnt lgkmcnt(1)
	v_pk_fma_f32 v[128:129], v[120:121], v[132:133], v[128:129] op_sel_hi:[1,0,1]
	v_pk_fma_f32 v[130:131], v[122:123], v[132:133], v[130:131] op_sel_hi:[1,0,1]
	v_pk_fma_f32 v[128:129], v[116:117], v[132:133], v[128:129] op_sel:[0,1,0]
	v_pk_fma_f32 v[130:131], v[118:119], v[132:133], v[130:131] op_sel:[0,1,0]
	v_pk_fma_f32 v[138:139], v[124:125], v[134:135], v[128:129] op_sel_hi:[1,0,1]
	v_pk_fma_f32 v[132:133], v[126:127], v[134:135], v[130:131] op_sel_hi:[1,0,1]
	ds_read_b128 v[128:131], v136 offset:1056
	v_mov_b32_e32 v134, v135
	v_pk_fma_f32 v[138:139], v[104:105], v[134:135], v[138:139] op_sel_hi:[1,0,1]
	v_pk_fma_f32 v[140:141], v[106:107], v[134:135], v[132:133] op_sel_hi:[1,0,1]
	ds_read_b128 v[132:135], v136 offset:1072
	s_waitcnt lgkmcnt(1)
	v_pk_fma_f32 v[140:141], v[70:71], v[128:129], v[140:141] op_sel_hi:[1,0,1]
	v_pk_fma_f32 v[138:139], v[68:69], v[128:129], v[138:139] op_sel_hi:[1,0,1]
	s_add_i32 s40, s40, s94
	v_pk_fma_f32 v[138:139], v[64:65], v[128:129], v[138:139] op_sel:[0,1,0]
	v_pk_fma_f32 v[128:129], v[66:67], v[128:129], v[140:141] op_sel:[0,1,0]
	v_pk_fma_f32 v[138:139], v[80:81], v[130:131], v[138:139] op_sel_hi:[1,0,1]
	v_pk_fma_f32 v[128:129], v[82:83], v[130:131], v[128:129] op_sel_hi:[1,0,1]
	v_mov_b32_e32 v130, v131
	v_pk_fma_f32 v[138:139], v[76:77], v[130:131], v[138:139] op_sel_hi:[1,0,1]
	v_pk_fma_f32 v[128:129], v[78:79], v[130:131], v[128:129] op_sel_hi:[1,0,1]
	s_waitcnt lgkmcnt(0)
	v_pk_fma_f32 v[130:131], v[88:89], v[132:133], v[138:139] op_sel_hi:[1,0,1]
	ds_read_b128 v[138:141], v136 offset:2048
	v_pk_fma_f32 v[128:129], v[90:91], v[132:133], v[128:129] op_sel_hi:[1,0,1]
	v_pk_fma_f32 v[130:131], v[84:85], v[132:133], v[130:131] op_sel:[0,1,0]
	v_pk_fma_f32 v[128:129], v[86:87], v[132:133], v[128:129] op_sel:[0,1,0]
	s_add_i32 s0, s0, s1
	v_pk_fma_f32 v[132:133], v[98:99], v[134:135], v[128:129] op_sel_hi:[1,0,1]
	v_pk_fma_f32 v[128:129], v[96:97], v[134:135], v[130:131] op_sel_hi:[1,0,1]
	v_mov_b32_e32 v130, v135
	v_pk_fma_f32 v[128:129], v[72:73], v[130:131], v[128:129] op_sel_hi:[1,0,1]
	v_pk_fma_f32 v[132:133], v[74:75], v[130:131], v[132:133] op_sel_hi:[1,0,1]
	s_waitcnt lgkmcnt(0)
	v_pk_fma_f32 v[130:131], v[100:101], v[138:139], 0 op_sel_hi:[1,0,0]
	v_pk_fma_f32 v[134:135], v[102:103], v[138:139], 0 op_sel_hi:[1,0,0]
	v_pk_fma_f32 v[130:131], v[92:93], v[138:139], v[130:131] op_sel:[0,1,0]
	v_pk_fma_f32 v[134:135], v[94:95], v[138:139], v[134:135] op_sel:[0,1,0]
	v_pk_fma_f32 v[130:131], v[112:113], v[140:141], v[130:131] op_sel_hi:[1,0,1]
	v_pk_fma_f32 v[134:135], v[114:115], v[140:141], v[134:135] op_sel_hi:[1,0,1]
	v_mov_b32_e32 v138, v141
	v_pk_fma_f32 v[130:131], v[108:109], v[138:139], v[130:131] op_sel_hi:[1,0,1]
	v_pk_fma_f32 v[134:135], v[110:111], v[138:139], v[134:135] op_sel_hi:[1,0,1]
	ds_read_b128 v[138:141], v136 offset:2080
	v_pk_fma_f32 v[134:135], v[122:123], v[146:147], v[134:135] op_sel_hi:[1,0,1]
	v_pk_fma_f32 v[130:131], v[120:121], v[146:147], v[130:131] op_sel_hi:[1,0,1]
	v_pk_fma_f32 v[134:135], v[118:119], v[146:147], v[134:135] op_sel:[0,1,0]
	v_pk_fma_f32 v[130:131], v[116:117], v[146:147], v[130:131] op_sel:[0,1,0]
	v_pk_fma_f32 v[134:135], v[126:127], v[148:149], v[134:135] op_sel_hi:[1,0,1]
	v_pk_fma_f32 v[130:131], v[124:125], v[148:149], v[130:131] op_sel_hi:[1,0,1]
	v_mov_b32_e32 v146, v149
	v_pk_fma_f32 v[130:131], v[104:105], v[146:147], v[130:131] op_sel_hi:[1,0,1]
	v_pk_fma_f32 v[134:135], v[106:107], v[146:147], v[134:135] op_sel_hi:[1,0,1]
	ds_read_b128 v[146:149], v136 offset:2096
	s_waitcnt lgkmcnt(1)
	v_pk_fma_f32 v[134:135], v[70:71], v[138:139], v[134:135] op_sel_hi:[1,0,1]
	v_pk_fma_f32 v[130:131], v[68:69], v[138:139], v[130:131] op_sel_hi:[1,0,1]
	v_pk_fma_f32 v[134:135], v[66:67], v[138:139], v[134:135] op_sel:[0,1,0]
	v_pk_fma_f32 v[130:131], v[64:65], v[138:139], v[130:131] op_sel:[0,1,0]
	v_pk_fma_f32 v[134:135], v[82:83], v[140:141], v[134:135] op_sel_hi:[1,0,1]
	v_pk_fma_f32 v[130:131], v[80:81], v[140:141], v[130:131] op_sel_hi:[1,0,1]
	v_mov_b32_e32 v138, v141
	v_pk_fma_f32 v[130:131], v[76:77], v[138:139], v[130:131] op_sel_hi:[1,0,1]
	v_pk_fma_f32 v[134:135], v[78:79], v[138:139], v[134:135] op_sel_hi:[1,0,1]
	ds_read_b128 v[138:141], v136 offset:3072
	s_waitcnt lgkmcnt(1)
; #define LAS __attribute__((address_space(3)))
; DI void attn_sample_item(const Params& p, int item, ldsp lds, int tid_) {
;     ...
; #pragma unroll
;     for (int t = 0; t < 4; ++t)
; #pragma unroll
;       for (int j4 = 0; j4 < 4; ++j4) { const f32x4 pp = *(const LAS f32x4*)(SC + t * 256 + wid * 32 + j4 * 4);
; #pragma unroll
;         for (int e = 0; e < 4; ++e) acc[t] += pp[e] * vvA[j4 * 4 + e]; }
; #pragma unroll
;     for (int t = 0; t < 4; ++t)
; #pragma unroll
;       for (int j4 = 0; j4 < 4; ++j4) { const f32x4 pp = *(const LAS f32x4*)(SC + t * 256 + wid * 32 + 16 + j4 * 4);
; #pragma unroll
;         for (int e = 0; e < 4; ++e) acc[t] += pp[e] * vvB[j4 * 4 + e]; }
	v_pk_fma_f32 v[134:135], v[90:91], v[146:147], v[134:135] op_sel_hi:[1,0,1]
	v_pk_fma_f32 v[130:131], v[88:89], v[146:147], v[130:131] op_sel_hi:[1,0,1]
	v_pk_fma_f32 v[134:135], v[86:87], v[146:147], v[134:135] op_sel:[0,1,0]
	v_pk_fma_f32 v[130:131], v[84:85], v[146:147], v[130:131] op_sel:[0,1,0]
	v_pk_fma_f32 v[134:135], v[98:99], v[148:149], v[134:135] op_sel_hi:[1,0,1]
	v_pk_fma_f32 v[130:131], v[96:97], v[148:149], v[130:131] op_sel_hi:[1,0,1]
	v_mov_b32_e32 v146, v149
	v_pk_fma_f32 v[130:131], v[72:73], v[146:147], v[130:131] op_sel_hi:[1,0,1]
	v_pk_fma_f32 v[134:135], v[74:75], v[146:147], v[134:135] op_sel_hi:[1,0,1]
	ds_read_b128 v[146:149], v136 offset:3088
	s_waitcnt lgkmcnt(1)
	v_pk_fma_f32 v[100:101], v[100:101], v[138:139], 0 op_sel_hi:[1,0,0]
	v_pk_fma_f32 v[102:103], v[102:103], v[138:139], 0 op_sel_hi:[1,0,0]
	v_pk_fma_f32 v[92:93], v[92:93], v[138:139], v[100:101] op_sel:[0,1,0]
	v_pk_fma_f32 v[94:95], v[94:95], v[138:139], v[102:103] op_sel:[0,1,0]
	v_pk_fma_f32 v[92:93], v[112:113], v[140:141], v[92:93] op_sel_hi:[1,0,1]
	v_pk_fma_f32 v[94:95], v[114:115], v[140:141], v[94:95] op_sel_hi:[1,0,1]
	v_mov_b32_e32 v100, v141
	v_pk_fma_f32 v[92:93], v[108:109], v[100:101], v[92:93] op_sel_hi:[1,0,1]
	v_pk_fma_f32 v[94:95], v[110:111], v[100:101], v[94:95] op_sel_hi:[1,0,1]
	s_waitcnt lgkmcnt(0)
	v_pk_fma_f32 v[92:93], v[120:121], v[146:147], v[92:93] op_sel_hi:[1,0,1]
	v_pk_fma_f32 v[94:95], v[122:123], v[146:147], v[94:95] op_sel_hi:[1,0,1]
	v_pk_fma_f32 v[92:93], v[116:117], v[146:147], v[92:93] op_sel:[0,1,0]
	v_pk_fma_f32 v[94:95], v[118:119], v[146:147], v[94:95] op_sel:[0,1,0]
	v_pk_fma_f32 v[102:103], v[124:125], v[148:149], v[92:93] op_sel_hi:[1,0,1]
	v_pk_fma_f32 v[100:101], v[126:127], v[148:149], v[94:95] op_sel_hi:[1,0,1]
	ds_read_b128 v[92:95], v136 offset:3104
	v_mov_b32_e32 v108, v149
	v_pk_fma_f32 v[104:105], v[104:105], v[108:109], v[102:103] op_sel_hi:[1,0,1]
	v_pk_fma_f32 v[106:107], v[106:107], v[108:109], v[100:101] op_sel_hi:[1,0,1]
	ds_read_b128 v[100:103], v136 offset:3120
	s_waitcnt lgkmcnt(1)
	v_pk_fma_f32 v[70:71], v[70:71], v[92:93], v[106:107] op_sel_hi:[1,0,1]
	v_pk_fma_f32 v[68:69], v[68:69], v[92:93], v[104:105] op_sel_hi:[1,0,1]
	v_pk_fma_f32 v[66:67], v[66:67], v[92:93], v[70:71] op_sel:[0,1,0]
	v_pk_fma_f32 v[64:65], v[64:65], v[92:93], v[68:69] op_sel:[0,1,0]
	v_pk_fma_f32 v[66:67], v[82:83], v[94:95], v[66:67] op_sel_hi:[1,0,1]
	v_pk_fma_f32 v[64:65], v[80:81], v[94:95], v[64:65] op_sel_hi:[1,0,1]
	v_mov_b32_e32 v68, v95
	v_pk_fma_f32 v[64:65], v[76:77], v[68:69], v[64:65] op_sel_hi:[1,0,1]
	v_pk_fma_f32 v[66:67], v[78:79], v[68:69], v[66:67] op_sel_hi:[1,0,1]
	ds_read_b128 v[68:71], v136 offset:64
	s_waitcnt lgkmcnt(1)
	v_pk_fma_f32 v[66:67], v[90:91], v[100:101], v[66:67] op_sel_hi:[1,0,1]
	v_pk_fma_f32 v[64:65], v[88:89], v[100:101], v[64:65] op_sel_hi:[1,0,1]
	v_pk_fma_f32 v[66:67], v[86:87], v[100:101], v[66:67] op_sel:[0,1,0]
	v_pk_fma_f32 v[64:65], v[84:85], v[100:101], v[64:65] op_sel:[0,1,0]
	v_pk_fma_f32 v[66:67], v[98:99], v[102:103], v[66:67] op_sel_hi:[1,0,1]
	v_pk_fma_f32 v[64:65], v[96:97], v[102:103], v[64:65] op_sel_hi:[1,0,1]
	v_mov_b32_e32 v76, v103
	v_pk_fma_f32 v[64:65], v[72:73], v[76:77], v[64:65] op_sel_hi:[1,0,1]
	v_pk_fma_f32 v[66:67], v[74:75], v[76:77], v[66:67] op_sel_hi:[1,0,1]
	ds_read_b128 v[72:75], v136 offset:80
	s_waitcnt vmcnt(15) lgkmcnt(1)
	v_pk_fma_f32 v[76:77], v[42:43], v[68:69], v[150:151] op_sel_hi:[1,0,1]
	v_pk_fma_f32 v[78:79], v[40:41], v[68:69], v[142:143] op_sel_hi:[1,0,1]
	s_waitcnt vmcnt(14)
	v_pk_fma_f32 v[76:77], v[38:39], v[68:69], v[76:77] op_sel:[0,1,0]
	v_pk_fma_f32 v[68:69], v[36:37], v[68:69], v[78:79] op_sel:[0,1,0]
	s_waitcnt vmcnt(13)
	v_pk_fma_f32 v[76:77], v[50:51], v[70:71], v[76:77] op_sel_hi:[1,0,1]
	v_pk_fma_f32 v[68:69], v[48:49], v[70:71], v[68:69] op_sel_hi:[1,0,1]
	v_mov_b32_e32 v70, v71
	s_waitcnt vmcnt(12)
	v_pk_fma_f32 v[76:77], v[46:47], v[70:71], v[76:77] op_sel_hi:[1,0,1]
	v_pk_fma_f32 v[68:69], v[44:45], v[70:71], v[68:69] op_sel_hi:[1,0,1]
	s_waitcnt vmcnt(11) lgkmcnt(0)
	v_pk_fma_f32 v[70:71], v[58:59], v[72:73], v[76:77] op_sel_hi:[1,0,1]
	v_pk_fma_f32 v[68:69], v[56:57], v[72:73], v[68:69] op_sel_hi:[1,0,1]
	s_waitcnt vmcnt(10)
	v_pk_fma_f32 v[70:71], v[54:55], v[72:73], v[70:71] op_sel:[0,1,0]
	v_pk_fma_f32 v[68:69], v[52:53], v[72:73], v[68:69] op_sel:[0,1,0]
	s_waitcnt vmcnt(9)
	v_pk_fma_f32 v[72:73], v[62:63], v[74:75], v[70:71] op_sel_hi:[1,0,1]
	v_pk_fma_f32 v[76:77], v[60:61], v[74:75], v[68:69] op_sel_hi:[1,0,1]
	ds_read_b128 v[68:71], v136 offset:96
	v_mov_b32_e32 v74, v75
	s_waitcnt vmcnt(8)
	v_pk_fma_f32 v[78:79], v[34:35], v[74:75], v[72:73] op_sel_hi:[1,0,1]
	v_pk_fma_f32 v[76:77], v[32:33], v[74:75], v[76:77] op_sel_hi:[1,0,1]
	ds_read_b128 v[72:75], v136 offset:112
	s_waitcnt vmcnt(7) lgkmcnt(1)
	v_pk_fma_f32 v[78:79], v[14:15], v[68:69], v[78:79] op_sel_hi:[1,0,1]
	v_pk_fma_f32 v[76:77], v[12:13], v[68:69], v[76:77] op_sel_hi:[1,0,1]
	s_waitcnt vmcnt(6)
	v_pk_fma_f32 v[78:79], v[6:7], v[68:69], v[78:79] op_sel:[0,1,0]
	v_pk_fma_f32 v[68:69], v[4:5], v[68:69], v[76:77] op_sel:[0,1,0]
	s_waitcnt vmcnt(5)
	v_pk_fma_f32 v[76:77], v[22:23], v[70:71], v[78:79] op_sel_hi:[1,0,1]
	v_pk_fma_f32 v[68:69], v[20:21], v[70:71], v[68:69] op_sel_hi:[1,0,1]
	v_mov_b32_e32 v70, v71
	s_waitcnt vmcnt(4)
	v_pk_fma_f32 v[76:77], v[10:11], v[70:71], v[76:77] op_sel_hi:[1,0,1]
	v_pk_fma_f32 v[68:69], v[8:9], v[70:71], v[68:69] op_sel_hi:[1,0,1]
	s_waitcnt vmcnt(3) lgkmcnt(0)
	v_pk_fma_f32 v[70:71], v[26:27], v[72:73], v[76:77] op_sel_hi:[1,0,1]
	v_pk_fma_f32 v[68:69], v[24:25], v[72:73], v[68:69] op_sel_hi:[1,0,1]
	s_waitcnt vmcnt(2)
; #define LAS __attribute__((address_space(3)))
; DI void attn_sample_item(const Params& p, int item, ldsp lds, int tid_) {
;     ...
; #pragma unroll
;     for (int t = 0; t < 4; ++t)
; #pragma unroll
;       for (int j4 = 0; j4 < 4; ++j4) { const f32x4 pp = *(const LAS f32x4*)(SC + t * 256 + wid * 32 + 16 + j4 * 4);
; #pragma unroll
;         for (int e = 0; e < 4; ++e) acc[t] += pp[e] * vvB[j4 * 4 + e]; }
	v_pk_fma_f32 v[70:71], v[18:19], v[72:73], v[70:71] op_sel:[0,1,0]
	v_pk_fma_f32 v[68:69], v[16:17], v[72:73], v[68:69] op_sel:[0,1,0]
	s_waitcnt vmcnt(1)
	v_pk_fma_f32 v[72:73], v[30:31], v[74:75], v[70:71] op_sel_hi:[1,0,1]
	v_pk_fma_f32 v[76:77], v[28:29], v[74:75], v[68:69] op_sel_hi:[1,0,1]
	ds_read_b128 v[68:71], v136 offset:1088
	v_mov_b32_e32 v78, v75
	s_waitcnt vmcnt(0)
	v_pk_fma_f32 v[74:75], v[2:3], v[78:79], v[72:73] op_sel_hi:[1,0,1]
	v_pk_fma_f32 v[72:73], v[0:1], v[78:79], v[76:77] op_sel_hi:[1,0,1]
	ds_read_b128 v[76:79], v136 offset:1104
	s_waitcnt lgkmcnt(1)
	v_pk_fma_f32 v[80:81], v[42:43], v[68:69], v[132:133] op_sel_hi:[1,0,1]
	v_pk_fma_f32 v[82:83], v[40:41], v[68:69], v[128:129] op_sel_hi:[1,0,1]
	v_pk_fma_f32 v[80:81], v[38:39], v[68:69], v[80:81] op_sel:[0,1,0]
	v_pk_fma_f32 v[68:69], v[36:37], v[68:69], v[82:83] op_sel:[0,1,0]
	v_pk_fma_f32 v[80:81], v[50:51], v[70:71], v[80:81] op_sel_hi:[1,0,1]
	v_pk_fma_f32 v[68:69], v[48:49], v[70:71], v[68:69] op_sel_hi:[1,0,1]
	v_mov_b32_e32 v70, v71
	v_pk_fma_f32 v[80:81], v[46:47], v[70:71], v[80:81] op_sel_hi:[1,0,1]
	v_pk_fma_f32 v[68:69], v[44:45], v[70:71], v[68:69] op_sel_hi:[1,0,1]
	s_waitcnt lgkmcnt(0)
	v_pk_fma_f32 v[70:71], v[58:59], v[76:77], v[80:81] op_sel_hi:[1,0,1]
	v_pk_fma_f32 v[68:69], v[56:57], v[76:77], v[68:69] op_sel_hi:[1,0,1]
	v_pk_fma_f32 v[70:71], v[54:55], v[76:77], v[70:71] op_sel:[0,1,0]
	v_pk_fma_f32 v[68:69], v[52:53], v[76:77], v[68:69] op_sel:[0,1,0]
	v_pk_fma_f32 v[76:77], v[62:63], v[78:79], v[70:71] op_sel_hi:[1,0,1]
	v_pk_fma_f32 v[80:81], v[60:61], v[78:79], v[68:69] op_sel_hi:[1,0,1]
	ds_read_b128 v[68:71], v136 offset:1120
	v_mov_b32_e32 v78, v79
	v_pk_fma_f32 v[82:83], v[34:35], v[78:79], v[76:77] op_sel_hi:[1,0,1]
	v_pk_fma_f32 v[80:81], v[32:33], v[78:79], v[80:81] op_sel_hi:[1,0,1]
	ds_read_b128 v[76:79], v136 offset:1136
	s_waitcnt lgkmcnt(1)
	v_pk_fma_f32 v[82:83], v[14:15], v[68:69], v[82:83] op_sel_hi:[1,0,1]
	v_pk_fma_f32 v[80:81], v[12:13], v[68:69], v[80:81] op_sel_hi:[1,0,1]
	v_pk_fma_f32 v[82:83], v[6:7], v[68:69], v[82:83] op_sel:[0,1,0]
	v_pk_fma_f32 v[68:69], v[4:5], v[68:69], v[80:81] op_sel:[0,1,0]
	v_pk_fma_f32 v[80:81], v[22:23], v[70:71], v[82:83] op_sel_hi:[1,0,1]
	v_pk_fma_f32 v[68:69], v[20:21], v[70:71], v[68:69] op_sel_hi:[1,0,1]
	v_mov_b32_e32 v70, v71
	v_pk_fma_f32 v[80:81], v[10:11], v[70:71], v[80:81] op_sel_hi:[1,0,1]
	v_pk_fma_f32 v[68:69], v[8:9], v[70:71], v[68:69] op_sel_hi:[1,0,1]
	s_waitcnt lgkmcnt(0)
	v_pk_fma_f32 v[70:71], v[26:27], v[76:77], v[80:81] op_sel_hi:[1,0,1]
	v_pk_fma_f32 v[68:69], v[24:25], v[76:77], v[68:69] op_sel_hi:[1,0,1]
	v_pk_fma_f32 v[70:71], v[18:19], v[76:77], v[70:71] op_sel:[0,1,0]
	v_pk_fma_f32 v[68:69], v[16:17], v[76:77], v[68:69] op_sel:[0,1,0]
	v_pk_fma_f32 v[76:77], v[30:31], v[78:79], v[70:71] op_sel_hi:[1,0,1]
	v_pk_fma_f32 v[80:81], v[28:29], v[78:79], v[68:69] op_sel_hi:[1,0,1]
	ds_read_b128 v[68:71], v136 offset:2112
	v_mov_b32_e32 v82, v79
	v_pk_fma_f32 v[78:79], v[2:3], v[82:83], v[76:77] op_sel_hi:[1,0,1]
	v_pk_fma_f32 v[76:77], v[0:1], v[82:83], v[80:81] op_sel_hi:[1,0,1]
	ds_read_b128 v[80:83], v136 offset:2128
	s_waitcnt lgkmcnt(1)
	v_pk_fma_f32 v[84:85], v[42:43], v[68:69], v[134:135] op_sel_hi:[1,0,1]
	v_pk_fma_f32 v[86:87], v[40:41], v[68:69], v[130:131] op_sel_hi:[1,0,1]
	v_pk_fma_f32 v[84:85], v[38:39], v[68:69], v[84:85] op_sel:[0,1,0]
	v_pk_fma_f32 v[68:69], v[36:37], v[68:69], v[86:87] op_sel:[0,1,0]
	v_pk_fma_f32 v[84:85], v[50:51], v[70:71], v[84:85] op_sel_hi:[1,0,1]
	v_pk_fma_f32 v[68:69], v[48:49], v[70:71], v[68:69] op_sel_hi:[1,0,1]
	v_mov_b32_e32 v70, v71
	v_pk_fma_f32 v[84:85], v[46:47], v[70:71], v[84:85] op_sel_hi:[1,0,1]
	v_pk_fma_f32 v[68:69], v[44:45], v[70:71], v[68:69] op_sel_hi:[1,0,1]
	s_waitcnt lgkmcnt(0)
	v_pk_fma_f32 v[70:71], v[58:59], v[80:81], v[84:85] op_sel_hi:[1,0,1]
	v_pk_fma_f32 v[68:69], v[56:57], v[80:81], v[68:69] op_sel_hi:[1,0,1]
	v_pk_fma_f32 v[70:71], v[54:55], v[80:81], v[70:71] op_sel:[0,1,0]
	v_pk_fma_f32 v[68:69], v[52:53], v[80:81], v[68:69] op_sel:[0,1,0]
	v_pk_fma_f32 v[80:81], v[62:63], v[82:83], v[70:71] op_sel_hi:[1,0,1]
	v_pk_fma_f32 v[84:85], v[60:61], v[82:83], v[68:69] op_sel_hi:[1,0,1]
	ds_read_b128 v[68:71], v136 offset:2144
	v_mov_b32_e32 v82, v83
	v_pk_fma_f32 v[86:87], v[34:35], v[82:83], v[80:81] op_sel_hi:[1,0,1]
	v_pk_fma_f32 v[84:85], v[32:33], v[82:83], v[84:85] op_sel_hi:[1,0,1]
	ds_read_b128 v[80:83], v136 offset:2160
	s_waitcnt lgkmcnt(1)
	v_pk_fma_f32 v[86:87], v[14:15], v[68:69], v[86:87] op_sel_hi:[1,0,1]
	v_pk_fma_f32 v[84:85], v[12:13], v[68:69], v[84:85] op_sel_hi:[1,0,1]
	v_pk_fma_f32 v[86:87], v[6:7], v[68:69], v[86:87] op_sel:[0,1,0]
	v_pk_fma_f32 v[68:69], v[4:5], v[68:69], v[84:85] op_sel:[0,1,0]
	v_pk_fma_f32 v[84:85], v[22:23], v[70:71], v[86:87] op_sel_hi:[1,0,1]
	v_pk_fma_f32 v[68:69], v[20:21], v[70:71], v[68:69] op_sel_hi:[1,0,1]
	v_mov_b32_e32 v70, v71
	v_pk_fma_f32 v[84:85], v[10:11], v[70:71], v[84:85] op_sel_hi:[1,0,1]
	v_pk_fma_f32 v[68:69], v[8:9], v[70:71], v[68:69] op_sel_hi:[1,0,1]
	s_waitcnt lgkmcnt(0)
	v_pk_fma_f32 v[70:71], v[26:27], v[80:81], v[84:85] op_sel_hi:[1,0,1]
	v_pk_fma_f32 v[68:69], v[24:25], v[80:81], v[68:69] op_sel_hi:[1,0,1]
	v_pk_fma_f32 v[70:71], v[18:19], v[80:81], v[70:71] op_sel:[0,1,0]
	v_pk_fma_f32 v[68:69], v[16:17], v[80:81], v[68:69] op_sel:[0,1,0]
	v_pk_fma_f32 v[80:81], v[30:31], v[82:83], v[70:71] op_sel_hi:[1,0,1]
	v_pk_fma_f32 v[84:85], v[28:29], v[82:83], v[68:69] op_sel_hi:[1,0,1]
	ds_read_b128 v[68:71], v136 offset:3136
	v_mov_b32_e32 v86, v83
	v_pk_fma_f32 v[82:83], v[2:3], v[86:87], v[80:81] op_sel_hi:[1,0,1]
	v_pk_fma_f32 v[80:81], v[0:1], v[86:87], v[84:85] op_sel_hi:[1,0,1]
	ds_read_b128 v[84:87], v136 offset:3152
	s_waitcnt lgkmcnt(1)
; #define LAS __attribute__((address_space(3)))
; DI unsigned pk2(float lo, float hi) { f32x2 v = {lo, hi}; return __builtin_bit_cast(unsigned, __builtin_convertvector(v, bf16x2v)); }
; DI void lbar() { asm volatile("s_waitcnt lgkmcnt(0)" ::: "memory"); __builtin_amdgcn_s_barrier(); asm volatile("" ::: "memory"); }
; DI void attn_sample_item(const Params& p, int item, ldsp lds, int tid_) {
;     ...
;   for (int t = 0; t < 4; ++t) { f32x4 a = {0.f, 0.f, 0.f, 0.f}; const float* pp = (const float*)(p.ws + B_PART) + (size_t)(b * 4 + t) * 1024 + h * 256 + lane * 4;
; #pragma unroll
;     for (int kp = 0; kp < 4; ++kp) a += *(const f32x4*)(pp + (size_t)kp * 512 * 1024);
;     q[t][0] = a[0] * 0.0625f; q[t][1] = a[1] * 0.0625f; q[t][2] = a[2] * 0.0625f; q[t][3] = a[3] * 0.0625f; }
;     ...
; #pragma unroll
;     for (int t = 0; t < 4; ++t)
; #pragma unroll
;       for (int j4 = 0; j4 < 4; ++j4) { const f32x4 pp = *(const LAS f32x4*)(SC + t * 256 + wid * 32 + 16 + j4 * 4);
; #pragma unroll
;         for (int e = 0; e < 4; ++e) acc[t] += pp[e] * vvB[j4 * 4 + e]; }
; #pragma unroll
;     for (int t = 0; t < 4; ++t) *(LAS f32x4*)(PART + (wid * 4 + t) * 256 + lane * 4) = acc[t];
;   }
;   lbar();
;   {
;     const int e0 = tid * 2, t = e0 >> 8, d = e0 & 255;
;     float s0 = 0.f, s1 = 0.f;
; #pragma unroll
;     for (int w = 0; w < 8; ++w) { const f32x2 v = *(const LAS f32x2*)(PART + (w * 4 + t) * 256 + d); s0 += v[0]; s1 += v[1]; }
;     *(unsigned*)((bf16_t*)(p.ws + B_XA) + (size_t)(TP + b * 4 + t) * D + h * 256 + d) = pk2(s0, s1);
;   }
;   lbar();
	v_pk_fma_f32 v[42:43], v[42:43], v[68:69], v[66:67] op_sel_hi:[1,0,1]
	v_pk_fma_f32 v[40:41], v[40:41], v[68:69], v[64:65] op_sel_hi:[1,0,1]
	v_pk_fma_f32 v[38:39], v[38:39], v[68:69], v[42:43] op_sel:[0,1,0]
	v_pk_fma_f32 v[36:37], v[36:37], v[68:69], v[40:41] op_sel:[0,1,0]
	v_pk_fma_f32 v[38:39], v[50:51], v[70:71], v[38:39] op_sel_hi:[1,0,1]
	v_pk_fma_f32 v[36:37], v[48:49], v[70:71], v[36:37] op_sel_hi:[1,0,1]
	v_mov_b32_e32 v40, v71
	v_pk_fma_f32 v[38:39], v[46:47], v[40:41], v[38:39] op_sel_hi:[1,0,1]
	v_pk_fma_f32 v[36:37], v[44:45], v[40:41], v[36:37] op_sel_hi:[1,0,1]
	s_waitcnt lgkmcnt(0)
	v_pk_fma_f32 v[38:39], v[58:59], v[84:85], v[38:39] op_sel_hi:[1,0,1]
	v_pk_fma_f32 v[36:37], v[56:57], v[84:85], v[36:37] op_sel_hi:[1,0,1]
	v_pk_fma_f32 v[38:39], v[54:55], v[84:85], v[38:39] op_sel:[0,1,0]
	v_pk_fma_f32 v[36:37], v[52:53], v[84:85], v[36:37] op_sel:[0,1,0]
	v_pk_fma_f32 v[40:41], v[62:63], v[86:87], v[38:39] op_sel_hi:[1,0,1]
	v_pk_fma_f32 v[42:43], v[60:61], v[86:87], v[36:37] op_sel_hi:[1,0,1]
	ds_read_b128 v[36:39], v136 offset:3168
	v_mov_b32_e32 v44, v87
	v_pk_fma_f32 v[40:41], v[34:35], v[44:45], v[40:41] op_sel_hi:[1,0,1]
	v_pk_fma_f32 v[42:43], v[32:33], v[44:45], v[42:43] op_sel_hi:[1,0,1]
	ds_read_b128 v[32:35], v136 offset:3184
	s_waitcnt lgkmcnt(1)
	v_pk_fma_f32 v[12:13], v[12:13], v[36:37], v[42:43] op_sel_hi:[1,0,1]
	v_pk_fma_f32 v[14:15], v[14:15], v[36:37], v[40:41] op_sel_hi:[1,0,1]
	v_pk_fma_f32 v[4:5], v[4:5], v[36:37], v[12:13] op_sel:[0,1,0]
	v_mov_b32_e32 v12, v39
	v_pk_fma_f32 v[4:5], v[20:21], v[38:39], v[4:5] op_sel_hi:[1,0,1]
	v_pk_fma_f32 v[6:7], v[6:7], v[36:37], v[14:15] op_sel:[0,1,0]
	v_pk_fma_f32 v[4:5], v[8:9], v[12:13], v[4:5] op_sel_hi:[1,0,1]
	v_pk_fma_f32 v[6:7], v[22:23], v[38:39], v[6:7] op_sel_hi:[1,0,1]
	s_waitcnt lgkmcnt(0)
	v_pk_fma_f32 v[4:5], v[24:25], v[32:33], v[4:5] op_sel_hi:[1,0,1]
	v_pk_fma_f32 v[6:7], v[10:11], v[12:13], v[6:7] op_sel_hi:[1,0,1]
	v_pk_fma_f32 v[4:5], v[16:17], v[32:33], v[4:5] op_sel:[0,1,0]
	v_pk_fma_f32 v[6:7], v[26:27], v[32:33], v[6:7] op_sel_hi:[1,0,1]
	v_pk_fma_f32 v[4:5], v[28:29], v[34:35], v[4:5] op_sel_hi:[1,0,1]
	v_mov_b32_e32 v8, v35
	v_pk_fma_f32 v[6:7], v[18:19], v[32:33], v[6:7] op_sel:[0,1,0]
	v_pk_fma_f32 v[0:1], v[0:1], v[8:9], v[4:5] op_sel_hi:[1,0,1]
	v_lshlrev_b32_e32 v4, 12, v210
	v_pk_fma_f32 v[6:7], v[30:31], v[34:35], v[6:7] op_sel_hi:[1,0,1]
	v_add3_u32 v4, 16, v4, v144
	v_pk_fma_f32 v[2:3], v[2:3], v[8:9], v[6:7] op_sel_hi:[1,0,1]
	ds_write_b128 v4, v[72:75] offset:4096
	ds_write_b128 v4, v[76:79] offset:5120
	ds_write_b128 v4, v[80:83] offset:6144
	ds_write_b128 v4, v[0:3] offset:7168
	v_lshlrev_b32_e32 v0, 1, v222
	v_ashrrev_i32_e32 v16, 7, v222
	v_and_b32_e32 v17, 0xfe, v0
	v_lshlrev_b32_e32 v0, 10, v16
	v_lshlrev_b32_e32 v1, 2, v17
	s_waitcnt lgkmcnt(0)
	s_barrier
	v_add3_u32 v12, 16, v0, v1
	ds_read2st64_b64 v[0:3], v12 offset0:8 offset1:16
	ds_read2st64_b64 v[4:7], v12 offset0:24 offset1:32
	ds_read2st64_b64 v[8:11], v12 offset0:40 offset1:48
	ds_read2st64_b64 v[12:15], v12 offset0:56 offset1:64
	v_lshlrev_b32_e32 v144, 1, v17
	s_waitcnt lgkmcnt(3)
	v_pk_add_f32 v[0:1], v[0:1], 0 op_sel_hi:[1,0]
	s_cmpk_lt_i32 s40, 0x200
	v_pk_add_f32 v[0:1], v[0:1], v[2:3]
	s_waitcnt lgkmcnt(2)
	v_pk_add_f32 v[0:1], v[0:1], v[4:5]
	s_nop 0
	v_pk_add_f32 v[0:1], v[0:1], v[6:7]
	s_waitcnt lgkmcnt(1)
	v_pk_add_f32 v[0:1], v[0:1], v[8:9]
	s_nop 0
	v_pk_add_f32 v[0:1], v[0:1], v[10:11]
	s_waitcnt lgkmcnt(0)
	v_pk_add_f32 v[0:1], v[0:1], v[12:13]
	s_nop 0
	v_pk_add_f32 v[0:1], v[0:1], v[14:15]
	s_nop 0
	v_cvt_pk_bf16_f32 v2, v0, v1
	v_add_u32_e32 v0, s4, v16
	v_ashrrev_i32_e32 v1, 31, v0
	v_lshlrev_b64 v[0:1], 11, v[0:1]
	v_lshl_add_u64 v[0:1], s[22:23], 0, v[0:1]
	v_lshl_add_u64 v[0:1], v[0:1], 0, s[26:27]
	v_lshl_add_u64 v[0:1], v[0:1], 0, v[144:145]
	global_store_dword v[0:1], v2, off
	s_waitcnt lgkmcnt(0)
	s_barrier
	s_cbranch_scc0 .LBB0_1670
.LBB0_1604:
	s_ashr_i32 s4, s40, 2
	s_ashr_i32 s5, s4, 31
	s_lshl_b64 s[4:5], s[4:5], 18
	s_and_b32 s26, s0, 0x300
	v_mov_b32_e32 v222, v212
	s_or_b32 s4, s4, s26
	s_and_b32 s28, s40, -4
	s_lshl_b32 s6, s26, 2
	s_add_u32 s6, s36, s6
	v_and_b32_e32 v223, 63, v222
	s_addc_u32 s7, s37, 0
	v_lshlrev_b32_e32 v144, 4, v223
	s_ashr_i32 s29, s28, 31
	v_lshl_add_u64 v[48:49], s[6:7], 0, v[144:145]
	s_lshl_b64 s[6:7], s[28:29], 12
	v_lshl_add_u64 v[8:9], v[48:49], 0, s[6:7]
	v_add_co_u32_e32 v4, vcc, s3, v8
	s_or_b32 s6, s28, 1
	s_nop 0
	v_addc_co_u32_e32 v5, vcc, 0, v9, vcc
	v_add_co_u32_e32 v10, vcc, s33, v8
	s_ashr_i32 s7, s6, 31
	s_nop 0
	v_addc_co_u32_e32 v11, vcc, 0, v9, vcc
	v_add_co_u32_e32 v12, vcc, s38, v8
	s_lshl_b64 s[6:7], s[6:7], 12
	s_nop 0
	v_addc_co_u32_e32 v13, vcc, 0, v9, vcc
	v_lshl_add_u64 v[24:25], v[48:49], 0, s[6:7]
	v_add_co_u32_e32 v20, vcc, s3, v24
	s_or_b32 s6, s28, 2
	s_nop 0
	v_addc_co_u32_e32 v21, vcc, 0, v25, vcc
	v_add_co_u32_e32 v26, vcc, s33, v24
	s_ashr_i32 s7, s6, 31
	s_nop 0
	v_addc_co_u32_e32 v27, vcc, 0, v25, vcc
	v_add_co_u32_e32 v28, vcc, s38, v24
	s_lshl_b64 s[6:7], s[6:7], 12
	global_load_dwordx4 v[0:3], v[8:9], off
	s_nop 0
	global_load_dwordx4 v[4:7], v[4:5], off
	v_addc_co_u32_e32 v29, vcc, 0, v25, vcc
	v_lshl_add_u64 v[44:45], v[48:49], 0, s[6:7]
	global_load_dwordx4 v[8:11], v[10:11], off
	s_nop 0
	global_load_dwordx4 v[12:15], v[12:13], off
	s_nop 0
	global_load_dwordx4 v[16:19], v[24:25], off
	s_nop 0
	global_load_dwordx4 v[20:23], v[20:21], off
	v_add_co_u32_e32 v36, vcc, s3, v44
	global_load_dwordx4 v[24:27], v[26:27], off
	s_nop 0
	global_load_dwordx4 v[28:31], v[28:29], off
	v_addc_co_u32_e32 v37, vcc, 0, v45, vcc
	v_add_co_u32_e32 v40, vcc, s33, v44
	global_load_dwordx4 v[32:35], v[44:45], off
	s_nop 0
	global_load_dwordx4 v[36:39], v[36:37], off
	v_addc_co_u32_e32 v41, vcc, 0, v45, vcc
	v_add_co_u32_e32 v44, vcc, s38, v44
	global_load_dwordx4 v[40:43], v[40:41], off
	s_nop 0
	v_addc_co_u32_e32 v45, vcc, 0, v45, vcc
	global_load_dwordx4 v[44:47], v[44:45], off
	s_or_b32 s6, s40, 3
	s_ashr_i32 s7, s6, 31
	s_lshl_b64 s[6:7], s[6:7], 12
	s_lshl_b64 s[30:31], s[4:5], 2
	s_add_u32 s4, s12, s30
	s_addc_u32 s5, s13, s31
	s_waitcnt vmcnt(11)
; DI void attn_sample_item(const Params& p, int item, ldsp lds, int tid_) {
;     ...
;   for (int t = 0; t < 4; ++t) { f32x4 a = {0.f, 0.f, 0.f, 0.f}; const float* pp = (const float*)(p.ws + B_PART) + (size_t)(b * 4 + t) * 1024 + h * 256 + lane * 4;
; #pragma unroll
;     for (int kp = 0; kp < 4; ++kp) a += *(const f32x4*)(pp + (size_t)kp * 512 * 1024);
;     q[t][0] = a[0] * 0.0625f; q[t][1] = a[1] * 0.0625f; q[t][2] = a[2] * 0.0625f; q[t][3] = a[3] * 0.0625f; }
;   const bool b0 = lane & 1, b1 = lane & 2;
;   f32x4 kvA[16], kvB[16];
; #pragma unroll
;   for (int j = 0; j < 16; ++j) kvA[j] = __builtin_nontemporal_load((const f32x4*)(ck + (size_t)(wid * 32 + j) * 1024 + lane * 4));
; #pragma unroll
;   for (int j = 0; j < 16; ++j) kvB[j] = __builtin_nontemporal_load((const f32x4*)(ck + (size_t)(wid * 32 + 16 + j) * 1024 + lane * 4));
	v_pk_add_f32 v[2:3], v[2:3], 0 op_sel_hi:[1,0]
	v_pk_add_f32 v[0:1], v[0:1], 0 op_sel_hi:[1,0]
	s_waitcnt vmcnt(10)
	v_pk_add_f32 v[2:3], v[2:3], v[6:7]
	v_pk_add_f32 v[0:1], v[0:1], v[4:5]
	s_waitcnt vmcnt(9)
	v_pk_add_f32 v[2:3], v[2:3], v[10:11]
	s_waitcnt vmcnt(7)
	v_pk_add_f32 v[4:5], v[18:19], 0 op_sel_hi:[1,0]
	v_pk_add_f32 v[6:7], v[16:17], 0 op_sel_hi:[1,0]
	v_pk_add_f32 v[0:1], v[0:1], v[8:9]
	s_waitcnt vmcnt(6)
	v_pk_add_f32 v[4:5], v[4:5], v[22:23]
	v_pk_add_f32 v[6:7], v[6:7], v[20:21]
	v_pk_add_f32 v[2:3], v[2:3], v[14:15]
	v_pk_add_f32 v[0:1], v[0:1], v[12:13]
	s_waitcnt vmcnt(5)
	v_pk_add_f32 v[4:5], v[4:5], v[26:27]
	v_pk_add_f32 v[6:7], v[6:7], v[24:25]
	v_mul_f32_e32 v228, 0x3d800000, v0
	v_mul_f32_e32 v231, 0x3d800000, v1
	v_mul_f32_e32 v229, 0x3d800000, v2
	v_mul_f32_e32 v225, 0x3d800000, v3
	s_waitcnt vmcnt(4)
	v_pk_add_f32 v[0:1], v[4:5], v[30:31]
	v_pk_add_f32 v[2:3], v[6:7], v[28:29]
	v_mul_f32_e32 v227, 0x3d800000, v0
	v_mul_f32_e32 v226, 0x3d800000, v2
	v_mul_f32_e32 v230, 0x3d800000, v3
	v_mul_f32_e32 v224, 0x3d800000, v1
	s_waitcnt vmcnt(3)
	v_pk_add_f32 v[0:1], v[34:35], 0 op_sel_hi:[1,0]
	v_pk_add_f32 v[2:3], v[32:33], 0 op_sel_hi:[1,0]
	s_waitcnt vmcnt(2)
	v_pk_add_f32 v[0:1], v[0:1], v[38:39]
	v_pk_add_f32 v[2:3], v[2:3], v[36:37]
	s_waitcnt vmcnt(1)
	v_pk_add_f32 v[0:1], v[0:1], v[42:43]
	v_pk_add_f32 v[2:3], v[2:3], v[40:41]
	s_waitcnt vmcnt(0)
	v_pk_add_f32 v[210:211], v[0:1], v[46:47]
	v_pk_add_f32 v[0:1], v[2:3], v[44:45]
	v_mul_f32_e32 v233, 0x3d800000, v210
	v_mul_f32_e32 v232, 0x3d800000, v0
	v_mul_f32_e32 v234, 0x3d800000, v1
	v_lshl_add_u64 v[0:1], v[48:49], 0, s[6:7]
	v_add_co_u32_e32 v2, vcc, s3, v0
	v_ashrrev_i32_e32 v210, 6, v222
	s_nop 0
	v_addc_co_u32_e32 v3, vcc, 0, v1, vcc
	global_load_dwordx4 v[128:131], v[0:1], off
	global_load_dwordx4 v[132:135], v[2:3], off
	v_add_co_u32_e32 v2, vcc, s33, v0
	v_mul_f32_e32 v211, 0x3d800000, v211
	s_nop 0
	v_addc_co_u32_e32 v3, vcc, 0, v1, vcc
	v_add_co_u32_e32 v0, vcc, s38, v0
	v_cmp_lt_i32_e64 s[6:7], v218, v216
	s_nop 0
	v_addc_co_u32_e32 v1, vcc, 0, v1, vcc
	global_load_dwordx4 v[136:139], v[2:3], off
	global_load_dwordx4 v[140:143], v[0:1], off
	v_lshlrev_b32_e32 v0, 5, v210
	v_ashrrev_i32_e32 v1, 31, v0
	v_or_b32_e32 v6, 1, v0
	v_lshl_add_u64 v[2:3], s[4:5], 0, v[144:145]
	v_lshlrev_b64 v[162:163], 12, v[0:1]
	v_ashrrev_i32_e32 v7, 31, v6
	v_lshl_add_u64 v[4:5], v[2:3], 0, v[162:163]
	v_lshlrev_b64 v[166:167], 12, v[6:7]
	v_lshl_add_u64 v[6:7], v[2:3], 0, v[166:167]
	global_load_dwordx4 v[124:127], v[4:5], off nt
	global_load_dwordx4 v[120:123], v[6:7], off nt
	v_or_b32_e32 v4, 2, v0
	v_ashrrev_i32_e32 v5, 31, v4
	v_or_b32_e32 v6, 3, v0
	v_lshlrev_b64 v[168:169], 12, v[4:5]
	v_ashrrev_i32_e32 v7, 31, v6
	v_lshl_add_u64 v[4:5], v[2:3], 0, v[168:169]
	v_lshlrev_b64 v[172:173], 12, v[6:7]
	v_lshl_add_u64 v[6:7], v[2:3], 0, v[172:173]
	global_load_dwordx4 v[116:119], v[4:5], off nt
	global_load_dwordx4 v[112:115], v[6:7], off nt
	v_or_b32_e32 v4, 4, v0
	v_ashrrev_i32_e32 v5, 31, v4
	v_or_b32_e32 v6, 5, v0
	v_lshlrev_b64 v[176:177], 12, v[4:5]
	v_ashrrev_i32_e32 v7, 31, v6
	v_lshl_add_u64 v[4:5], v[2:3], 0, v[176:177]
	v_lshlrev_b64 v[180:181], 12, v[6:7]
	v_lshl_add_u64 v[6:7], v[2:3], 0, v[180:181]
	global_load_dwordx4 v[108:111], v[4:5], off nt
	global_load_dwordx4 v[104:107], v[6:7], off nt
	v_or_b32_e32 v4, 6, v0
	v_ashrrev_i32_e32 v5, 31, v4
	v_or_b32_e32 v6, 7, v0
	v_lshlrev_b64 v[182:183], 12, v[4:5]
	v_ashrrev_i32_e32 v7, 31, v6
	v_lshl_add_u64 v[4:5], v[2:3], 0, v[182:183]
	v_lshlrev_b64 v[186:187], 12, v[6:7]
	v_lshl_add_u64 v[6:7], v[2:3], 0, v[186:187]
	global_load_dwordx4 v[100:103], v[4:5], off nt
	global_load_dwordx4 v[96:99], v[6:7], off nt
	v_or_b32_e32 v4, 8, v0
	v_ashrrev_i32_e32 v5, 31, v4
	v_or_b32_e32 v6, 9, v0
	v_lshlrev_b64 v[190:191], 12, v[4:5]
	v_ashrrev_i32_e32 v7, 31, v6
	v_lshl_add_u64 v[4:5], v[2:3], 0, v[190:191]
	v_lshlrev_b64 v[194:195], 12, v[6:7]
	v_lshl_add_u64 v[6:7], v[2:3], 0, v[194:195]
	global_load_dwordx4 v[92:95], v[4:5], off nt
	global_load_dwordx4 v[88:91], v[6:7], off nt
	v_or_b32_e32 v4, 10, v0
	v_ashrrev_i32_e32 v5, 31, v4
	v_or_b32_e32 v6, 11, v0
	v_lshlrev_b64 v[198:199], 12, v[4:5]
	v_ashrrev_i32_e32 v7, 31, v6
	v_lshl_add_u64 v[4:5], v[2:3], 0, v[198:199]
	v_lshlrev_b64 v[200:201], 12, v[6:7]
	v_lshl_add_u64 v[6:7], v[2:3], 0, v[200:201]
	global_load_dwordx4 v[84:87], v[4:5], off nt
	global_load_dwordx4 v[80:83], v[6:7], off nt
	v_or_b32_e32 v4, 12, v0
	v_ashrrev_i32_e32 v5, 31, v4
	v_or_b32_e32 v6, 13, v0
	v_lshlrev_b64 v[202:203], 12, v[4:5]
	v_ashrrev_i32_e32 v7, 31, v6
	v_lshl_add_u64 v[4:5], v[2:3], 0, v[202:203]
	v_lshlrev_b64 v[204:205], 12, v[6:7]
	v_lshl_add_u64 v[6:7], v[2:3], 0, v[204:205]
	global_load_dwordx4 v[76:79], v[4:5], off nt
	global_load_dwordx4 v[72:75], v[6:7], off nt
	v_or_b32_e32 v4, 14, v0
	v_ashrrev_i32_e32 v5, 31, v4
	v_or_b32_e32 v6, 15, v0
	v_lshlrev_b64 v[206:207], 12, v[4:5]
	v_ashrrev_i32_e32 v7, 31, v6
	v_lshl_add_u64 v[4:5], v[2:3], 0, v[206:207]
	v_lshlrev_b64 v[208:209], 12, v[6:7]
	v_lshl_add_u64 v[6:7], v[2:3], 0, v[208:209]
	global_load_dwordx4 v[68:71], v[4:5], off nt
	global_load_dwordx4 v[64:67], v[6:7], off nt
	v_or_b32_e32 v4, 16, v0
	v_ashrrev_i32_e32 v5, 31, v4
	v_or_b32_e32 v6, 17, v0
	v_lshlrev_b64 v[146:147], 12, v[4:5]
	v_ashrrev_i32_e32 v7, 31, v6
	v_lshl_add_u64 v[4:5], v[2:3], 0, v[146:147]
	v_lshlrev_b64 v[148:149], 12, v[6:7]
	v_lshl_add_u64 v[6:7], v[2:3], 0, v[148:149]
	global_load_dwordx4 v[60:63], v[4:5], off nt
	global_load_dwordx4 v[56:59], v[6:7], off nt
	v_or_b32_e32 v4, 18, v0
	v_ashrrev_i32_e32 v5, 31, v4
	v_or_b32_e32 v6, 19, v0
; DI void attn_sample_item(const Params& p, int item, ldsp lds, int tid_) {
;     ...
;   for (int j = 0; j < 16; ++j) kvA[j] = __builtin_nontemporal_load((const f32x4*)(ck + (size_t)(wid * 32 + j) * 1024 + lane * 4));
; #pragma unroll
;   for (int j = 0; j < 16; ++j) kvB[j] = __builtin_nontemporal_load((const f32x4*)(ck + (size_t)(wid * 32 + 16 + j) * 1024 + lane * 4));
;     ...
;   SC_SCORE(kvA, 0)
;   SC_SCORE(kvB, 1)
	v_lshlrev_b64 v[150:151], 12, v[4:5]
	v_ashrrev_i32_e32 v7, 31, v6
	v_lshl_add_u64 v[4:5], v[2:3], 0, v[150:151]
	v_lshlrev_b64 v[152:153], 12, v[6:7]
	v_lshl_add_u64 v[6:7], v[2:3], 0, v[152:153]
	global_load_dwordx4 v[52:55], v[4:5], off nt
	global_load_dwordx4 v[48:51], v[6:7], off nt
	v_or_b32_e32 v4, 20, v0
	v_ashrrev_i32_e32 v5, 31, v4
	v_or_b32_e32 v6, 21, v0
	v_lshlrev_b64 v[154:155], 12, v[4:5]
	v_ashrrev_i32_e32 v7, 31, v6
	v_lshl_add_u64 v[4:5], v[2:3], 0, v[154:155]
	v_lshlrev_b64 v[156:157], 12, v[6:7]
	v_lshl_add_u64 v[6:7], v[2:3], 0, v[156:157]
	global_load_dwordx4 v[44:47], v[4:5], off nt
	global_load_dwordx4 v[40:43], v[6:7], off nt
	v_or_b32_e32 v4, 22, v0
	v_ashrrev_i32_e32 v5, 31, v4
	v_or_b32_e32 v6, 23, v0
	v_lshlrev_b64 v[158:159], 12, v[4:5]
	v_ashrrev_i32_e32 v7, 31, v6
	v_lshl_add_u64 v[4:5], v[2:3], 0, v[158:159]
	v_lshlrev_b64 v[160:161], 12, v[6:7]
	v_lshl_add_u64 v[6:7], v[2:3], 0, v[160:161]
	global_load_dwordx4 v[36:39], v[4:5], off nt
	global_load_dwordx4 v[32:35], v[6:7], off nt
	v_or_b32_e32 v4, 24, v0
	v_ashrrev_i32_e32 v5, 31, v4
	v_or_b32_e32 v6, 25, v0
	v_lshlrev_b64 v[164:165], 12, v[4:5]
	v_ashrrev_i32_e32 v7, 31, v6
	v_lshl_add_u64 v[4:5], v[2:3], 0, v[164:165]
	v_lshlrev_b64 v[170:171], 12, v[6:7]
	v_lshl_add_u64 v[6:7], v[2:3], 0, v[170:171]
	global_load_dwordx4 v[28:31], v[4:5], off nt
	global_load_dwordx4 v[24:27], v[6:7], off nt
	v_or_b32_e32 v4, 26, v0
	v_ashrrev_i32_e32 v5, 31, v4
	v_or_b32_e32 v6, 27, v0
	v_lshlrev_b64 v[174:175], 12, v[4:5]
	v_ashrrev_i32_e32 v7, 31, v6
	v_lshl_add_u64 v[4:5], v[2:3], 0, v[174:175]
	v_lshlrev_b64 v[178:179], 12, v[6:7]
	v_lshl_add_u64 v[6:7], v[2:3], 0, v[178:179]
	global_load_dwordx4 v[20:23], v[4:5], off nt
	global_load_dwordx4 v[16:19], v[6:7], off nt
	v_or_b32_e32 v4, 28, v0
	v_ashrrev_i32_e32 v5, 31, v4
	v_or_b32_e32 v6, 29, v0
	v_lshlrev_b64 v[184:185], 12, v[4:5]
	v_ashrrev_i32_e32 v7, 31, v6
	v_lshl_add_u64 v[4:5], v[2:3], 0, v[184:185]
	v_lshlrev_b64 v[188:189], 12, v[6:7]
	v_lshl_add_u64 v[6:7], v[2:3], 0, v[188:189]
	global_load_dwordx4 v[12:15], v[4:5], off nt
	global_load_dwordx4 v[8:11], v[6:7], off nt
	v_or_b32_e32 v4, 30, v0
	v_or_b32_e32 v0, 31, v0
	v_ashrrev_i32_e32 v5, 31, v4
	v_ashrrev_i32_e32 v1, 31, v0
	v_lshlrev_b64 v[192:193], 12, v[4:5]
	v_lshlrev_b64 v[196:197], 12, v[0:1]
	v_lshl_add_u64 v[4:5], v[2:3], 0, v[192:193]
	v_lshl_add_u64 v[0:1], v[2:3], 0, v[196:197]
	global_load_dwordx4 v[4:7], v[4:5], off nt
	s_nop 0
	global_load_dwordx4 v[0:3], v[0:1], off nt
	s_waitcnt vmcnt(35)
	v_pk_add_f32 v[128:129], v[128:129], 0 op_sel_hi:[1,0]
	v_pk_add_f32 v[130:131], v[130:131], 0 op_sel_hi:[1,0]
	s_waitcnt vmcnt(34)
	v_pk_add_f32 v[128:129], v[128:129], v[132:133]
	v_pk_add_f32 v[130:131], v[130:131], v[134:135]
	s_waitcnt vmcnt(33)
	v_pk_add_f32 v[128:129], v[128:129], v[136:137]
	v_pk_add_f32 v[130:131], v[130:131], v[138:139]
	s_waitcnt vmcnt(32)
	v_pk_add_f32 v[128:129], v[128:129], v[140:141]
	v_pk_add_f32 v[130:131], v[130:131], v[142:143]
	v_mul_f32_e32 v138, 0x3d800000, v129
	v_mul_f32_e32 v135, 0x3d800000, v128
	v_mul_f32_e32 v134, 0x3d800000, v131
	v_mul_f32_e32 v137, 0x3d800000, v130
	v_lshlrev_b32_e32 v128, 2, v215
	v_lshlrev_b32_e32 v129, 2, v217
	v_lshlrev_b32_e32 v130, 2, v218
	v_lshlrev_b32_e32 v131, 2, v219
	v_lshlrev_b32_e32 v132, 2, v220
	v_lshlrev_b32_e32 v133, 2, v221
	v_lshl_add_u32 v136, v210, 7, 16
	v_and_b32_e32 v139, 3, v223
	v_bfrev_b32_e32 v139, v139
	v_lshrrev_b32_e32 v139, 20, v139
	v_and_b32_e32 v235, -4, v223
	v_add3_u32 v235, v136, v139, v235
	v_mov_b32_e32 v236, v228
	v_mov_b32_e32 v237, v226
	v_mov_b32_e32 v238, v231
	v_mov_b32_e32 v239, v230
	v_mov_b32_e32 v240, v229
	v_mov_b32_e32 v241, v227
	v_mov_b32_e32 v242, v225
	v_mov_b32_e32 v243, v224
	v_mov_b32_e32 v244, v232
	v_mov_b32_e32 v245, v135
	v_mov_b32_e32 v246, v234
	v_mov_b32_e32 v247, v138
	v_mov_b32_e32 v248, v233
	v_mov_b32_e32 v249, v137
	v_mov_b32_e32 v250, v211
	v_mov_b32_e32 v251, v134
	s_mov_b32 vcc_lo, 0x55555555
	s_mov_b32 vcc_hi, 0x55555555
	s_mov_b32 s4, 0x33333333
	s_mov_b32 s5, 0x33333333
	s_mov_b32 s6, 0x0f0f0f0f
	s_mov_b32 s7, 0x0f0f0f0f
	s_mov_b32 s64, 0x00ff00ff
	s_mov_b32 s65, 0x00ff00ff
	s_waitcnt vmcnt(31)
	v_pk_mul_f32 v[252:253], v[236:237], v[124:125] op_sel_hi:[1,0]
	v_pk_mul_f32 v[254:255], v[244:245], v[124:125] op_sel_hi:[1,0]
	v_pk_fma_f32 v[252:253], v[238:239], v[124:125], v[252:253] op_sel:[0,1,0]
	v_pk_fma_f32 v[254:255], v[246:247], v[124:125], v[254:255] op_sel:[0,1,0]
	v_pk_fma_f32 v[252:253], v[240:241], v[126:127], v[252:253] op_sel_hi:[1,0,1]
	v_pk_fma_f32 v[254:255], v[248:249], v[126:127], v[254:255] op_sel_hi:[1,0,1]
	v_pk_fma_f32 v[252:253], v[242:243], v[126:127], v[252:253] op_sel:[0,1,0]
	v_pk_fma_f32 v[254:255], v[250:251], v[126:127], v[254:255] op_sel:[0,1,0]
	s_waitcnt vmcnt(30)
	v_pk_mul_f32 v[140:141], v[236:237], v[120:121] op_sel_hi:[1,0]
	v_pk_mul_f32 v[142:143], v[244:245], v[120:121] op_sel_hi:[1,0]
	v_pk_fma_f32 v[140:141], v[238:239], v[120:121], v[140:141] op_sel:[0,1,0]
	v_pk_fma_f32 v[142:143], v[246:247], v[120:121], v[142:143] op_sel:[0,1,0]
	v_pk_fma_f32 v[140:141], v[240:241], v[122:123], v[140:141] op_sel_hi:[1,0,1]
	v_pk_fma_f32 v[142:143], v[248:249], v[122:123], v[142:143] op_sel_hi:[1,0,1]
	v_pk_fma_f32 v[140:141], v[242:243], v[122:123], v[140:141] op_sel:[0,1,0]
	v_pk_fma_f32 v[142:143], v[250:251], v[122:123], v[142:143] op_sel:[0,1,0]
	v_add_f32_dpp v124, v252, v252 quad_perm:[1,0,3,2] row_mask:0xf bank_mask:0xf
	v_add_f32_dpp v125, v253, v253 quad_perm:[1,0,3,2] row_mask:0xf bank_mask:0xf
	v_add_f32_dpp v126, v254, v254 quad_perm:[1,0,3,2] row_mask:0xf bank_mask:0xf
	v_add_f32_dpp v127, v255, v255 quad_perm:[1,0,3,2] row_mask:0xf bank_mask:0xf
	v_cndmask_b32_e32 v124, v126, v124, vcc
	v_cndmask_b32_e32 v125, v127, v125, vcc
	s_waitcnt vmcnt(29)
; DI void attn_sample_item(const Params& p, int item, ldsp lds, int tid_) {
;     ...
;   SC_SCORE(kvA, 0)
;   SC_SCORE(kvB, 1)
	v_pk_mul_f32 v[252:253], v[236:237], v[116:117] op_sel_hi:[1,0]
	v_pk_mul_f32 v[254:255], v[244:245], v[116:117] op_sel_hi:[1,0]
	v_pk_fma_f32 v[252:253], v[238:239], v[116:117], v[252:253] op_sel:[0,1,0]
	v_pk_fma_f32 v[254:255], v[246:247], v[116:117], v[254:255] op_sel:[0,1,0]
	v_pk_fma_f32 v[252:253], v[240:241], v[118:119], v[252:253] op_sel_hi:[1,0,1]
	v_pk_fma_f32 v[254:255], v[248:249], v[118:119], v[254:255] op_sel_hi:[1,0,1]
	v_pk_fma_f32 v[252:253], v[242:243], v[118:119], v[252:253] op_sel:[0,1,0]
	v_pk_fma_f32 v[254:255], v[250:251], v[118:119], v[254:255] op_sel:[0,1,0]
	v_add_f32_dpp v120, v140, v140 quad_perm:[1,0,3,2] row_mask:0xf bank_mask:0xf
	v_add_f32_dpp v121, v141, v141 quad_perm:[1,0,3,2] row_mask:0xf bank_mask:0xf
	v_add_f32_dpp v122, v142, v142 quad_perm:[1,0,3,2] row_mask:0xf bank_mask:0xf
	v_add_f32_dpp v123, v143, v143 quad_perm:[1,0,3,2] row_mask:0xf bank_mask:0xf
	v_cndmask_b32_e32 v120, v122, v120, vcc
	v_cndmask_b32_e32 v121, v123, v121, vcc
	v_add_f32_dpp v126, v124, v124 quad_perm:[2,3,0,1] row_mask:0xf bank_mask:0xf
	v_add_f32_dpp v127, v125, v125 quad_perm:[2,3,0,1] row_mask:0xf bank_mask:0xf
	v_cndmask_b32_e64 v124, v127, v126, s[4:5]
	s_waitcnt vmcnt(28)
	v_pk_mul_f32 v[140:141], v[236:237], v[112:113] op_sel_hi:[1,0]
	v_pk_mul_f32 v[142:143], v[244:245], v[112:113] op_sel_hi:[1,0]
	v_pk_fma_f32 v[140:141], v[238:239], v[112:113], v[140:141] op_sel:[0,1,0]
	v_pk_fma_f32 v[142:143], v[246:247], v[112:113], v[142:143] op_sel:[0,1,0]
	v_pk_fma_f32 v[140:141], v[240:241], v[114:115], v[140:141] op_sel_hi:[1,0,1]
	v_pk_fma_f32 v[142:143], v[248:249], v[114:115], v[142:143] op_sel_hi:[1,0,1]
	v_pk_fma_f32 v[140:141], v[242:243], v[114:115], v[140:141] op_sel:[0,1,0]
	v_pk_fma_f32 v[142:143], v[250:251], v[114:115], v[142:143] op_sel:[0,1,0]
	v_add_f32_dpp v116, v252, v252 quad_perm:[1,0,3,2] row_mask:0xf bank_mask:0xf
	v_add_f32_dpp v117, v253, v253 quad_perm:[1,0,3,2] row_mask:0xf bank_mask:0xf
	v_add_f32_dpp v118, v254, v254 quad_perm:[1,0,3,2] row_mask:0xf bank_mask:0xf
	v_add_f32_dpp v119, v255, v255 quad_perm:[1,0,3,2] row_mask:0xf bank_mask:0xf
	v_cndmask_b32_e32 v116, v118, v116, vcc
	v_cndmask_b32_e32 v117, v119, v117, vcc
	v_add_f32_dpp v122, v120, v120 quad_perm:[2,3,0,1] row_mask:0xf bank_mask:0xf
	v_add_f32_dpp v123, v121, v121 quad_perm:[2,3,0,1] row_mask:0xf bank_mask:0xf
	v_cndmask_b32_e64 v120, v123, v122, s[4:5]
	v_cndmask_b32_e64 v125, v120, v124, s[6:7]
	v_cndmask_b32_e64 v126, v124, v120, s[6:7]
	s_waitcnt vmcnt(27)
	v_pk_mul_f32 v[252:253], v[236:237], v[108:109] op_sel_hi:[1,0]
	v_pk_mul_f32 v[254:255], v[244:245], v[108:109] op_sel_hi:[1,0]
	v_pk_fma_f32 v[252:253], v[238:239], v[108:109], v[252:253] op_sel:[0,1,0]
	v_pk_fma_f32 v[254:255], v[246:247], v[108:109], v[254:255] op_sel:[0,1,0]
	v_pk_fma_f32 v[252:253], v[240:241], v[110:111], v[252:253] op_sel_hi:[1,0,1]
	v_pk_fma_f32 v[254:255], v[248:249], v[110:111], v[254:255] op_sel_hi:[1,0,1]
	v_pk_fma_f32 v[252:253], v[242:243], v[110:111], v[252:253] op_sel:[0,1,0]
	v_pk_fma_f32 v[254:255], v[250:251], v[110:111], v[254:255] op_sel:[0,1,0]
	v_add_f32_dpp v124, v126, v125 row_ror:4 row_mask:0xf bank_mask:0xf
	v_add_f32_dpp v112, v140, v140 quad_perm:[1,0,3,2] row_mask:0xf bank_mask:0xf
	v_add_f32_dpp v113, v141, v141 quad_perm:[1,0,3,2] row_mask:0xf bank_mask:0xf
	v_add_f32_dpp v114, v142, v142 quad_perm:[1,0,3,2] row_mask:0xf bank_mask:0xf
	v_add_f32_dpp v115, v143, v143 quad_perm:[1,0,3,2] row_mask:0xf bank_mask:0xf
	v_cndmask_b32_e32 v112, v114, v112, vcc
	v_cndmask_b32_e32 v113, v115, v113, vcc
	v_add_f32_dpp v118, v116, v116 quad_perm:[2,3,0,1] row_mask:0xf bank_mask:0xf
	v_add_f32_dpp v119, v117, v117 quad_perm:[2,3,0,1] row_mask:0xf bank_mask:0xf
	v_cndmask_b32_e64 v116, v119, v118, s[4:5]
	s_waitcnt vmcnt(26)
	v_pk_mul_f32 v[140:141], v[236:237], v[104:105] op_sel_hi:[1,0]
	v_pk_mul_f32 v[142:143], v[244:245], v[104:105] op_sel_hi:[1,0]
	v_pk_fma_f32 v[140:141], v[238:239], v[104:105], v[140:141] op_sel:[0,1,0]
	v_pk_fma_f32 v[142:143], v[246:247], v[104:105], v[142:143] op_sel:[0,1,0]
	v_pk_fma_f32 v[140:141], v[240:241], v[106:107], v[140:141] op_sel_hi:[1,0,1]
	v_pk_fma_f32 v[142:143], v[248:249], v[106:107], v[142:143] op_sel_hi:[1,0,1]
	v_pk_fma_f32 v[140:141], v[242:243], v[106:107], v[140:141] op_sel:[0,1,0]
	v_pk_fma_f32 v[142:143], v[250:251], v[106:107], v[142:143] op_sel:[0,1,0]
	v_add_f32_dpp v108, v252, v252 quad_perm:[1,0,3,2] row_mask:0xf bank_mask:0xf
	v_add_f32_dpp v109, v253, v253 quad_perm:[1,0,3,2] row_mask:0xf bank_mask:0xf
	v_add_f32_dpp v110, v254, v254 quad_perm:[1,0,3,2] row_mask:0xf bank_mask:0xf
	v_add_f32_dpp v111, v255, v255 quad_perm:[1,0,3,2] row_mask:0xf bank_mask:0xf
	v_cndmask_b32_e32 v108, v110, v108, vcc
	v_cndmask_b32_e32 v109, v111, v109, vcc
	v_add_f32_dpp v114, v112, v112 quad_perm:[2,3,0,1] row_mask:0xf bank_mask:0xf
	v_add_f32_dpp v115, v113, v113 quad_perm:[2,3,0,1] row_mask:0xf bank_mask:0xf
	v_cndmask_b32_e64 v112, v115, v114, s[4:5]
	v_cndmask_b32_e64 v117, v112, v116, s[6:7]
	v_cndmask_b32_e64 v118, v116, v112, s[6:7]
	s_waitcnt vmcnt(25)
; DI void attn_sample_item(const Params& p, int item, ldsp lds, int tid_) {
;     ...
;   SC_SCORE(kvA, 0)
;   SC_SCORE(kvB, 1)
	v_pk_mul_f32 v[252:253], v[236:237], v[100:101] op_sel_hi:[1,0]
	v_pk_mul_f32 v[254:255], v[244:245], v[100:101] op_sel_hi:[1,0]
	v_pk_fma_f32 v[252:253], v[238:239], v[100:101], v[252:253] op_sel:[0,1,0]
	v_pk_fma_f32 v[254:255], v[246:247], v[100:101], v[254:255] op_sel:[0,1,0]
	v_pk_fma_f32 v[252:253], v[240:241], v[102:103], v[252:253] op_sel_hi:[1,0,1]
	v_pk_fma_f32 v[254:255], v[248:249], v[102:103], v[254:255] op_sel_hi:[1,0,1]
	v_pk_fma_f32 v[252:253], v[242:243], v[102:103], v[252:253] op_sel:[0,1,0]
	v_pk_fma_f32 v[254:255], v[250:251], v[102:103], v[254:255] op_sel:[0,1,0]
	v_add_f32_dpp v116, v118, v117 row_ror:4 row_mask:0xf bank_mask:0xf
	v_cndmask_b32_e64 v125, v116, v124, s[64:65]
	v_cndmask_b32_e64 v126, v124, v116, s[64:65]
	v_add_f32_dpp v104, v140, v140 quad_perm:[1,0,3,2] row_mask:0xf bank_mask:0xf
	v_add_f32_dpp v105, v141, v141 quad_perm:[1,0,3,2] row_mask:0xf bank_mask:0xf
	v_add_f32_dpp v106, v142, v142 quad_perm:[1,0,3,2] row_mask:0xf bank_mask:0xf
	v_add_f32_dpp v107, v143, v143 quad_perm:[1,0,3,2] row_mask:0xf bank_mask:0xf
	v_cndmask_b32_e32 v104, v106, v104, vcc
	v_cndmask_b32_e32 v105, v107, v105, vcc
	v_add_f32_dpp v110, v108, v108 quad_perm:[2,3,0,1] row_mask:0xf bank_mask:0xf
	v_add_f32_dpp v111, v109, v109 quad_perm:[2,3,0,1] row_mask:0xf bank_mask:0xf
	v_cndmask_b32_e64 v108, v111, v110, s[4:5]
	s_waitcnt vmcnt(24)
	v_pk_mul_f32 v[140:141], v[236:237], v[96:97] op_sel_hi:[1,0]
	v_pk_mul_f32 v[142:143], v[244:245], v[96:97] op_sel_hi:[1,0]
	v_pk_fma_f32 v[140:141], v[238:239], v[96:97], v[140:141] op_sel:[0,1,0]
	v_pk_fma_f32 v[142:143], v[246:247], v[96:97], v[142:143] op_sel:[0,1,0]
	v_pk_fma_f32 v[140:141], v[240:241], v[98:99], v[140:141] op_sel_hi:[1,0,1]
	v_pk_fma_f32 v[142:143], v[248:249], v[98:99], v[142:143] op_sel_hi:[1,0,1]
	v_pk_fma_f32 v[140:141], v[242:243], v[98:99], v[140:141] op_sel:[0,1,0]
	v_pk_fma_f32 v[142:143], v[250:251], v[98:99], v[142:143] op_sel:[0,1,0]
	v_add_f32_dpp v124, v126, v125 row_ror:8 row_mask:0xf bank_mask:0xf
	v_add_f32_dpp v100, v252, v252 quad_perm:[1,0,3,2] row_mask:0xf bank_mask:0xf
	v_add_f32_dpp v101, v253, v253 quad_perm:[1,0,3,2] row_mask:0xf bank_mask:0xf
	v_add_f32_dpp v102, v254, v254 quad_perm:[1,0,3,2] row_mask:0xf bank_mask:0xf
	v_add_f32_dpp v103, v255, v255 quad_perm:[1,0,3,2] row_mask:0xf bank_mask:0xf
	v_cndmask_b32_e32 v100, v102, v100, vcc
	v_cndmask_b32_e32 v101, v103, v101, vcc
	v_add_f32_dpp v106, v104, v104 quad_perm:[2,3,0,1] row_mask:0xf bank_mask:0xf
	v_add_f32_dpp v107, v105, v105 quad_perm:[2,3,0,1] row_mask:0xf bank_mask:0xf
	v_cndmask_b32_e64 v104, v107, v106, s[4:5]
	v_cndmask_b32_e64 v109, v104, v108, s[6:7]
	v_cndmask_b32_e64 v110, v108, v104, s[6:7]
	s_waitcnt vmcnt(23)
	v_pk_mul_f32 v[252:253], v[236:237], v[92:93] op_sel_hi:[1,0]
	v_pk_mul_f32 v[254:255], v[244:245], v[92:93] op_sel_hi:[1,0]
	v_pk_fma_f32 v[252:253], v[238:239], v[92:93], v[252:253] op_sel:[0,1,0]
	v_pk_fma_f32 v[254:255], v[246:247], v[92:93], v[254:255] op_sel:[0,1,0]
	v_pk_fma_f32 v[252:253], v[240:241], v[94:95], v[252:253] op_sel_hi:[1,0,1]
	v_pk_fma_f32 v[254:255], v[248:249], v[94:95], v[254:255] op_sel_hi:[1,0,1]
	v_pk_fma_f32 v[252:253], v[242:243], v[94:95], v[252:253] op_sel:[0,1,0]
	v_pk_fma_f32 v[254:255], v[250:251], v[94:95], v[254:255] op_sel:[0,1,0]
	v_add_f32_dpp v108, v110, v109 row_ror:4 row_mask:0xf bank_mask:0xf
	v_add_f32_dpp v96, v140, v140 quad_perm:[1,0,3,2] row_mask:0xf bank_mask:0xf
	v_add_f32_dpp v97, v141, v141 quad_perm:[1,0,3,2] row_mask:0xf bank_mask:0xf
	v_add_f32_dpp v98, v142, v142 quad_perm:[1,0,3,2] row_mask:0xf bank_mask:0xf
	v_add_f32_dpp v99, v143, v143 quad_perm:[1,0,3,2] row_mask:0xf bank_mask:0xf
	v_cndmask_b32_e32 v96, v98, v96, vcc
	v_cndmask_b32_e32 v97, v99, v97, vcc
	v_add_f32_dpp v102, v100, v100 quad_perm:[2,3,0,1] row_mask:0xf bank_mask:0xf
	v_add_f32_dpp v103, v101, v101 quad_perm:[2,3,0,1] row_mask:0xf bank_mask:0xf
	v_cndmask_b32_e64 v100, v103, v102, s[4:5]
	s_waitcnt vmcnt(22)
	v_pk_mul_f32 v[140:141], v[236:237], v[88:89] op_sel_hi:[1,0]
	v_pk_mul_f32 v[142:143], v[244:245], v[88:89] op_sel_hi:[1,0]
	v_pk_fma_f32 v[140:141], v[238:239], v[88:89], v[140:141] op_sel:[0,1,0]
	v_pk_fma_f32 v[142:143], v[246:247], v[88:89], v[142:143] op_sel:[0,1,0]
	v_pk_fma_f32 v[140:141], v[240:241], v[90:91], v[140:141] op_sel_hi:[1,0,1]
	v_pk_fma_f32 v[142:143], v[248:249], v[90:91], v[142:143] op_sel_hi:[1,0,1]
	v_pk_fma_f32 v[140:141], v[242:243], v[90:91], v[140:141] op_sel:[0,1,0]
	v_pk_fma_f32 v[142:143], v[250:251], v[90:91], v[142:143] op_sel:[0,1,0]
	v_add_f32_dpp v92, v252, v252 quad_perm:[1,0,3,2] row_mask:0xf bank_mask:0xf
	v_add_f32_dpp v93, v253, v253 quad_perm:[1,0,3,2] row_mask:0xf bank_mask:0xf
	v_add_f32_dpp v94, v254, v254 quad_perm:[1,0,3,2] row_mask:0xf bank_mask:0xf
	v_add_f32_dpp v95, v255, v255 quad_perm:[1,0,3,2] row_mask:0xf bank_mask:0xf
	v_cndmask_b32_e32 v92, v94, v92, vcc
	v_cndmask_b32_e32 v93, v95, v93, vcc
	v_add_f32_dpp v98, v96, v96 quad_perm:[2,3,0,1] row_mask:0xf bank_mask:0xf
	v_add_f32_dpp v99, v97, v97 quad_perm:[2,3,0,1] row_mask:0xf bank_mask:0xf
	v_cndmask_b32_e64 v96, v99, v98, s[4:5]
	v_cndmask_b32_e64 v101, v96, v100, s[6:7]
	v_cndmask_b32_e64 v102, v100, v96, s[6:7]
	s_waitcnt vmcnt(21)
; DI void attn_sample_item(const Params& p, int item, ldsp lds, int tid_) {
;     ...
;   SC_SCORE(kvA, 0)
;   SC_SCORE(kvB, 1)
	v_pk_mul_f32 v[252:253], v[236:237], v[84:85] op_sel_hi:[1,0]
	v_pk_mul_f32 v[254:255], v[244:245], v[84:85] op_sel_hi:[1,0]
	v_pk_fma_f32 v[252:253], v[238:239], v[84:85], v[252:253] op_sel:[0,1,0]
	v_pk_fma_f32 v[254:255], v[246:247], v[84:85], v[254:255] op_sel:[0,1,0]
	v_pk_fma_f32 v[252:253], v[240:241], v[86:87], v[252:253] op_sel_hi:[1,0,1]
	v_pk_fma_f32 v[254:255], v[248:249], v[86:87], v[254:255] op_sel_hi:[1,0,1]
	v_pk_fma_f32 v[252:253], v[242:243], v[86:87], v[252:253] op_sel:[0,1,0]
	v_pk_fma_f32 v[254:255], v[250:251], v[86:87], v[254:255] op_sel:[0,1,0]
	v_add_f32_dpp v100, v102, v101 row_ror:4 row_mask:0xf bank_mask:0xf
	v_cndmask_b32_e64 v109, v100, v108, s[64:65]
	v_cndmask_b32_e64 v110, v108, v100, s[64:65]
	v_add_f32_dpp v88, v140, v140 quad_perm:[1,0,3,2] row_mask:0xf bank_mask:0xf
	v_add_f32_dpp v89, v141, v141 quad_perm:[1,0,3,2] row_mask:0xf bank_mask:0xf
	v_add_f32_dpp v90, v142, v142 quad_perm:[1,0,3,2] row_mask:0xf bank_mask:0xf
	v_add_f32_dpp v91, v143, v143 quad_perm:[1,0,3,2] row_mask:0xf bank_mask:0xf
	v_cndmask_b32_e32 v88, v90, v88, vcc
	v_cndmask_b32_e32 v89, v91, v89, vcc
	v_add_f32_dpp v94, v92, v92 quad_perm:[2,3,0,1] row_mask:0xf bank_mask:0xf
	v_add_f32_dpp v95, v93, v93 quad_perm:[2,3,0,1] row_mask:0xf bank_mask:0xf
	v_cndmask_b32_e64 v92, v95, v94, s[4:5]
	s_waitcnt vmcnt(20)
	v_pk_mul_f32 v[140:141], v[236:237], v[80:81] op_sel_hi:[1,0]
	v_pk_mul_f32 v[142:143], v[244:245], v[80:81] op_sel_hi:[1,0]
	v_pk_fma_f32 v[140:141], v[238:239], v[80:81], v[140:141] op_sel:[0,1,0]
	v_pk_fma_f32 v[142:143], v[246:247], v[80:81], v[142:143] op_sel:[0,1,0]
	v_pk_fma_f32 v[140:141], v[240:241], v[82:83], v[140:141] op_sel_hi:[1,0,1]
	v_pk_fma_f32 v[142:143], v[248:249], v[82:83], v[142:143] op_sel_hi:[1,0,1]
	v_pk_fma_f32 v[140:141], v[242:243], v[82:83], v[140:141] op_sel:[0,1,0]
	v_pk_fma_f32 v[142:143], v[250:251], v[82:83], v[142:143] op_sel:[0,1,0]
	v_add_f32_dpp v108, v110, v109 row_ror:8 row_mask:0xf bank_mask:0xf
	v_add_f32_dpp v84, v252, v252 quad_perm:[1,0,3,2] row_mask:0xf bank_mask:0xf
	v_add_f32_dpp v85, v253, v253 quad_perm:[1,0,3,2] row_mask:0xf bank_mask:0xf
	v_add_f32_dpp v86, v254, v254 quad_perm:[1,0,3,2] row_mask:0xf bank_mask:0xf
	v_add_f32_dpp v87, v255, v255 quad_perm:[1,0,3,2] row_mask:0xf bank_mask:0xf
	v_cndmask_b32_e32 v84, v86, v84, vcc
	v_cndmask_b32_e32 v85, v87, v85, vcc
	v_add_f32_dpp v90, v88, v88 quad_perm:[2,3,0,1] row_mask:0xf bank_mask:0xf
	v_add_f32_dpp v91, v89, v89 quad_perm:[2,3,0,1] row_mask:0xf bank_mask:0xf
	v_cndmask_b32_e64 v88, v91, v90, s[4:5]
	v_cndmask_b32_e64 v93, v88, v92, s[6:7]
	v_cndmask_b32_e64 v94, v92, v88, s[6:7]
	s_waitcnt vmcnt(19)
	v_pk_mul_f32 v[252:253], v[236:237], v[76:77] op_sel_hi:[1,0]
	v_pk_mul_f32 v[254:255], v[244:245], v[76:77] op_sel_hi:[1,0]
	v_pk_fma_f32 v[252:253], v[238:239], v[76:77], v[252:253] op_sel:[0,1,0]
	v_pk_fma_f32 v[254:255], v[246:247], v[76:77], v[254:255] op_sel:[0,1,0]
	v_pk_fma_f32 v[252:253], v[240:241], v[78:79], v[252:253] op_sel_hi:[1,0,1]
	v_pk_fma_f32 v[254:255], v[248:249], v[78:79], v[254:255] op_sel_hi:[1,0,1]
	v_pk_fma_f32 v[252:253], v[242:243], v[78:79], v[252:253] op_sel:[0,1,0]
	v_pk_fma_f32 v[254:255], v[250:251], v[78:79], v[254:255] op_sel:[0,1,0]
	v_permlane16_swap_b32_e32 v124, v108
	v_add_f32_e32 v124, v124, v108
	v_add_f32_dpp v92, v94, v93 row_ror:4 row_mask:0xf bank_mask:0xf
	v_add_f32_dpp v80, v140, v140 quad_perm:[1,0,3,2] row_mask:0xf bank_mask:0xf
	v_add_f32_dpp v81, v141, v141 quad_perm:[1,0,3,2] row_mask:0xf bank_mask:0xf
	v_add_f32_dpp v82, v142, v142 quad_perm:[1,0,3,2] row_mask:0xf bank_mask:0xf
	v_add_f32_dpp v83, v143, v143 quad_perm:[1,0,3,2] row_mask:0xf bank_mask:0xf
	v_cndmask_b32_e32 v80, v82, v80, vcc
	v_cndmask_b32_e32 v81, v83, v81, vcc
	v_add_f32_dpp v86, v84, v84 quad_perm:[2,3,0,1] row_mask:0xf bank_mask:0xf
	v_add_f32_dpp v87, v85, v85 quad_perm:[2,3,0,1] row_mask:0xf bank_mask:0xf
	v_cndmask_b32_e64 v84, v87, v86, s[4:5]
	s_waitcnt vmcnt(18)
	v_pk_mul_f32 v[140:141], v[236:237], v[72:73] op_sel_hi:[1,0]
	v_pk_mul_f32 v[142:143], v[244:245], v[72:73] op_sel_hi:[1,0]
	v_pk_fma_f32 v[140:141], v[238:239], v[72:73], v[140:141] op_sel:[0,1,0]
	v_pk_fma_f32 v[142:143], v[246:247], v[72:73], v[142:143] op_sel:[0,1,0]
	v_pk_fma_f32 v[140:141], v[240:241], v[74:75], v[140:141] op_sel_hi:[1,0,1]
	v_pk_fma_f32 v[142:143], v[248:249], v[74:75], v[142:143] op_sel_hi:[1,0,1]
	v_pk_fma_f32 v[140:141], v[242:243], v[74:75], v[140:141] op_sel:[0,1,0]
	v_pk_fma_f32 v[142:143], v[250:251], v[74:75], v[142:143] op_sel:[0,1,0]
	v_add_f32_dpp v76, v252, v252 quad_perm:[1,0,3,2] row_mask:0xf bank_mask:0xf
	v_add_f32_dpp v77, v253, v253 quad_perm:[1,0,3,2] row_mask:0xf bank_mask:0xf
	v_add_f32_dpp v78, v254, v254 quad_perm:[1,0,3,2] row_mask:0xf bank_mask:0xf
	v_add_f32_dpp v79, v255, v255 quad_perm:[1,0,3,2] row_mask:0xf bank_mask:0xf
	v_cndmask_b32_e32 v76, v78, v76, vcc
	v_cndmask_b32_e32 v77, v79, v77, vcc
	v_add_f32_dpp v82, v80, v80 quad_perm:[2,3,0,1] row_mask:0xf bank_mask:0xf
	v_add_f32_dpp v83, v81, v81 quad_perm:[2,3,0,1] row_mask:0xf bank_mask:0xf
	v_cndmask_b32_e64 v80, v83, v82, s[4:5]
	v_cndmask_b32_e64 v85, v80, v84, s[6:7]
	v_cndmask_b32_e64 v86, v84, v80, s[6:7]
	s_waitcnt vmcnt(17)
; DI void attn_sample_item(const Params& p, int item, ldsp lds, int tid_) {
;     ...
;   SC_SCORE(kvA, 0)
;   SC_SCORE(kvB, 1)
	v_pk_mul_f32 v[252:253], v[236:237], v[68:69] op_sel_hi:[1,0]
	v_pk_mul_f32 v[254:255], v[244:245], v[68:69] op_sel_hi:[1,0]
	v_pk_fma_f32 v[252:253], v[238:239], v[68:69], v[252:253] op_sel:[0,1,0]
	v_pk_fma_f32 v[254:255], v[246:247], v[68:69], v[254:255] op_sel:[0,1,0]
	v_pk_fma_f32 v[252:253], v[240:241], v[70:71], v[252:253] op_sel_hi:[1,0,1]
	v_pk_fma_f32 v[254:255], v[248:249], v[70:71], v[254:255] op_sel_hi:[1,0,1]
	v_pk_fma_f32 v[252:253], v[242:243], v[70:71], v[252:253] op_sel:[0,1,0]
	v_pk_fma_f32 v[254:255], v[250:251], v[70:71], v[254:255] op_sel:[0,1,0]
	v_add_f32_dpp v84, v86, v85 row_ror:4 row_mask:0xf bank_mask:0xf
	v_cndmask_b32_e64 v93, v84, v92, s[64:65]
	v_cndmask_b32_e64 v94, v92, v84, s[64:65]
	v_add_f32_dpp v72, v140, v140 quad_perm:[1,0,3,2] row_mask:0xf bank_mask:0xf
	v_add_f32_dpp v73, v141, v141 quad_perm:[1,0,3,2] row_mask:0xf bank_mask:0xf
	v_add_f32_dpp v74, v142, v142 quad_perm:[1,0,3,2] row_mask:0xf bank_mask:0xf
	v_add_f32_dpp v75, v143, v143 quad_perm:[1,0,3,2] row_mask:0xf bank_mask:0xf
	v_cndmask_b32_e32 v72, v74, v72, vcc
	v_cndmask_b32_e32 v73, v75, v73, vcc
	v_add_f32_dpp v78, v76, v76 quad_perm:[2,3,0,1] row_mask:0xf bank_mask:0xf
	v_add_f32_dpp v79, v77, v77 quad_perm:[2,3,0,1] row_mask:0xf bank_mask:0xf
	v_cndmask_b32_e64 v76, v79, v78, s[4:5]
	s_waitcnt vmcnt(16)
	v_pk_mul_f32 v[140:141], v[236:237], v[64:65] op_sel_hi:[1,0]
	v_pk_mul_f32 v[142:143], v[244:245], v[64:65] op_sel_hi:[1,0]
	v_pk_fma_f32 v[140:141], v[238:239], v[64:65], v[140:141] op_sel:[0,1,0]
	v_pk_fma_f32 v[142:143], v[246:247], v[64:65], v[142:143] op_sel:[0,1,0]
	v_pk_fma_f32 v[140:141], v[240:241], v[66:67], v[140:141] op_sel_hi:[1,0,1]
	v_pk_fma_f32 v[142:143], v[248:249], v[66:67], v[142:143] op_sel_hi:[1,0,1]
	v_pk_fma_f32 v[140:141], v[242:243], v[66:67], v[140:141] op_sel:[0,1,0]
	v_pk_fma_f32 v[142:143], v[250:251], v[66:67], v[142:143] op_sel:[0,1,0]
	v_add_f32_dpp v92, v94, v93 row_ror:8 row_mask:0xf bank_mask:0xf
	v_add_f32_dpp v68, v252, v252 quad_perm:[1,0,3,2] row_mask:0xf bank_mask:0xf
	v_add_f32_dpp v69, v253, v253 quad_perm:[1,0,3,2] row_mask:0xf bank_mask:0xf
	v_add_f32_dpp v70, v254, v254 quad_perm:[1,0,3,2] row_mask:0xf bank_mask:0xf
	v_add_f32_dpp v71, v255, v255 quad_perm:[1,0,3,2] row_mask:0xf bank_mask:0xf
	v_cndmask_b32_e32 v68, v70, v68, vcc
	v_cndmask_b32_e32 v69, v71, v69, vcc
	v_add_f32_dpp v74, v72, v72 quad_perm:[2,3,0,1] row_mask:0xf bank_mask:0xf
	v_add_f32_dpp v75, v73, v73 quad_perm:[2,3,0,1] row_mask:0xf bank_mask:0xf
	v_cndmask_b32_e64 v72, v75, v74, s[4:5]
	v_cndmask_b32_e64 v77, v72, v76, s[6:7]
	v_cndmask_b32_e64 v78, v76, v72, s[6:7]
	s_waitcnt vmcnt(15)
	v_pk_mul_f32 v[252:253], v[236:237], v[60:61] op_sel_hi:[1,0]
	v_pk_mul_f32 v[254:255], v[244:245], v[60:61] op_sel_hi:[1,0]
	v_pk_fma_f32 v[252:253], v[238:239], v[60:61], v[252:253] op_sel:[0,1,0]
	v_pk_fma_f32 v[254:255], v[246:247], v[60:61], v[254:255] op_sel:[0,1,0]
	v_pk_fma_f32 v[252:253], v[240:241], v[62:63], v[252:253] op_sel_hi:[1,0,1]
	v_pk_fma_f32 v[254:255], v[248:249], v[62:63], v[254:255] op_sel_hi:[1,0,1]
	v_pk_fma_f32 v[252:253], v[242:243], v[62:63], v[252:253] op_sel:[0,1,0]
	v_pk_fma_f32 v[254:255], v[250:251], v[62:63], v[254:255] op_sel:[0,1,0]
	v_add_f32_dpp v76, v78, v77 row_ror:4 row_mask:0xf bank_mask:0xf
	v_add_f32_dpp v64, v140, v140 quad_perm:[1,0,3,2] row_mask:0xf bank_mask:0xf
	v_add_f32_dpp v65, v141, v141 quad_perm:[1,0,3,2] row_mask:0xf bank_mask:0xf
	v_add_f32_dpp v66, v142, v142 quad_perm:[1,0,3,2] row_mask:0xf bank_mask:0xf
	v_add_f32_dpp v67, v143, v143 quad_perm:[1,0,3,2] row_mask:0xf bank_mask:0xf
	v_cndmask_b32_e32 v64, v66, v64, vcc
	v_cndmask_b32_e32 v65, v67, v65, vcc
	v_add_f32_dpp v70, v68, v68 quad_perm:[2,3,0,1] row_mask:0xf bank_mask:0xf
	v_add_f32_dpp v71, v69, v69 quad_perm:[2,3,0,1] row_mask:0xf bank_mask:0xf
	v_cndmask_b32_e64 v68, v71, v70, s[4:5]
	s_waitcnt vmcnt(14)
	v_pk_mul_f32 v[140:141], v[236:237], v[56:57] op_sel_hi:[1,0]
	v_pk_mul_f32 v[142:143], v[244:245], v[56:57] op_sel_hi:[1,0]
	v_pk_fma_f32 v[140:141], v[238:239], v[56:57], v[140:141] op_sel:[0,1,0]
	v_pk_fma_f32 v[142:143], v[246:247], v[56:57], v[142:143] op_sel:[0,1,0]
	v_pk_fma_f32 v[140:141], v[240:241], v[58:59], v[140:141] op_sel_hi:[1,0,1]
	v_pk_fma_f32 v[142:143], v[248:249], v[58:59], v[142:143] op_sel_hi:[1,0,1]
	v_pk_fma_f32 v[140:141], v[242:243], v[58:59], v[140:141] op_sel:[0,1,0]
	v_pk_fma_f32 v[142:143], v[250:251], v[58:59], v[142:143] op_sel:[0,1,0]
	v_add_f32_dpp v60, v252, v252 quad_perm:[1,0,3,2] row_mask:0xf bank_mask:0xf
	v_add_f32_dpp v61, v253, v253 quad_perm:[1,0,3,2] row_mask:0xf bank_mask:0xf
	v_add_f32_dpp v62, v254, v254 quad_perm:[1,0,3,2] row_mask:0xf bank_mask:0xf
	v_add_f32_dpp v63, v255, v255 quad_perm:[1,0,3,2] row_mask:0xf bank_mask:0xf
	v_cndmask_b32_e32 v60, v62, v60, vcc
	v_cndmask_b32_e32 v61, v63, v61, vcc
	v_add_f32_dpp v66, v64, v64 quad_perm:[2,3,0,1] row_mask:0xf bank_mask:0xf
	v_add_f32_dpp v67, v65, v65 quad_perm:[2,3,0,1] row_mask:0xf bank_mask:0xf
	v_cndmask_b32_e64 v64, v67, v66, s[4:5]
	v_cndmask_b32_e64 v69, v64, v68, s[6:7]
	v_cndmask_b32_e64 v70, v68, v64, s[6:7]
	s_waitcnt vmcnt(13)
; DI void attn_sample_item(const Params& p, int item, ldsp lds, int tid_) {
;     ...
;   SC_SCORE(kvA, 0)
;   SC_SCORE(kvB, 1)
	v_pk_mul_f32 v[252:253], v[236:237], v[52:53] op_sel_hi:[1,0]
	v_pk_mul_f32 v[254:255], v[244:245], v[52:53] op_sel_hi:[1,0]
	v_pk_fma_f32 v[252:253], v[238:239], v[52:53], v[252:253] op_sel:[0,1,0]
	v_pk_fma_f32 v[254:255], v[246:247], v[52:53], v[254:255] op_sel:[0,1,0]
	v_pk_fma_f32 v[252:253], v[240:241], v[54:55], v[252:253] op_sel_hi:[1,0,1]
	v_pk_fma_f32 v[254:255], v[248:249], v[54:55], v[254:255] op_sel_hi:[1,0,1]
	v_pk_fma_f32 v[252:253], v[242:243], v[54:55], v[252:253] op_sel:[0,1,0]
	v_pk_fma_f32 v[254:255], v[250:251], v[54:55], v[254:255] op_sel:[0,1,0]
	v_add_f32_dpp v68, v70, v69 row_ror:4 row_mask:0xf bank_mask:0xf
	v_cndmask_b32_e64 v77, v68, v76, s[64:65]
	v_cndmask_b32_e64 v78, v76, v68, s[64:65]
	v_add_f32_dpp v56, v140, v140 quad_perm:[1,0,3,2] row_mask:0xf bank_mask:0xf
	v_add_f32_dpp v57, v141, v141 quad_perm:[1,0,3,2] row_mask:0xf bank_mask:0xf
	v_add_f32_dpp v58, v142, v142 quad_perm:[1,0,3,2] row_mask:0xf bank_mask:0xf
	v_add_f32_dpp v59, v143, v143 quad_perm:[1,0,3,2] row_mask:0xf bank_mask:0xf
	v_cndmask_b32_e32 v56, v58, v56, vcc
	v_cndmask_b32_e32 v57, v59, v57, vcc
	v_add_f32_dpp v62, v60, v60 quad_perm:[2,3,0,1] row_mask:0xf bank_mask:0xf
	v_add_f32_dpp v63, v61, v61 quad_perm:[2,3,0,1] row_mask:0xf bank_mask:0xf
	v_cndmask_b32_e64 v60, v63, v62, s[4:5]
	s_waitcnt vmcnt(12)
	v_pk_mul_f32 v[140:141], v[236:237], v[48:49] op_sel_hi:[1,0]
	v_pk_mul_f32 v[142:143], v[244:245], v[48:49] op_sel_hi:[1,0]
	v_pk_fma_f32 v[140:141], v[238:239], v[48:49], v[140:141] op_sel:[0,1,0]
	v_pk_fma_f32 v[142:143], v[246:247], v[48:49], v[142:143] op_sel:[0,1,0]
	v_pk_fma_f32 v[140:141], v[240:241], v[50:51], v[140:141] op_sel_hi:[1,0,1]
	v_pk_fma_f32 v[142:143], v[248:249], v[50:51], v[142:143] op_sel_hi:[1,0,1]
	v_pk_fma_f32 v[140:141], v[242:243], v[50:51], v[140:141] op_sel:[0,1,0]
	v_pk_fma_f32 v[142:143], v[250:251], v[50:51], v[142:143] op_sel:[0,1,0]
	v_add_f32_dpp v76, v78, v77 row_ror:8 row_mask:0xf bank_mask:0xf
	v_add_f32_dpp v52, v252, v252 quad_perm:[1,0,3,2] row_mask:0xf bank_mask:0xf
	v_add_f32_dpp v53, v253, v253 quad_perm:[1,0,3,2] row_mask:0xf bank_mask:0xf
	v_add_f32_dpp v54, v254, v254 quad_perm:[1,0,3,2] row_mask:0xf bank_mask:0xf
	v_add_f32_dpp v55, v255, v255 quad_perm:[1,0,3,2] row_mask:0xf bank_mask:0xf
	v_cndmask_b32_e32 v52, v54, v52, vcc
	v_cndmask_b32_e32 v53, v55, v53, vcc
	v_add_f32_dpp v58, v56, v56 quad_perm:[2,3,0,1] row_mask:0xf bank_mask:0xf
	v_add_f32_dpp v59, v57, v57 quad_perm:[2,3,0,1] row_mask:0xf bank_mask:0xf
	v_cndmask_b32_e64 v56, v59, v58, s[4:5]
	v_cndmask_b32_e64 v61, v56, v60, s[6:7]
	v_cndmask_b32_e64 v62, v60, v56, s[6:7]
	s_waitcnt vmcnt(11)
	v_pk_mul_f32 v[252:253], v[236:237], v[44:45] op_sel_hi:[1,0]
	v_pk_mul_f32 v[254:255], v[244:245], v[44:45] op_sel_hi:[1,0]
	v_pk_fma_f32 v[252:253], v[238:239], v[44:45], v[252:253] op_sel:[0,1,0]
	v_pk_fma_f32 v[254:255], v[246:247], v[44:45], v[254:255] op_sel:[0,1,0]
	v_pk_fma_f32 v[252:253], v[240:241], v[46:47], v[252:253] op_sel_hi:[1,0,1]
	v_pk_fma_f32 v[254:255], v[248:249], v[46:47], v[254:255] op_sel_hi:[1,0,1]
	v_pk_fma_f32 v[252:253], v[242:243], v[46:47], v[252:253] op_sel:[0,1,0]
	v_pk_fma_f32 v[254:255], v[250:251], v[46:47], v[254:255] op_sel:[0,1,0]
	v_permlane16_swap_b32_e32 v92, v76
	v_add_f32_e32 v92, v92, v76
	v_add_f32_dpp v60, v62, v61 row_ror:4 row_mask:0xf bank_mask:0xf
	v_add_f32_dpp v48, v140, v140 quad_perm:[1,0,3,2] row_mask:0xf bank_mask:0xf
	v_add_f32_dpp v49, v141, v141 quad_perm:[1,0,3,2] row_mask:0xf bank_mask:0xf
	v_add_f32_dpp v50, v142, v142 quad_perm:[1,0,3,2] row_mask:0xf bank_mask:0xf
	v_add_f32_dpp v51, v143, v143 quad_perm:[1,0,3,2] row_mask:0xf bank_mask:0xf
	v_cndmask_b32_e32 v48, v50, v48, vcc
	v_cndmask_b32_e32 v49, v51, v49, vcc
	v_add_f32_dpp v54, v52, v52 quad_perm:[2,3,0,1] row_mask:0xf bank_mask:0xf
	v_add_f32_dpp v55, v53, v53 quad_perm:[2,3,0,1] row_mask:0xf bank_mask:0xf
	v_cndmask_b32_e64 v52, v55, v54, s[4:5]
	s_waitcnt vmcnt(10)
	v_pk_mul_f32 v[140:141], v[236:237], v[40:41] op_sel_hi:[1,0]
	v_pk_mul_f32 v[142:143], v[244:245], v[40:41] op_sel_hi:[1,0]
	v_pk_fma_f32 v[140:141], v[238:239], v[40:41], v[140:141] op_sel:[0,1,0]
	v_pk_fma_f32 v[142:143], v[246:247], v[40:41], v[142:143] op_sel:[0,1,0]
	v_pk_fma_f32 v[140:141], v[240:241], v[42:43], v[140:141] op_sel_hi:[1,0,1]
	v_pk_fma_f32 v[142:143], v[248:249], v[42:43], v[142:143] op_sel_hi:[1,0,1]
	v_pk_fma_f32 v[140:141], v[242:243], v[42:43], v[140:141] op_sel:[0,1,0]
	v_pk_fma_f32 v[142:143], v[250:251], v[42:43], v[142:143] op_sel:[0,1,0]
	v_permlane32_swap_b32_e32 v124, v92
	v_add_f32_e32 v124, v124, v92
	ds_write_b32 v235, v124
	v_add_f32_dpp v44, v252, v252 quad_perm:[1,0,3,2] row_mask:0xf bank_mask:0xf
	v_add_f32_dpp v45, v253, v253 quad_perm:[1,0,3,2] row_mask:0xf bank_mask:0xf
	v_add_f32_dpp v46, v254, v254 quad_perm:[1,0,3,2] row_mask:0xf bank_mask:0xf
	v_add_f32_dpp v47, v255, v255 quad_perm:[1,0,3,2] row_mask:0xf bank_mask:0xf
	v_cndmask_b32_e32 v44, v46, v44, vcc
	v_cndmask_b32_e32 v45, v47, v45, vcc
	v_add_f32_dpp v50, v48, v48 quad_perm:[2,3,0,1] row_mask:0xf bank_mask:0xf
	v_add_f32_dpp v51, v49, v49 quad_perm:[2,3,0,1] row_mask:0xf bank_mask:0xf
	v_cndmask_b32_e64 v48, v51, v50, s[4:5]
	v_cndmask_b32_e64 v53, v48, v52, s[6:7]
	v_cndmask_b32_e64 v54, v52, v48, s[6:7]
	s_waitcnt vmcnt(9)
; DI void attn_sample_item(const Params& p, int item, ldsp lds, int tid_) {
;     ...
;   SC_SCORE(kvA, 0)
;   SC_SCORE(kvB, 1)
	v_pk_mul_f32 v[252:253], v[236:237], v[36:37] op_sel_hi:[1,0]
	v_pk_mul_f32 v[254:255], v[244:245], v[36:37] op_sel_hi:[1,0]
	v_pk_fma_f32 v[252:253], v[238:239], v[36:37], v[252:253] op_sel:[0,1,0]
	v_pk_fma_f32 v[254:255], v[246:247], v[36:37], v[254:255] op_sel:[0,1,0]
	v_pk_fma_f32 v[252:253], v[240:241], v[38:39], v[252:253] op_sel_hi:[1,0,1]
	v_pk_fma_f32 v[254:255], v[248:249], v[38:39], v[254:255] op_sel_hi:[1,0,1]
	v_pk_fma_f32 v[252:253], v[242:243], v[38:39], v[252:253] op_sel:[0,1,0]
	v_pk_fma_f32 v[254:255], v[250:251], v[38:39], v[254:255] op_sel:[0,1,0]
	v_add_f32_dpp v52, v54, v53 row_ror:4 row_mask:0xf bank_mask:0xf
	v_cndmask_b32_e64 v61, v52, v60, s[64:65]
	v_cndmask_b32_e64 v62, v60, v52, s[64:65]
	v_add_f32_dpp v40, v140, v140 quad_perm:[1,0,3,2] row_mask:0xf bank_mask:0xf
	v_add_f32_dpp v41, v141, v141 quad_perm:[1,0,3,2] row_mask:0xf bank_mask:0xf
	v_add_f32_dpp v42, v142, v142 quad_perm:[1,0,3,2] row_mask:0xf bank_mask:0xf
	v_add_f32_dpp v43, v143, v143 quad_perm:[1,0,3,2] row_mask:0xf bank_mask:0xf
	v_cndmask_b32_e32 v40, v42, v40, vcc
	v_cndmask_b32_e32 v41, v43, v41, vcc
	v_add_f32_dpp v46, v44, v44 quad_perm:[2,3,0,1] row_mask:0xf bank_mask:0xf
	v_add_f32_dpp v47, v45, v45 quad_perm:[2,3,0,1] row_mask:0xf bank_mask:0xf
	v_cndmask_b32_e64 v44, v47, v46, s[4:5]
	s_waitcnt vmcnt(8)
	v_pk_mul_f32 v[140:141], v[236:237], v[32:33] op_sel_hi:[1,0]
	v_pk_mul_f32 v[142:143], v[244:245], v[32:33] op_sel_hi:[1,0]
	v_pk_fma_f32 v[140:141], v[238:239], v[32:33], v[140:141] op_sel:[0,1,0]
	v_pk_fma_f32 v[142:143], v[246:247], v[32:33], v[142:143] op_sel:[0,1,0]
	v_pk_fma_f32 v[140:141], v[240:241], v[34:35], v[140:141] op_sel_hi:[1,0,1]
	v_pk_fma_f32 v[142:143], v[248:249], v[34:35], v[142:143] op_sel_hi:[1,0,1]
	v_pk_fma_f32 v[140:141], v[242:243], v[34:35], v[140:141] op_sel:[0,1,0]
	v_pk_fma_f32 v[142:143], v[250:251], v[34:35], v[142:143] op_sel:[0,1,0]
	v_add_f32_dpp v60, v62, v61 row_ror:8 row_mask:0xf bank_mask:0xf
	v_add_f32_dpp v36, v252, v252 quad_perm:[1,0,3,2] row_mask:0xf bank_mask:0xf
	v_add_f32_dpp v37, v253, v253 quad_perm:[1,0,3,2] row_mask:0xf bank_mask:0xf
	v_add_f32_dpp v38, v254, v254 quad_perm:[1,0,3,2] row_mask:0xf bank_mask:0xf
	v_add_f32_dpp v39, v255, v255 quad_perm:[1,0,3,2] row_mask:0xf bank_mask:0xf
	v_cndmask_b32_e32 v36, v38, v36, vcc
	v_cndmask_b32_e32 v37, v39, v37, vcc
	v_add_f32_dpp v42, v40, v40 quad_perm:[2,3,0,1] row_mask:0xf bank_mask:0xf
	v_add_f32_dpp v43, v41, v41 quad_perm:[2,3,0,1] row_mask:0xf bank_mask:0xf
	v_cndmask_b32_e64 v40, v43, v42, s[4:5]
	v_cndmask_b32_e64 v45, v40, v44, s[6:7]
	v_cndmask_b32_e64 v46, v44, v40, s[6:7]
	s_waitcnt vmcnt(7)
	v_pk_mul_f32 v[252:253], v[236:237], v[28:29] op_sel_hi:[1,0]
	v_pk_mul_f32 v[254:255], v[244:245], v[28:29] op_sel_hi:[1,0]
	v_pk_fma_f32 v[252:253], v[238:239], v[28:29], v[252:253] op_sel:[0,1,0]
	v_pk_fma_f32 v[254:255], v[246:247], v[28:29], v[254:255] op_sel:[0,1,0]
	v_pk_fma_f32 v[252:253], v[240:241], v[30:31], v[252:253] op_sel_hi:[1,0,1]
	v_pk_fma_f32 v[254:255], v[248:249], v[30:31], v[254:255] op_sel_hi:[1,0,1]
	v_pk_fma_f32 v[252:253], v[242:243], v[30:31], v[252:253] op_sel:[0,1,0]
	v_pk_fma_f32 v[254:255], v[250:251], v[30:31], v[254:255] op_sel:[0,1,0]
	v_add_f32_dpp v44, v46, v45 row_ror:4 row_mask:0xf bank_mask:0xf
	v_add_f32_dpp v32, v140, v140 quad_perm:[1,0,3,2] row_mask:0xf bank_mask:0xf
	v_add_f32_dpp v33, v141, v141 quad_perm:[1,0,3,2] row_mask:0xf bank_mask:0xf
	v_add_f32_dpp v34, v142, v142 quad_perm:[1,0,3,2] row_mask:0xf bank_mask:0xf
	v_add_f32_dpp v35, v143, v143 quad_perm:[1,0,3,2] row_mask:0xf bank_mask:0xf
	v_cndmask_b32_e32 v32, v34, v32, vcc
	v_cndmask_b32_e32 v33, v35, v33, vcc
	v_add_f32_dpp v38, v36, v36 quad_perm:[2,3,0,1] row_mask:0xf bank_mask:0xf
	v_add_f32_dpp v39, v37, v37 quad_perm:[2,3,0,1] row_mask:0xf bank_mask:0xf
	v_cndmask_b32_e64 v36, v39, v38, s[4:5]
	s_waitcnt vmcnt(6)
	v_pk_mul_f32 v[140:141], v[236:237], v[24:25] op_sel_hi:[1,0]
	v_pk_mul_f32 v[142:143], v[244:245], v[24:25] op_sel_hi:[1,0]
	v_pk_fma_f32 v[140:141], v[238:239], v[24:25], v[140:141] op_sel:[0,1,0]
	v_pk_fma_f32 v[142:143], v[246:247], v[24:25], v[142:143] op_sel:[0,1,0]
	v_pk_fma_f32 v[140:141], v[240:241], v[26:27], v[140:141] op_sel_hi:[1,0,1]
	v_pk_fma_f32 v[142:143], v[248:249], v[26:27], v[142:143] op_sel_hi:[1,0,1]
	v_pk_fma_f32 v[140:141], v[242:243], v[26:27], v[140:141] op_sel:[0,1,0]
	v_pk_fma_f32 v[142:143], v[250:251], v[26:27], v[142:143] op_sel:[0,1,0]
	v_add_f32_dpp v28, v252, v252 quad_perm:[1,0,3,2] row_mask:0xf bank_mask:0xf
	v_add_f32_dpp v29, v253, v253 quad_perm:[1,0,3,2] row_mask:0xf bank_mask:0xf
	v_add_f32_dpp v30, v254, v254 quad_perm:[1,0,3,2] row_mask:0xf bank_mask:0xf
	v_add_f32_dpp v31, v255, v255 quad_perm:[1,0,3,2] row_mask:0xf bank_mask:0xf
	v_cndmask_b32_e32 v28, v30, v28, vcc
	v_cndmask_b32_e32 v29, v31, v29, vcc
	v_add_f32_dpp v34, v32, v32 quad_perm:[2,3,0,1] row_mask:0xf bank_mask:0xf
	v_add_f32_dpp v35, v33, v33 quad_perm:[2,3,0,1] row_mask:0xf bank_mask:0xf
	v_cndmask_b32_e64 v32, v35, v34, s[4:5]
	v_cndmask_b32_e64 v37, v32, v36, s[6:7]
	v_cndmask_b32_e64 v38, v36, v32, s[6:7]
	s_waitcnt vmcnt(5)
; DI void attn_sample_item(const Params& p, int item, ldsp lds, int tid_) {
;     ...
;   SC_SCORE(kvA, 0)
;   SC_SCORE(kvB, 1)
	v_pk_mul_f32 v[252:253], v[236:237], v[20:21] op_sel_hi:[1,0]
	v_pk_mul_f32 v[254:255], v[244:245], v[20:21] op_sel_hi:[1,0]
	v_pk_fma_f32 v[252:253], v[238:239], v[20:21], v[252:253] op_sel:[0,1,0]
	v_pk_fma_f32 v[254:255], v[246:247], v[20:21], v[254:255] op_sel:[0,1,0]
	v_pk_fma_f32 v[252:253], v[240:241], v[22:23], v[252:253] op_sel_hi:[1,0,1]
	v_pk_fma_f32 v[254:255], v[248:249], v[22:23], v[254:255] op_sel_hi:[1,0,1]
	v_pk_fma_f32 v[252:253], v[242:243], v[22:23], v[252:253] op_sel:[0,1,0]
	v_pk_fma_f32 v[254:255], v[250:251], v[22:23], v[254:255] op_sel:[0,1,0]
	v_add_f32_dpp v36, v38, v37 row_ror:4 row_mask:0xf bank_mask:0xf
	v_cndmask_b32_e64 v45, v36, v44, s[64:65]
	v_cndmask_b32_e64 v46, v44, v36, s[64:65]
	v_add_f32_dpp v24, v140, v140 quad_perm:[1,0,3,2] row_mask:0xf bank_mask:0xf
	v_add_f32_dpp v25, v141, v141 quad_perm:[1,0,3,2] row_mask:0xf bank_mask:0xf
	v_add_f32_dpp v26, v142, v142 quad_perm:[1,0,3,2] row_mask:0xf bank_mask:0xf
	v_add_f32_dpp v27, v143, v143 quad_perm:[1,0,3,2] row_mask:0xf bank_mask:0xf
	v_cndmask_b32_e32 v24, v26, v24, vcc
	v_cndmask_b32_e32 v25, v27, v25, vcc
	v_add_f32_dpp v30, v28, v28 quad_perm:[2,3,0,1] row_mask:0xf bank_mask:0xf
	v_add_f32_dpp v31, v29, v29 quad_perm:[2,3,0,1] row_mask:0xf bank_mask:0xf
	v_cndmask_b32_e64 v28, v31, v30, s[4:5]
	s_waitcnt vmcnt(4)
	v_pk_mul_f32 v[140:141], v[236:237], v[16:17] op_sel_hi:[1,0]
	v_pk_mul_f32 v[142:143], v[244:245], v[16:17] op_sel_hi:[1,0]
	v_pk_fma_f32 v[140:141], v[238:239], v[16:17], v[140:141] op_sel:[0,1,0]
	v_pk_fma_f32 v[142:143], v[246:247], v[16:17], v[142:143] op_sel:[0,1,0]
	v_pk_fma_f32 v[140:141], v[240:241], v[18:19], v[140:141] op_sel_hi:[1,0,1]
	v_pk_fma_f32 v[142:143], v[248:249], v[18:19], v[142:143] op_sel_hi:[1,0,1]
	v_pk_fma_f32 v[140:141], v[242:243], v[18:19], v[140:141] op_sel:[0,1,0]
	v_pk_fma_f32 v[142:143], v[250:251], v[18:19], v[142:143] op_sel:[0,1,0]
	v_add_f32_dpp v44, v46, v45 row_ror:8 row_mask:0xf bank_mask:0xf
	v_add_f32_dpp v20, v252, v252 quad_perm:[1,0,3,2] row_mask:0xf bank_mask:0xf
	v_add_f32_dpp v21, v253, v253 quad_perm:[1,0,3,2] row_mask:0xf bank_mask:0xf
	v_add_f32_dpp v22, v254, v254 quad_perm:[1,0,3,2] row_mask:0xf bank_mask:0xf
	v_add_f32_dpp v23, v255, v255 quad_perm:[1,0,3,2] row_mask:0xf bank_mask:0xf
	v_cndmask_b32_e32 v20, v22, v20, vcc
	v_cndmask_b32_e32 v21, v23, v21, vcc
	v_add_f32_dpp v26, v24, v24 quad_perm:[2,3,0,1] row_mask:0xf bank_mask:0xf
	v_add_f32_dpp v27, v25, v25 quad_perm:[2,3,0,1] row_mask:0xf bank_mask:0xf
	v_cndmask_b32_e64 v24, v27, v26, s[4:5]
	v_cndmask_b32_e64 v29, v24, v28, s[6:7]
	v_cndmask_b32_e64 v30, v28, v24, s[6:7]
	s_waitcnt vmcnt(3)
	v_pk_mul_f32 v[252:253], v[236:237], v[12:13] op_sel_hi:[1,0]
	v_pk_mul_f32 v[254:255], v[244:245], v[12:13] op_sel_hi:[1,0]
	v_pk_fma_f32 v[252:253], v[238:239], v[12:13], v[252:253] op_sel:[0,1,0]
	v_pk_fma_f32 v[254:255], v[246:247], v[12:13], v[254:255] op_sel:[0,1,0]
	v_pk_fma_f32 v[252:253], v[240:241], v[14:15], v[252:253] op_sel_hi:[1,0,1]
	v_pk_fma_f32 v[254:255], v[248:249], v[14:15], v[254:255] op_sel_hi:[1,0,1]
	v_pk_fma_f32 v[252:253], v[242:243], v[14:15], v[252:253] op_sel:[0,1,0]
	v_pk_fma_f32 v[254:255], v[250:251], v[14:15], v[254:255] op_sel:[0,1,0]
	v_permlane16_swap_b32_e32 v60, v44
	v_add_f32_e32 v60, v60, v44
	v_add_f32_dpp v28, v30, v29 row_ror:4 row_mask:0xf bank_mask:0xf
	v_add_f32_dpp v16, v140, v140 quad_perm:[1,0,3,2] row_mask:0xf bank_mask:0xf
	v_add_f32_dpp v17, v141, v141 quad_perm:[1,0,3,2] row_mask:0xf bank_mask:0xf
	v_add_f32_dpp v18, v142, v142 quad_perm:[1,0,3,2] row_mask:0xf bank_mask:0xf
	v_add_f32_dpp v19, v143, v143 quad_perm:[1,0,3,2] row_mask:0xf bank_mask:0xf
	v_cndmask_b32_e32 v16, v18, v16, vcc
	v_cndmask_b32_e32 v17, v19, v17, vcc
	v_add_f32_dpp v22, v20, v20 quad_perm:[2,3,0,1] row_mask:0xf bank_mask:0xf
	v_add_f32_dpp v23, v21, v21 quad_perm:[2,3,0,1] row_mask:0xf bank_mask:0xf
	v_cndmask_b32_e64 v20, v23, v22, s[4:5]
	s_waitcnt vmcnt(2)
	v_pk_mul_f32 v[140:141], v[236:237], v[8:9] op_sel_hi:[1,0]
	v_pk_mul_f32 v[142:143], v[244:245], v[8:9] op_sel_hi:[1,0]
	v_pk_fma_f32 v[140:141], v[238:239], v[8:9], v[140:141] op_sel:[0,1,0]
	v_pk_fma_f32 v[142:143], v[246:247], v[8:9], v[142:143] op_sel:[0,1,0]
	v_pk_fma_f32 v[140:141], v[240:241], v[10:11], v[140:141] op_sel_hi:[1,0,1]
	v_pk_fma_f32 v[142:143], v[248:249], v[10:11], v[142:143] op_sel_hi:[1,0,1]
	v_pk_fma_f32 v[140:141], v[242:243], v[10:11], v[140:141] op_sel:[0,1,0]
	v_pk_fma_f32 v[142:143], v[250:251], v[10:11], v[142:143] op_sel:[0,1,0]
	v_add_f32_dpp v12, v252, v252 quad_perm:[1,0,3,2] row_mask:0xf bank_mask:0xf
	v_add_f32_dpp v13, v253, v253 quad_perm:[1,0,3,2] row_mask:0xf bank_mask:0xf
	v_add_f32_dpp v14, v254, v254 quad_perm:[1,0,3,2] row_mask:0xf bank_mask:0xf
	v_add_f32_dpp v15, v255, v255 quad_perm:[1,0,3,2] row_mask:0xf bank_mask:0xf
	v_cndmask_b32_e32 v12, v14, v12, vcc
	v_cndmask_b32_e32 v13, v15, v13, vcc
	v_add_f32_dpp v18, v16, v16 quad_perm:[2,3,0,1] row_mask:0xf bank_mask:0xf
	v_add_f32_dpp v19, v17, v17 quad_perm:[2,3,0,1] row_mask:0xf bank_mask:0xf
	v_cndmask_b32_e64 v16, v19, v18, s[4:5]
	v_cndmask_b32_e64 v21, v16, v20, s[6:7]
	v_cndmask_b32_e64 v22, v20, v16, s[6:7]
	s_waitcnt vmcnt(1)
; DI void lbar() { asm volatile("s_waitcnt lgkmcnt(0)" ::: "memory"); __builtin_amdgcn_s_barrier(); asm volatile("" ::: "memory"); }
; DI float wave_sum(float v) { for (int o = 32; o >= 1; o >>= 1) v += __shfl_xor(v, o); return v; }
; DI void attn_sample_item(const Params& p, int item, ldsp lds, int tid_) {
;     ...
;   SC_SCORE(kvA, 0)
;   SC_SCORE(kvB, 1)
;     ...
;   f32x4 vvA[16], vvB[16];
; #pragma unroll
;   for (int j = 0; j < 16; ++j) vvA[j] = __builtin_nontemporal_load((const f32x4*)(cv + (size_t)(wid * 32 + j) * 1024 + lane * 4));
;   lbar();
;   if (wid < 4) {
;     float v[4]; float mx = -1e30f;
; #pragma unroll
;     for (int j = 0; j < 4; ++j) { v[j] = SC[wid * 256 + j * 64 + lane]; mx = fmaxf(mx, v[j]); }
;     for (int o = 32; o >= 1; o >>= 1) mx = fmaxf(mx, __shfl_xor(mx, o));
;     float s = 0.f;
; #pragma unroll
;     for (int j = 0; j < 4; ++j) { v[j] = __expf(v[j] - mx); s += v[j]; }
;     s = wave_sum(s); const float inv = 1.f / s;
; #pragma unroll
;     for (int j = 0; j < 4; ++j) SC[wid * 256 + j * 64 + lane] = v[j] * inv;
;   }
	v_pk_mul_f32 v[252:253], v[236:237], v[4:5] op_sel_hi:[1,0]
	v_pk_mul_f32 v[254:255], v[244:245], v[4:5] op_sel_hi:[1,0]
	v_pk_fma_f32 v[252:253], v[238:239], v[4:5], v[252:253] op_sel:[0,1,0]
	v_pk_fma_f32 v[254:255], v[246:247], v[4:5], v[254:255] op_sel:[0,1,0]
	v_pk_fma_f32 v[252:253], v[240:241], v[6:7], v[252:253] op_sel_hi:[1,0,1]
	v_pk_fma_f32 v[254:255], v[248:249], v[6:7], v[254:255] op_sel_hi:[1,0,1]
	v_pk_fma_f32 v[252:253], v[242:243], v[6:7], v[252:253] op_sel:[0,1,0]
	v_pk_fma_f32 v[254:255], v[250:251], v[6:7], v[254:255] op_sel:[0,1,0]
	v_add_f32_dpp v20, v22, v21 row_ror:4 row_mask:0xf bank_mask:0xf
	v_cndmask_b32_e64 v29, v20, v28, s[64:65]
	v_cndmask_b32_e64 v30, v28, v20, s[64:65]
	v_add_f32_dpp v8, v140, v140 quad_perm:[1,0,3,2] row_mask:0xf bank_mask:0xf
	v_add_f32_dpp v9, v141, v141 quad_perm:[1,0,3,2] row_mask:0xf bank_mask:0xf
	v_add_f32_dpp v10, v142, v142 quad_perm:[1,0,3,2] row_mask:0xf bank_mask:0xf
	v_add_f32_dpp v11, v143, v143 quad_perm:[1,0,3,2] row_mask:0xf bank_mask:0xf
	v_cndmask_b32_e32 v8, v10, v8, vcc
	v_cndmask_b32_e32 v9, v11, v9, vcc
	v_add_f32_dpp v14, v12, v12 quad_perm:[2,3,0,1] row_mask:0xf bank_mask:0xf
	v_add_f32_dpp v15, v13, v13 quad_perm:[2,3,0,1] row_mask:0xf bank_mask:0xf
	v_cndmask_b32_e64 v12, v15, v14, s[4:5]
	s_waitcnt vmcnt(0)
	v_pk_mul_f32 v[140:141], v[236:237], v[0:1] op_sel_hi:[1,0]
	v_pk_mul_f32 v[142:143], v[244:245], v[0:1] op_sel_hi:[1,0]
	v_pk_fma_f32 v[140:141], v[238:239], v[0:1], v[140:141] op_sel:[0,1,0]
	v_pk_fma_f32 v[142:143], v[246:247], v[0:1], v[142:143] op_sel:[0,1,0]
	v_pk_fma_f32 v[140:141], v[240:241], v[2:3], v[140:141] op_sel_hi:[1,0,1]
	v_pk_fma_f32 v[142:143], v[248:249], v[2:3], v[142:143] op_sel_hi:[1,0,1]
	v_pk_fma_f32 v[140:141], v[242:243], v[2:3], v[140:141] op_sel:[0,1,0]
	v_pk_fma_f32 v[142:143], v[250:251], v[2:3], v[142:143] op_sel:[0,1,0]
	v_add_f32_dpp v28, v30, v29 row_ror:8 row_mask:0xf bank_mask:0xf
	v_add_f32_dpp v4, v252, v252 quad_perm:[1,0,3,2] row_mask:0xf bank_mask:0xf
	v_add_f32_dpp v5, v253, v253 quad_perm:[1,0,3,2] row_mask:0xf bank_mask:0xf
	v_add_f32_dpp v6, v254, v254 quad_perm:[1,0,3,2] row_mask:0xf bank_mask:0xf
	v_add_f32_dpp v7, v255, v255 quad_perm:[1,0,3,2] row_mask:0xf bank_mask:0xf
	v_cndmask_b32_e32 v4, v6, v4, vcc
	v_cndmask_b32_e32 v5, v7, v5, vcc
	v_add_f32_dpp v10, v8, v8 quad_perm:[2,3,0,1] row_mask:0xf bank_mask:0xf
	v_add_f32_dpp v11, v9, v9 quad_perm:[2,3,0,1] row_mask:0xf bank_mask:0xf
	v_cndmask_b32_e64 v8, v11, v10, s[4:5]
	v_cndmask_b32_e64 v13, v8, v12, s[6:7]
	v_cndmask_b32_e64 v14, v12, v8, s[6:7]
	s_nop 1
	v_add_f32_dpp v12, v14, v13 row_ror:4 row_mask:0xf bank_mask:0xf
	v_add_f32_dpp v0, v140, v140 quad_perm:[1,0,3,2] row_mask:0xf bank_mask:0xf
	v_add_f32_dpp v1, v141, v141 quad_perm:[1,0,3,2] row_mask:0xf bank_mask:0xf
	v_add_f32_dpp v2, v142, v142 quad_perm:[1,0,3,2] row_mask:0xf bank_mask:0xf
	v_add_f32_dpp v3, v143, v143 quad_perm:[1,0,3,2] row_mask:0xf bank_mask:0xf
	v_cndmask_b32_e32 v0, v2, v0, vcc
	v_cndmask_b32_e32 v1, v3, v1, vcc
	v_add_f32_dpp v6, v4, v4 quad_perm:[2,3,0,1] row_mask:0xf bank_mask:0xf
	v_add_f32_dpp v7, v5, v5 quad_perm:[2,3,0,1] row_mask:0xf bank_mask:0xf
	v_cndmask_b32_e64 v4, v7, v6, s[4:5]
	v_add_f32_dpp v2, v0, v0 quad_perm:[2,3,0,1] row_mask:0xf bank_mask:0xf
	v_add_f32_dpp v3, v1, v1 quad_perm:[2,3,0,1] row_mask:0xf bank_mask:0xf
	v_cndmask_b32_e64 v0, v3, v2, s[4:5]
	v_cndmask_b32_e64 v5, v0, v4, s[6:7]
	v_cndmask_b32_e64 v6, v4, v0, s[6:7]
	s_nop 1
	v_add_f32_dpp v4, v6, v5 row_ror:4 row_mask:0xf bank_mask:0xf
	v_cndmask_b32_e64 v13, v4, v12, s[64:65]
	v_cndmask_b32_e64 v14, v12, v4, s[64:65]
	s_nop 1
	v_add_f32_dpp v12, v14, v13 row_ror:8 row_mask:0xf bank_mask:0xf
	s_nop 1
	v_permlane16_swap_b32_e32 v28, v12
	v_add_f32_e32 v28, v28, v12
	s_nop 1
	v_permlane32_swap_b32_e32 v60, v28
	v_add_f32_e32 v60, v60, v28
	ds_write_b32 v235, v60 offset:64
	v_lshlrev_b32_e32 v2, 2, v223
	s_waitcnt lgkmcnt(0)
	s_barrier
	v_cmp_gt_i32_e32 vcc, 4, v210
	s_and_saveexec_b64 s[4:5], vcc
	s_cbranch_execz .LBB0_1603
	v_lshlrev_b32_e32 v3, 10, v210
	v_add3_u32 v6, 16, v3, v2
	ds_read2st64_b32 v[2:3], v6 offset1:1
	ds_read2st64_b32 v[4:5], v6 offset0:2 offset1:3
	s_waitcnt lgkmcnt(1)
	v_max3_f32 v7, v2, s39, v3
	s_waitcnt lgkmcnt(0)
	v_max3_f32 v7, v7, v4, v5
	ds_bpermute_b32 v8, v133, v7
	s_waitcnt lgkmcnt(0)
	v_max_f32_e32 v8, v8, v8
	v_max_f32_e32 v7, v7, v8
	ds_bpermute_b32 v8, v132, v7
	s_waitcnt lgkmcnt(0)
	v_max_f32_e32 v8, v8, v8
	v_max_f32_e32 v7, v7, v8
	ds_bpermute_b32 v8, v131, v7
	s_waitcnt lgkmcnt(0)
	v_max_f32_e32 v8, v8, v8
	v_max_f32_e32 v7, v7, v8
	ds_bpermute_b32 v8, v130, v7
	s_waitcnt lgkmcnt(0)
	v_max_f32_e32 v8, v8, v8
	v_max_f32_e32 v7, v7, v8
	ds_bpermute_b32 v8, v129, v7
	s_waitcnt lgkmcnt(0)
	v_max_f32_e32 v8, v8, v8
	v_max_f32_e32 v7, v7, v8
	ds_bpermute_b32 v8, v128, v7
	s_waitcnt lgkmcnt(0)
	v_max_f32_e32 v8, v8, v8
	v_max_f32_e32 v7, v7, v8
	v_sub_f32_e32 v2, v2, v7
	v_sub_f32_e32 v3, v3, v7
	v_mul_f32_e32 v2, 0x3fb8aa3b, v2
	v_sub_f32_e32 v4, v4, v7
	v_mul_f32_e32 v3, 0x3fb8aa3b, v3
	v_exp_f32_e32 v2, v2
	v_sub_f32_e32 v5, v5, v7
	v_mul_f32_e32 v4, 0x3fb8aa3b, v4
	v_exp_f32_e32 v3, v3
	v_mul_f32_e32 v5, 0x3fb8aa3b, v5
	v_exp_f32_e32 v4, v4
	v_exp_f32_e32 v5, v5
	v_add_f32_e32 v7, 0, v2
	v_add_f32_e32 v7, v3, v7
	v_add_f32_e32 v7, v4, v7
	v_add_f32_e32 v7, v5, v7
	ds_bpermute_b32 v8, v133, v7
	s_waitcnt lgkmcnt(0)
	v_add_f32_e32 v7, v7, v8
	ds_bpermute_b32 v8, v132, v7
	s_waitcnt lgkmcnt(0)
	v_add_f32_e32 v7, v7, v8
	ds_bpermute_b32 v8, v131, v7
	s_waitcnt lgkmcnt(0)
	v_add_f32_e32 v7, v7, v8
	ds_bpermute_b32 v8, v130, v7
	s_waitcnt lgkmcnt(0)
	v_add_f32_e32 v7, v7, v8
	ds_bpermute_b32 v8, v129, v7
	s_waitcnt lgkmcnt(0)
	v_add_f32_e32 v7, v7, v8
	ds_bpermute_b32 v8, v128, v7
	s_waitcnt lgkmcnt(0)
	v_add_f32_e32 v7, v7, v8
	v_div_scale_f32 v8, s[6:7], v7, v7, 1.0
	v_rcp_f32_e32 v9, v8
	v_div_scale_f32 v10, vcc, 1.0, v7, 1.0
	v_fma_f32 v11, -v8, v9, 1.0
	v_fmac_f32_e32 v9, v11, v9
	v_mul_f32_e32 v11, v10, v9
	v_fma_f32 v12, -v8, v11, v10
	v_fmac_f32_e32 v11, v12, v9
	v_fma_f32 v8, -v8, v11, v10
	v_div_fmas_f32 v8, v8, v9, v11
	v_div_fixup_f32 v7, v8, v7, 1.0
	v_mul_f32_e32 v2, v2, v7
	v_mul_f32_e32 v3, v3, v7
	v_mul_f32_e32 v4, v4, v7
	v_mul_f32_e32 v5, v5, v7
	ds_write2st64_b32 v6, v2, v3 offset1:1
	ds_write2st64_b32 v6, v4, v5 offset0:2 offset1:3
	s_branch .LBB0_1603

; #define LAS __attribute__((address_space(3)))
; DI void lbar() { asm volatile("s_waitcnt lgkmcnt(0)" ::: "memory"); __builtin_amdgcn_s_barrier(); asm volatile("" ::: "memory"); }
; DI float wave_sum(float v) { for (int o = 32; o >= 1; o >>= 1) v += __shfl_xor(v, o); return v; }
; DI void attn_sample_item(const Params& p, int item, ldsp lds, int tid_) {
;     ...
;   for (int j = 0; j < 16; ++j) vvA[j] = __builtin_nontemporal_load((const f32x4*)(cv + (size_t)(wid * 32 + j) * 1024 + lane * 4));
;   lbar();
;   if (wid < 4) {
;     float v[4]; float mx = -1e30f;
; #pragma unroll
;     for (int j = 0; j < 4; ++j) { v[j] = SC[wid * 256 + j * 64 + lane]; mx = fmaxf(mx, v[j]); }
;     for (int o = 32; o >= 1; o >>= 1) mx = fmaxf(mx, __shfl_xor(mx, o));
;     float s = 0.f;
; #pragma unroll
;     for (int j = 0; j < 4; ++j) { v[j] = __expf(v[j] - mx); s += v[j]; }
;     s = wave_sum(s); const float inv = 1.f / s;
; #pragma unroll
;     for (int j = 0; j < 4; ++j) SC[wid * 256 + j * 64 + lane] = v[j] * inv;
;   }
; #pragma unroll
;   for (int j = 0; j < 16; ++j) vvB[j] = __builtin_nontemporal_load((const f32x4*)(cv + (size_t)(wid * 32 + 16 + j) * 1024 + lane * 4));
;   lbar();
;   {
;     f32x4 acc[4];
; #pragma unroll
;     for (int t = 0; t < 4; ++t) acc[t] = (f32x4){0.f, 0.f, 0.f, 0.f};
; #pragma unroll
;     for (int t = 0; t < 4; ++t)
; #pragma unroll
;       for (int j4 = 0; j4 < 4; ++j4) { const f32x4 pp = *(const LAS f32x4*)(SC + t * 256 + wid * 32 + j4 * 4);
; #pragma unroll
;         for (int e = 0; e < 4; ++e) acc[t] += pp[e] * vvA[j4 * 4 + e]; }
.LBB0_1675:
	s_or_b64 exec, exec, s[4:5]
	s_add_u32 s4, s14, s28
	s_addc_u32 s5, s15, s29
	v_lshlrev_b32_e32 v0, 4, v223
	v_mov_b32_e32 v1, v145
	v_lshl_add_u64 v[0:1], s[4:5], 0, v[0:1]
	v_lshl_add_u64 v[4:5], v[0:1], 0, v[158:159]
	v_lshl_add_u64 v[6:7], v[0:1], 0, v[162:163]
	global_load_dwordx4 v[100:103], v[4:5], off nt
	global_load_dwordx4 v[92:95], v[6:7], off nt
	v_lshl_add_u64 v[4:5], v[0:1], 0, v[164:165]
	v_lshl_add_u64 v[6:7], v[0:1], 0, v[168:169]
	global_load_dwordx4 v[112:115], v[4:5], off nt
	global_load_dwordx4 v[108:111], v[6:7], off nt
	v_lshl_add_u64 v[4:5], v[0:1], 0, v[172:173]
	v_lshl_add_u64 v[6:7], v[0:1], 0, v[176:177]
	global_load_dwordx4 v[120:123], v[4:5], off nt
	global_load_dwordx4 v[116:119], v[6:7], off nt
	v_lshl_add_u64 v[4:5], v[0:1], 0, v[180:181]
	v_lshl_add_u64 v[6:7], v[0:1], 0, v[184:185]
	global_load_dwordx4 v[124:127], v[4:5], off nt
	global_load_dwordx4 v[104:107], v[6:7], off nt
	v_lshl_add_u64 v[4:5], v[0:1], 0, v[188:189]
	v_lshl_add_u64 v[6:7], v[0:1], 0, v[192:193]
	global_load_dwordx4 v[68:71], v[4:5], off nt
	global_load_dwordx4 v[64:67], v[6:7], off nt
	v_lshl_add_u64 v[4:5], v[0:1], 0, v[196:197]
	v_lshl_add_u64 v[6:7], v[0:1], 0, v[200:201]
	global_load_dwordx4 v[80:83], v[4:5], off nt
	global_load_dwordx4 v[76:79], v[6:7], off nt
	v_lshl_add_u64 v[4:5], v[0:1], 0, v[202:203]
	v_lshl_add_u64 v[6:7], v[0:1], 0, v[204:205]
	global_load_dwordx4 v[88:91], v[4:5], off nt
	global_load_dwordx4 v[84:87], v[6:7], off nt
	v_lshl_add_u64 v[4:5], v[0:1], 0, v[206:207]
	v_lshl_add_u64 v[6:7], v[0:1], 0, v[208:209]
	global_load_dwordx4 v[96:99], v[4:5], off nt
	global_load_dwordx4 v[72:75], v[6:7], off nt
	v_lshl_add_u64 v[2:3], v[0:1], 0, v[146:147]
	v_lshl_add_u64 v[4:5], v[0:1], 0, v[148:149]
	global_load_dwordx4 v[40:43], v[2:3], off nt
	global_load_dwordx4 v[36:39], v[4:5], off nt
	v_lshl_add_u64 v[2:3], v[0:1], 0, v[150:151]
	v_lshl_add_u64 v[4:5], v[0:1], 0, v[152:153]
	global_load_dwordx4 v[48:51], v[2:3], off nt
	global_load_dwordx4 v[44:47], v[4:5], off nt
	v_lshl_add_u64 v[2:3], v[0:1], 0, v[154:155]
	v_lshl_add_u64 v[4:5], v[0:1], 0, v[156:157]
	global_load_dwordx4 v[56:59], v[2:3], off nt
	global_load_dwordx4 v[52:55], v[4:5], off nt
	v_lshl_add_u64 v[2:3], v[0:1], 0, v[160:161]
	v_lshl_add_u64 v[4:5], v[0:1], 0, v[166:167]
	global_load_dwordx4 v[60:63], v[2:3], off nt
	global_load_dwordx4 v[32:35], v[4:5], off nt
	v_lshl_add_u64 v[2:3], v[0:1], 0, v[170:171]
	v_lshl_add_u64 v[4:5], v[0:1], 0, v[174:175]
	global_load_dwordx4 v[12:15], v[2:3], off nt
	s_nop 0
	global_load_dwordx4 v[4:7], v[4:5], off nt
	v_lshl_add_u64 v[2:3], v[0:1], 0, v[178:179]
	v_lshl_add_u64 v[8:9], v[0:1], 0, v[182:183]
	global_load_dwordx4 v[20:23], v[2:3], off nt
	s_nop 0
	global_load_dwordx4 v[8:11], v[8:9], off nt
	v_lshl_add_u64 v[2:3], v[0:1], 0, v[186:187]
	v_lshl_add_u64 v[16:17], v[0:1], 0, v[190:191]
	global_load_dwordx4 v[24:27], v[2:3], off nt
	s_nop 0
	global_load_dwordx4 v[16:19], v[16:17], off nt
	v_lshl_add_u64 v[2:3], v[0:1], 0, v[194:195]
	v_lshl_add_u64 v[0:1], v[0:1], 0, v[198:199]
	global_load_dwordx4 v[28:31], v[2:3], off nt
	s_nop 0
	global_load_dwordx4 v[0:3], v[0:1], off nt
	s_waitcnt lgkmcnt(0)
	s_barrier
	ds_read_b128 v[128:131], v136
	ds_read_b128 v[132:135], v136 offset:16
	ds_read_b128 v[138:141], v136 offset:32
	ds_read_b128 v[146:149], v136 offset:48
	s_add_i32 s4, s26, 0x4000
	s_waitcnt vmcnt(31) lgkmcnt(3)
	v_pk_fma_f32 v[142:143], v[100:101], v[128:129], 0 op_sel_hi:[1,0,0]
	v_pk_fma_f32 v[150:151], v[102:103], v[128:129], 0 op_sel_hi:[1,0,0]
	s_lshl_b32 s24, s24, 1
	s_waitcnt vmcnt(30)
	v_pk_fma_f32 v[150:151], v[94:95], v[128:129], v[150:151] op_sel:[0,1,0]
	v_pk_fma_f32 v[128:129], v[92:93], v[128:129], v[142:143] op_sel:[0,1,0]
	s_waitcnt vmcnt(29)
	v_pk_fma_f32 v[142:143], v[114:115], v[130:131], v[150:151] op_sel_hi:[1,0,1]
	v_pk_fma_f32 v[128:129], v[112:113], v[130:131], v[128:129] op_sel_hi:[1,0,1]
	v_mov_b32_e32 v130, v131
	s_waitcnt vmcnt(28)
	v_pk_fma_f32 v[128:129], v[108:109], v[130:131], v[128:129] op_sel_hi:[1,0,1]
	v_pk_fma_f32 v[130:131], v[110:111], v[130:131], v[142:143] op_sel_hi:[1,0,1]
	s_waitcnt vmcnt(27) lgkmcnt(2)
	v_pk_fma_f32 v[128:129], v[120:121], v[132:133], v[128:129] op_sel_hi:[1,0,1]
	v_pk_fma_f32 v[130:131], v[122:123], v[132:133], v[130:131] op_sel_hi:[1,0,1]
	s_waitcnt vmcnt(26)
	v_pk_fma_f32 v[128:129], v[116:117], v[132:133], v[128:129] op_sel:[0,1,0]
	v_pk_fma_f32 v[130:131], v[118:119], v[132:133], v[130:131] op_sel:[0,1,0]
	s_waitcnt vmcnt(25)
	v_pk_fma_f32 v[128:129], v[124:125], v[134:135], v[128:129] op_sel_hi:[1,0,1]
	v_pk_fma_f32 v[130:131], v[126:127], v[134:135], v[130:131] op_sel_hi:[1,0,1]
	v_mov_b32_e32 v132, v135
	s_waitcnt vmcnt(24)
	v_pk_fma_f32 v[128:129], v[104:105], v[132:133], v[128:129] op_sel_hi:[1,0,1]
	v_pk_fma_f32 v[130:131], v[106:107], v[132:133], v[130:131] op_sel_hi:[1,0,1]
	s_waitcnt vmcnt(23) lgkmcnt(1)
	v_pk_fma_f32 v[128:129], v[68:69], v[138:139], v[128:129] op_sel_hi:[1,0,1]
	v_pk_fma_f32 v[130:131], v[70:71], v[138:139], v[130:131] op_sel_hi:[1,0,1]
	s_waitcnt vmcnt(22)
	v_pk_fma_f32 v[128:129], v[64:65], v[138:139], v[128:129] op_sel:[0,1,0]
	v_pk_fma_f32 v[130:131], v[66:67], v[138:139], v[130:131] op_sel:[0,1,0]
	s_waitcnt vmcnt(21)
	v_pk_fma_f32 v[128:129], v[80:81], v[140:141], v[128:129] op_sel_hi:[1,0,1]
	v_pk_fma_f32 v[130:131], v[82:83], v[140:141], v[130:131] op_sel_hi:[1,0,1]
	v_mov_b32_e32 v132, v141
	s_waitcnt vmcnt(20)
	v_pk_fma_f32 v[128:129], v[76:77], v[132:133], v[128:129] op_sel_hi:[1,0,1]
	v_pk_fma_f32 v[130:131], v[78:79], v[132:133], v[130:131] op_sel_hi:[1,0,1]
	s_waitcnt vmcnt(19) lgkmcnt(0)
; #define LAS __attribute__((address_space(3)))
; DI void attn_sample_item(const Params& p, int item, ldsp lds, int tid_) {
;     ...
; #pragma unroll
;     for (int t = 0; t < 4; ++t)
; #pragma unroll
;       for (int j4 = 0; j4 < 4; ++j4) { const f32x4 pp = *(const LAS f32x4*)(SC + t * 256 + wid * 32 + j4 * 4);
; #pragma unroll
;         for (int e = 0; e < 4; ++e) acc[t] += pp[e] * vvA[j4 * 4 + e]; }
; #pragma unroll
;     for (int t = 0; t < 4; ++t)
; #pragma unroll
;       for (int j4 = 0; j4 < 4; ++j4) { const f32x4 pp = *(const LAS f32x4*)(SC + t * 256 + wid * 32 + 16 + j4 * 4);
; #pragma unroll
;         for (int e = 0; e < 4; ++e) acc[t] += pp[e] * vvB[j4 * 4 + e]; }
	v_pk_fma_f32 v[128:129], v[88:89], v[146:147], v[128:129] op_sel_hi:[1,0,1]
	v_pk_fma_f32 v[130:131], v[90:91], v[146:147], v[130:131] op_sel_hi:[1,0,1]
	s_waitcnt vmcnt(18)
	v_pk_fma_f32 v[128:129], v[84:85], v[146:147], v[128:129] op_sel:[0,1,0]
	v_pk_fma_f32 v[130:131], v[86:87], v[146:147], v[130:131] op_sel:[0,1,0]
	s_waitcnt vmcnt(17)
	v_pk_fma_f32 v[134:135], v[96:97], v[148:149], v[128:129] op_sel_hi:[1,0,1]
	v_pk_fma_f32 v[132:133], v[98:99], v[148:149], v[130:131] op_sel_hi:[1,0,1]
	ds_read_b128 v[128:131], v136 offset:1024
	v_mov_b32_e32 v138, v149
	s_waitcnt vmcnt(16)
	v_pk_fma_f32 v[142:143], v[72:73], v[138:139], v[134:135] op_sel_hi:[1,0,1]
	v_pk_fma_f32 v[150:151], v[74:75], v[138:139], v[132:133] op_sel_hi:[1,0,1]
	ds_read_b128 v[132:135], v136 offset:1040
	s_waitcnt lgkmcnt(1)
	v_pk_fma_f32 v[138:139], v[100:101], v[128:129], 0 op_sel_hi:[1,0,0]
	v_pk_fma_f32 v[140:141], v[102:103], v[128:129], 0 op_sel_hi:[1,0,0]
	ds_read_b128 v[146:149], v136 offset:2064
	v_pk_fma_f32 v[140:141], v[94:95], v[128:129], v[140:141] op_sel:[0,1,0]
	v_pk_fma_f32 v[128:129], v[92:93], v[128:129], v[138:139] op_sel:[0,1,0]
	v_pk_fma_f32 v[138:139], v[114:115], v[130:131], v[140:141] op_sel_hi:[1,0,1]
	v_pk_fma_f32 v[128:129], v[112:113], v[130:131], v[128:129] op_sel_hi:[1,0,1]
	v_mov_b32_e32 v130, v131
	v_pk_fma_f32 v[128:129], v[108:109], v[130:131], v[128:129] op_sel_hi:[1,0,1]
	v_pk_fma_f32 v[130:131], v[110:111], v[130:131], v[138:139] op_sel_hi:[1,0,1]
	s_waitcnt lgkmcnt(1)
	v_pk_fma_f32 v[128:129], v[120:121], v[132:133], v[128:129] op_sel_hi:[1,0,1]
	v_pk_fma_f32 v[130:131], v[122:123], v[132:133], v[130:131] op_sel_hi:[1,0,1]
	v_pk_fma_f32 v[128:129], v[116:117], v[132:133], v[128:129] op_sel:[0,1,0]
	v_pk_fma_f32 v[130:131], v[118:119], v[132:133], v[130:131] op_sel:[0,1,0]
	v_pk_fma_f32 v[138:139], v[124:125], v[134:135], v[128:129] op_sel_hi:[1,0,1]
	v_pk_fma_f32 v[132:133], v[126:127], v[134:135], v[130:131] op_sel_hi:[1,0,1]
	ds_read_b128 v[128:131], v136 offset:1056
	v_mov_b32_e32 v134, v135
	v_pk_fma_f32 v[138:139], v[104:105], v[134:135], v[138:139] op_sel_hi:[1,0,1]
	v_pk_fma_f32 v[140:141], v[106:107], v[134:135], v[132:133] op_sel_hi:[1,0,1]
	ds_read_b128 v[132:135], v136 offset:1072
	s_waitcnt lgkmcnt(1)
	v_pk_fma_f32 v[140:141], v[70:71], v[128:129], v[140:141] op_sel_hi:[1,0,1]
	v_pk_fma_f32 v[138:139], v[68:69], v[128:129], v[138:139] op_sel_hi:[1,0,1]
	s_add_i32 s38, s38, s94
	v_pk_fma_f32 v[138:139], v[64:65], v[128:129], v[138:139] op_sel:[0,1,0]
	v_pk_fma_f32 v[128:129], v[66:67], v[128:129], v[140:141] op_sel:[0,1,0]
	v_pk_fma_f32 v[138:139], v[80:81], v[130:131], v[138:139] op_sel_hi:[1,0,1]
	v_pk_fma_f32 v[128:129], v[82:83], v[130:131], v[128:129] op_sel_hi:[1,0,1]
	v_mov_b32_e32 v130, v131
	v_pk_fma_f32 v[138:139], v[76:77], v[130:131], v[138:139] op_sel_hi:[1,0,1]
	v_pk_fma_f32 v[128:129], v[78:79], v[130:131], v[128:129] op_sel_hi:[1,0,1]
	s_waitcnt lgkmcnt(0)
	v_pk_fma_f32 v[130:131], v[88:89], v[132:133], v[138:139] op_sel_hi:[1,0,1]
	ds_read_b128 v[138:141], v136 offset:2048
	v_pk_fma_f32 v[128:129], v[90:91], v[132:133], v[128:129] op_sel_hi:[1,0,1]
	v_pk_fma_f32 v[130:131], v[84:85], v[132:133], v[130:131] op_sel:[0,1,0]
	v_pk_fma_f32 v[128:129], v[86:87], v[132:133], v[128:129] op_sel:[0,1,0]
	s_add_i32 s0, s0, s1
	v_pk_fma_f32 v[132:133], v[98:99], v[134:135], v[128:129] op_sel_hi:[1,0,1]
	v_pk_fma_f32 v[128:129], v[96:97], v[134:135], v[130:131] op_sel_hi:[1,0,1]
	v_mov_b32_e32 v130, v135
	v_pk_fma_f32 v[128:129], v[72:73], v[130:131], v[128:129] op_sel_hi:[1,0,1]
	v_pk_fma_f32 v[132:133], v[74:75], v[130:131], v[132:133] op_sel_hi:[1,0,1]
	s_waitcnt lgkmcnt(0)
	v_pk_fma_f32 v[130:131], v[100:101], v[138:139], 0 op_sel_hi:[1,0,0]
	v_pk_fma_f32 v[134:135], v[102:103], v[138:139], 0 op_sel_hi:[1,0,0]
	v_pk_fma_f32 v[130:131], v[92:93], v[138:139], v[130:131] op_sel:[0,1,0]
	v_pk_fma_f32 v[134:135], v[94:95], v[138:139], v[134:135] op_sel:[0,1,0]
	v_pk_fma_f32 v[130:131], v[112:113], v[140:141], v[130:131] op_sel_hi:[1,0,1]
	v_pk_fma_f32 v[134:135], v[114:115], v[140:141], v[134:135] op_sel_hi:[1,0,1]
	v_mov_b32_e32 v138, v141
	v_pk_fma_f32 v[130:131], v[108:109], v[138:139], v[130:131] op_sel_hi:[1,0,1]
	v_pk_fma_f32 v[134:135], v[110:111], v[138:139], v[134:135] op_sel_hi:[1,0,1]
	ds_read_b128 v[138:141], v136 offset:2080
	v_pk_fma_f32 v[134:135], v[122:123], v[146:147], v[134:135] op_sel_hi:[1,0,1]
	v_pk_fma_f32 v[130:131], v[120:121], v[146:147], v[130:131] op_sel_hi:[1,0,1]
	v_pk_fma_f32 v[134:135], v[118:119], v[146:147], v[134:135] op_sel:[0,1,0]
	v_pk_fma_f32 v[130:131], v[116:117], v[146:147], v[130:131] op_sel:[0,1,0]
	v_pk_fma_f32 v[134:135], v[126:127], v[148:149], v[134:135] op_sel_hi:[1,0,1]
	v_pk_fma_f32 v[130:131], v[124:125], v[148:149], v[130:131] op_sel_hi:[1,0,1]
	v_mov_b32_e32 v146, v149
	v_pk_fma_f32 v[130:131], v[104:105], v[146:147], v[130:131] op_sel_hi:[1,0,1]
	v_pk_fma_f32 v[134:135], v[106:107], v[146:147], v[134:135] op_sel_hi:[1,0,1]
	ds_read_b128 v[146:149], v136 offset:2096
	s_waitcnt lgkmcnt(1)
	v_pk_fma_f32 v[134:135], v[70:71], v[138:139], v[134:135] op_sel_hi:[1,0,1]
	v_pk_fma_f32 v[130:131], v[68:69], v[138:139], v[130:131] op_sel_hi:[1,0,1]
	v_pk_fma_f32 v[134:135], v[66:67], v[138:139], v[134:135] op_sel:[0,1,0]
	v_pk_fma_f32 v[130:131], v[64:65], v[138:139], v[130:131] op_sel:[0,1,0]
	v_pk_fma_f32 v[134:135], v[82:83], v[140:141], v[134:135] op_sel_hi:[1,0,1]
	v_pk_fma_f32 v[130:131], v[80:81], v[140:141], v[130:131] op_sel_hi:[1,0,1]
	v_mov_b32_e32 v138, v141
	v_pk_fma_f32 v[130:131], v[76:77], v[138:139], v[130:131] op_sel_hi:[1,0,1]
	v_pk_fma_f32 v[134:135], v[78:79], v[138:139], v[134:135] op_sel_hi:[1,0,1]
	ds_read_b128 v[138:141], v136 offset:3072
	s_waitcnt lgkmcnt(1)
; #define LAS __attribute__((address_space(3)))
; DI void attn_sample_item(const Params& p, int item, ldsp lds, int tid_) {
;     ...
; #pragma unroll
;     for (int t = 0; t < 4; ++t)
; #pragma unroll
;       for (int j4 = 0; j4 < 4; ++j4) { const f32x4 pp = *(const LAS f32x4*)(SC + t * 256 + wid * 32 + j4 * 4);
; #pragma unroll
;         for (int e = 0; e < 4; ++e) acc[t] += pp[e] * vvA[j4 * 4 + e]; }
; #pragma unroll
;     for (int t = 0; t < 4; ++t)
; #pragma unroll
;       for (int j4 = 0; j4 < 4; ++j4) { const f32x4 pp = *(const LAS f32x4*)(SC + t * 256 + wid * 32 + 16 + j4 * 4);
; #pragma unroll
;         for (int e = 0; e < 4; ++e) acc[t] += pp[e] * vvB[j4 * 4 + e]; }
	v_pk_fma_f32 v[134:135], v[90:91], v[146:147], v[134:135] op_sel_hi:[1,0,1]
	v_pk_fma_f32 v[130:131], v[88:89], v[146:147], v[130:131] op_sel_hi:[1,0,1]
	v_pk_fma_f32 v[134:135], v[86:87], v[146:147], v[134:135] op_sel:[0,1,0]
	v_pk_fma_f32 v[130:131], v[84:85], v[146:147], v[130:131] op_sel:[0,1,0]
	v_pk_fma_f32 v[134:135], v[98:99], v[148:149], v[134:135] op_sel_hi:[1,0,1]
	v_pk_fma_f32 v[130:131], v[96:97], v[148:149], v[130:131] op_sel_hi:[1,0,1]
	v_mov_b32_e32 v146, v149
	v_pk_fma_f32 v[130:131], v[72:73], v[146:147], v[130:131] op_sel_hi:[1,0,1]
	v_pk_fma_f32 v[134:135], v[74:75], v[146:147], v[134:135] op_sel_hi:[1,0,1]
	ds_read_b128 v[146:149], v136 offset:3088
	s_waitcnt lgkmcnt(1)
	v_pk_fma_f32 v[100:101], v[100:101], v[138:139], 0 op_sel_hi:[1,0,0]
	v_pk_fma_f32 v[102:103], v[102:103], v[138:139], 0 op_sel_hi:[1,0,0]
	v_pk_fma_f32 v[92:93], v[92:93], v[138:139], v[100:101] op_sel:[0,1,0]
	v_pk_fma_f32 v[94:95], v[94:95], v[138:139], v[102:103] op_sel:[0,1,0]
	v_pk_fma_f32 v[92:93], v[112:113], v[140:141], v[92:93] op_sel_hi:[1,0,1]
	v_pk_fma_f32 v[94:95], v[114:115], v[140:141], v[94:95] op_sel_hi:[1,0,1]
	v_mov_b32_e32 v100, v141
	v_pk_fma_f32 v[92:93], v[108:109], v[100:101], v[92:93] op_sel_hi:[1,0,1]
	v_pk_fma_f32 v[94:95], v[110:111], v[100:101], v[94:95] op_sel_hi:[1,0,1]
	s_waitcnt lgkmcnt(0)
	v_pk_fma_f32 v[92:93], v[120:121], v[146:147], v[92:93] op_sel_hi:[1,0,1]
	v_pk_fma_f32 v[94:95], v[122:123], v[146:147], v[94:95] op_sel_hi:[1,0,1]
	v_pk_fma_f32 v[92:93], v[116:117], v[146:147], v[92:93] op_sel:[0,1,0]
	v_pk_fma_f32 v[94:95], v[118:119], v[146:147], v[94:95] op_sel:[0,1,0]
	v_pk_fma_f32 v[102:103], v[124:125], v[148:149], v[92:93] op_sel_hi:[1,0,1]
	v_pk_fma_f32 v[100:101], v[126:127], v[148:149], v[94:95] op_sel_hi:[1,0,1]
	ds_read_b128 v[92:95], v136 offset:3104
	v_mov_b32_e32 v108, v149
	v_pk_fma_f32 v[104:105], v[104:105], v[108:109], v[102:103] op_sel_hi:[1,0,1]
	v_pk_fma_f32 v[106:107], v[106:107], v[108:109], v[100:101] op_sel_hi:[1,0,1]
	ds_read_b128 v[100:103], v136 offset:3120
	s_waitcnt lgkmcnt(1)
	v_pk_fma_f32 v[70:71], v[70:71], v[92:93], v[106:107] op_sel_hi:[1,0,1]
	v_pk_fma_f32 v[68:69], v[68:69], v[92:93], v[104:105] op_sel_hi:[1,0,1]
	v_pk_fma_f32 v[66:67], v[66:67], v[92:93], v[70:71] op_sel:[0,1,0]
	v_pk_fma_f32 v[64:65], v[64:65], v[92:93], v[68:69] op_sel:[0,1,0]
	v_pk_fma_f32 v[66:67], v[82:83], v[94:95], v[66:67] op_sel_hi:[1,0,1]
	v_pk_fma_f32 v[64:65], v[80:81], v[94:95], v[64:65] op_sel_hi:[1,0,1]
	v_mov_b32_e32 v68, v95
	v_pk_fma_f32 v[64:65], v[76:77], v[68:69], v[64:65] op_sel_hi:[1,0,1]
	v_pk_fma_f32 v[66:67], v[78:79], v[68:69], v[66:67] op_sel_hi:[1,0,1]
	ds_read_b128 v[68:71], v136 offset:64
	s_waitcnt lgkmcnt(1)
	v_pk_fma_f32 v[66:67], v[90:91], v[100:101], v[66:67] op_sel_hi:[1,0,1]
	v_pk_fma_f32 v[64:65], v[88:89], v[100:101], v[64:65] op_sel_hi:[1,0,1]
	v_pk_fma_f32 v[66:67], v[86:87], v[100:101], v[66:67] op_sel:[0,1,0]
	v_pk_fma_f32 v[64:65], v[84:85], v[100:101], v[64:65] op_sel:[0,1,0]
	v_pk_fma_f32 v[66:67], v[98:99], v[102:103], v[66:67] op_sel_hi:[1,0,1]
	v_pk_fma_f32 v[64:65], v[96:97], v[102:103], v[64:65] op_sel_hi:[1,0,1]
	v_mov_b32_e32 v76, v103
	v_pk_fma_f32 v[64:65], v[72:73], v[76:77], v[64:65] op_sel_hi:[1,0,1]
	v_pk_fma_f32 v[66:67], v[74:75], v[76:77], v[66:67] op_sel_hi:[1,0,1]
	ds_read_b128 v[72:75], v136 offset:80
	s_waitcnt vmcnt(15) lgkmcnt(1)
	v_pk_fma_f32 v[76:77], v[42:43], v[68:69], v[150:151] op_sel_hi:[1,0,1]
	v_pk_fma_f32 v[78:79], v[40:41], v[68:69], v[142:143] op_sel_hi:[1,0,1]
	s_waitcnt vmcnt(14)
	v_pk_fma_f32 v[76:77], v[38:39], v[68:69], v[76:77] op_sel:[0,1,0]
	v_pk_fma_f32 v[68:69], v[36:37], v[68:69], v[78:79] op_sel:[0,1,0]
	s_waitcnt vmcnt(13)
	v_pk_fma_f32 v[76:77], v[50:51], v[70:71], v[76:77] op_sel_hi:[1,0,1]
	v_pk_fma_f32 v[68:69], v[48:49], v[70:71], v[68:69] op_sel_hi:[1,0,1]
	v_mov_b32_e32 v70, v71
	s_waitcnt vmcnt(12)
	v_pk_fma_f32 v[76:77], v[46:47], v[70:71], v[76:77] op_sel_hi:[1,0,1]
	v_pk_fma_f32 v[68:69], v[44:45], v[70:71], v[68:69] op_sel_hi:[1,0,1]
	s_waitcnt vmcnt(11) lgkmcnt(0)
	v_pk_fma_f32 v[70:71], v[58:59], v[72:73], v[76:77] op_sel_hi:[1,0,1]
	v_pk_fma_f32 v[68:69], v[56:57], v[72:73], v[68:69] op_sel_hi:[1,0,1]
	s_waitcnt vmcnt(10)
	v_pk_fma_f32 v[70:71], v[54:55], v[72:73], v[70:71] op_sel:[0,1,0]
	v_pk_fma_f32 v[68:69], v[52:53], v[72:73], v[68:69] op_sel:[0,1,0]
	s_waitcnt vmcnt(9)
	v_pk_fma_f32 v[72:73], v[62:63], v[74:75], v[70:71] op_sel_hi:[1,0,1]
	v_pk_fma_f32 v[76:77], v[60:61], v[74:75], v[68:69] op_sel_hi:[1,0,1]
	ds_read_b128 v[68:71], v136 offset:96
	v_mov_b32_e32 v74, v75
	s_waitcnt vmcnt(8)
	v_pk_fma_f32 v[78:79], v[34:35], v[74:75], v[72:73] op_sel_hi:[1,0,1]
	v_pk_fma_f32 v[76:77], v[32:33], v[74:75], v[76:77] op_sel_hi:[1,0,1]
	ds_read_b128 v[72:75], v136 offset:112
	s_waitcnt vmcnt(7) lgkmcnt(1)
	v_pk_fma_f32 v[78:79], v[14:15], v[68:69], v[78:79] op_sel_hi:[1,0,1]
	v_pk_fma_f32 v[76:77], v[12:13], v[68:69], v[76:77] op_sel_hi:[1,0,1]
	s_waitcnt vmcnt(6)
	v_pk_fma_f32 v[78:79], v[6:7], v[68:69], v[78:79] op_sel:[0,1,0]
	v_pk_fma_f32 v[68:69], v[4:5], v[68:69], v[76:77] op_sel:[0,1,0]
	s_waitcnt vmcnt(5)
	v_pk_fma_f32 v[76:77], v[22:23], v[70:71], v[78:79] op_sel_hi:[1,0,1]
	v_pk_fma_f32 v[68:69], v[20:21], v[70:71], v[68:69] op_sel_hi:[1,0,1]
	v_mov_b32_e32 v70, v71
	s_waitcnt vmcnt(4)
	v_pk_fma_f32 v[76:77], v[10:11], v[70:71], v[76:77] op_sel_hi:[1,0,1]
	v_pk_fma_f32 v[68:69], v[8:9], v[70:71], v[68:69] op_sel_hi:[1,0,1]
	s_waitcnt vmcnt(3) lgkmcnt(0)
	v_pk_fma_f32 v[70:71], v[26:27], v[72:73], v[76:77] op_sel_hi:[1,0,1]
	v_pk_fma_f32 v[68:69], v[24:25], v[72:73], v[68:69] op_sel_hi:[1,0,1]
	s_waitcnt vmcnt(2)
; #define LAS __attribute__((address_space(3)))
; DI void attn_sample_item(const Params& p, int item, ldsp lds, int tid_) {
;     ...
; #pragma unroll
;     for (int t = 0; t < 4; ++t)
; #pragma unroll
;       for (int j4 = 0; j4 < 4; ++j4) { const f32x4 pp = *(const LAS f32x4*)(SC + t * 256 + wid * 32 + 16 + j4 * 4);
; #pragma unroll
;         for (int e = 0; e < 4; ++e) acc[t] += pp[e] * vvB[j4 * 4 + e]; }
	v_pk_fma_f32 v[70:71], v[18:19], v[72:73], v[70:71] op_sel:[0,1,0]
	v_pk_fma_f32 v[68:69], v[16:17], v[72:73], v[68:69] op_sel:[0,1,0]
	s_waitcnt vmcnt(1)
	v_pk_fma_f32 v[72:73], v[30:31], v[74:75], v[70:71] op_sel_hi:[1,0,1]
	v_pk_fma_f32 v[76:77], v[28:29], v[74:75], v[68:69] op_sel_hi:[1,0,1]
	ds_read_b128 v[68:71], v136 offset:1088
	v_mov_b32_e32 v78, v75
	s_waitcnt vmcnt(0)
	v_pk_fma_f32 v[74:75], v[2:3], v[78:79], v[72:73] op_sel_hi:[1,0,1]
	v_pk_fma_f32 v[72:73], v[0:1], v[78:79], v[76:77] op_sel_hi:[1,0,1]
	ds_read_b128 v[76:79], v136 offset:1104
	s_waitcnt lgkmcnt(1)
	v_pk_fma_f32 v[80:81], v[42:43], v[68:69], v[132:133] op_sel_hi:[1,0,1]
	v_pk_fma_f32 v[82:83], v[40:41], v[68:69], v[128:129] op_sel_hi:[1,0,1]
	v_pk_fma_f32 v[80:81], v[38:39], v[68:69], v[80:81] op_sel:[0,1,0]
	v_pk_fma_f32 v[68:69], v[36:37], v[68:69], v[82:83] op_sel:[0,1,0]
	v_pk_fma_f32 v[80:81], v[50:51], v[70:71], v[80:81] op_sel_hi:[1,0,1]
	v_pk_fma_f32 v[68:69], v[48:49], v[70:71], v[68:69] op_sel_hi:[1,0,1]
	v_mov_b32_e32 v70, v71
	v_pk_fma_f32 v[80:81], v[46:47], v[70:71], v[80:81] op_sel_hi:[1,0,1]
	v_pk_fma_f32 v[68:69], v[44:45], v[70:71], v[68:69] op_sel_hi:[1,0,1]
	s_waitcnt lgkmcnt(0)
	v_pk_fma_f32 v[70:71], v[58:59], v[76:77], v[80:81] op_sel_hi:[1,0,1]
	v_pk_fma_f32 v[68:69], v[56:57], v[76:77], v[68:69] op_sel_hi:[1,0,1]
	v_pk_fma_f32 v[70:71], v[54:55], v[76:77], v[70:71] op_sel:[0,1,0]
	v_pk_fma_f32 v[68:69], v[52:53], v[76:77], v[68:69] op_sel:[0,1,0]
	v_pk_fma_f32 v[76:77], v[62:63], v[78:79], v[70:71] op_sel_hi:[1,0,1]
	v_pk_fma_f32 v[80:81], v[60:61], v[78:79], v[68:69] op_sel_hi:[1,0,1]
	ds_read_b128 v[68:71], v136 offset:1120
	v_mov_b32_e32 v78, v79
	v_pk_fma_f32 v[82:83], v[34:35], v[78:79], v[76:77] op_sel_hi:[1,0,1]
	v_pk_fma_f32 v[80:81], v[32:33], v[78:79], v[80:81] op_sel_hi:[1,0,1]
	ds_read_b128 v[76:79], v136 offset:1136
	s_waitcnt lgkmcnt(1)
	v_pk_fma_f32 v[82:83], v[14:15], v[68:69], v[82:83] op_sel_hi:[1,0,1]
	v_pk_fma_f32 v[80:81], v[12:13], v[68:69], v[80:81] op_sel_hi:[1,0,1]
	v_pk_fma_f32 v[82:83], v[6:7], v[68:69], v[82:83] op_sel:[0,1,0]
	v_pk_fma_f32 v[68:69], v[4:5], v[68:69], v[80:81] op_sel:[0,1,0]
	v_pk_fma_f32 v[80:81], v[22:23], v[70:71], v[82:83] op_sel_hi:[1,0,1]
	v_pk_fma_f32 v[68:69], v[20:21], v[70:71], v[68:69] op_sel_hi:[1,0,1]
	v_mov_b32_e32 v70, v71
	v_pk_fma_f32 v[80:81], v[10:11], v[70:71], v[80:81] op_sel_hi:[1,0,1]
	v_pk_fma_f32 v[68:69], v[8:9], v[70:71], v[68:69] op_sel_hi:[1,0,1]
	s_waitcnt lgkmcnt(0)
	v_pk_fma_f32 v[70:71], v[26:27], v[76:77], v[80:81] op_sel_hi:[1,0,1]
	v_pk_fma_f32 v[68:69], v[24:25], v[76:77], v[68:69] op_sel_hi:[1,0,1]
	v_pk_fma_f32 v[70:71], v[18:19], v[76:77], v[70:71] op_sel:[0,1,0]
	v_pk_fma_f32 v[68:69], v[16:17], v[76:77], v[68:69] op_sel:[0,1,0]
	v_pk_fma_f32 v[76:77], v[30:31], v[78:79], v[70:71] op_sel_hi:[1,0,1]
	v_pk_fma_f32 v[80:81], v[28:29], v[78:79], v[68:69] op_sel_hi:[1,0,1]
	ds_read_b128 v[68:71], v136 offset:2112
	v_mov_b32_e32 v82, v79
	v_pk_fma_f32 v[78:79], v[2:3], v[82:83], v[76:77] op_sel_hi:[1,0,1]
	v_pk_fma_f32 v[76:77], v[0:1], v[82:83], v[80:81] op_sel_hi:[1,0,1]
	ds_read_b128 v[80:83], v136 offset:2128
	s_waitcnt lgkmcnt(1)
	v_pk_fma_f32 v[84:85], v[42:43], v[68:69], v[134:135] op_sel_hi:[1,0,1]
	v_pk_fma_f32 v[86:87], v[40:41], v[68:69], v[130:131] op_sel_hi:[1,0,1]
	v_pk_fma_f32 v[84:85], v[38:39], v[68:69], v[84:85] op_sel:[0,1,0]
	v_pk_fma_f32 v[68:69], v[36:37], v[68:69], v[86:87] op_sel:[0,1,0]
	v_pk_fma_f32 v[84:85], v[50:51], v[70:71], v[84:85] op_sel_hi:[1,0,1]
	v_pk_fma_f32 v[68:69], v[48:49], v[70:71], v[68:69] op_sel_hi:[1,0,1]
	v_mov_b32_e32 v70, v71
	v_pk_fma_f32 v[84:85], v[46:47], v[70:71], v[84:85] op_sel_hi:[1,0,1]
	v_pk_fma_f32 v[68:69], v[44:45], v[70:71], v[68:69] op_sel_hi:[1,0,1]
	s_waitcnt lgkmcnt(0)
	v_pk_fma_f32 v[70:71], v[58:59], v[80:81], v[84:85] op_sel_hi:[1,0,1]
	v_pk_fma_f32 v[68:69], v[56:57], v[80:81], v[68:69] op_sel_hi:[1,0,1]
	v_pk_fma_f32 v[70:71], v[54:55], v[80:81], v[70:71] op_sel:[0,1,0]
	v_pk_fma_f32 v[68:69], v[52:53], v[80:81], v[68:69] op_sel:[0,1,0]
	v_pk_fma_f32 v[80:81], v[62:63], v[82:83], v[70:71] op_sel_hi:[1,0,1]
	v_pk_fma_f32 v[84:85], v[60:61], v[82:83], v[68:69] op_sel_hi:[1,0,1]
	ds_read_b128 v[68:71], v136 offset:2144
	v_mov_b32_e32 v82, v83
	v_pk_fma_f32 v[86:87], v[34:35], v[82:83], v[80:81] op_sel_hi:[1,0,1]
	v_pk_fma_f32 v[84:85], v[32:33], v[82:83], v[84:85] op_sel_hi:[1,0,1]
	ds_read_b128 v[80:83], v136 offset:2160
	s_waitcnt lgkmcnt(1)
	v_pk_fma_f32 v[86:87], v[14:15], v[68:69], v[86:87] op_sel_hi:[1,0,1]
	v_pk_fma_f32 v[84:85], v[12:13], v[68:69], v[84:85] op_sel_hi:[1,0,1]
	v_pk_fma_f32 v[86:87], v[6:7], v[68:69], v[86:87] op_sel:[0,1,0]
	v_pk_fma_f32 v[68:69], v[4:5], v[68:69], v[84:85] op_sel:[0,1,0]
	v_pk_fma_f32 v[84:85], v[22:23], v[70:71], v[86:87] op_sel_hi:[1,0,1]
	v_pk_fma_f32 v[68:69], v[20:21], v[70:71], v[68:69] op_sel_hi:[1,0,1]
	v_mov_b32_e32 v70, v71
	v_pk_fma_f32 v[84:85], v[10:11], v[70:71], v[84:85] op_sel_hi:[1,0,1]
	v_pk_fma_f32 v[68:69], v[8:9], v[70:71], v[68:69] op_sel_hi:[1,0,1]
	s_waitcnt lgkmcnt(0)
	v_pk_fma_f32 v[70:71], v[26:27], v[80:81], v[84:85] op_sel_hi:[1,0,1]
	v_pk_fma_f32 v[68:69], v[24:25], v[80:81], v[68:69] op_sel_hi:[1,0,1]
	v_pk_fma_f32 v[70:71], v[18:19], v[80:81], v[70:71] op_sel:[0,1,0]
	v_pk_fma_f32 v[68:69], v[16:17], v[80:81], v[68:69] op_sel:[0,1,0]
	v_pk_fma_f32 v[80:81], v[30:31], v[82:83], v[70:71] op_sel_hi:[1,0,1]
	v_pk_fma_f32 v[84:85], v[28:29], v[82:83], v[68:69] op_sel_hi:[1,0,1]
	ds_read_b128 v[68:71], v136 offset:3136
	v_mov_b32_e32 v86, v83
	v_pk_fma_f32 v[82:83], v[2:3], v[86:87], v[80:81] op_sel_hi:[1,0,1]
	v_pk_fma_f32 v[80:81], v[0:1], v[86:87], v[84:85] op_sel_hi:[1,0,1]
	ds_read_b128 v[84:87], v136 offset:3152
	s_waitcnt lgkmcnt(1)
; #define LAS __attribute__((address_space(3)))
; DI unsigned pk2(float lo, float hi) { f32x2 v = {lo, hi}; return __builtin_bit_cast(unsigned, __builtin_convertvector(v, bf16x2v)); }
; DI void lbar() { asm volatile("s_waitcnt lgkmcnt(0)" ::: "memory"); __builtin_amdgcn_s_barrier(); asm volatile("" ::: "memory"); }
; DI void attn_sample_item(const Params& p, int item, ldsp lds, int tid_) {
;     ...
;   for (int t = 0; t < 4; ++t) { f32x4 a = {0.f, 0.f, 0.f, 0.f}; const float* pp = (const float*)(p.ws + B_PART) + (size_t)(b * 4 + t) * 1024 + h * 256 + lane * 4;
; #pragma unroll
;     for (int kp = 0; kp < 4; ++kp) a += *(const f32x4*)(pp + (size_t)kp * 512 * 1024);
;     q[t][0] = a[0] * 0.0625f; q[t][1] = a[1] * 0.0625f; q[t][2] = a[2] * 0.0625f; q[t][3] = a[3] * 0.0625f; }
;     ...
; #pragma unroll
;     for (int t = 0; t < 4; ++t)
; #pragma unroll
;       for (int j4 = 0; j4 < 4; ++j4) { const f32x4 pp = *(const LAS f32x4*)(SC + t * 256 + wid * 32 + 16 + j4 * 4);
; #pragma unroll
;         for (int e = 0; e < 4; ++e) acc[t] += pp[e] * vvB[j4 * 4 + e]; }
; #pragma unroll
;     for (int t = 0; t < 4; ++t) *(LAS f32x4*)(PART + (wid * 4 + t) * 256 + lane * 4) = acc[t];
;   }
;   lbar();
;   {
;     const int e0 = tid * 2, t = e0 >> 8, d = e0 & 255;
;     float s0 = 0.f, s1 = 0.f;
; #pragma unroll
;     for (int w = 0; w < 8; ++w) { const f32x2 v = *(const LAS f32x2*)(PART + (w * 4 + t) * 256 + d); s0 += v[0]; s1 += v[1]; }
;     *(unsigned*)((bf16_t*)(p.ws + B_XA) + (size_t)(TP + b * 4 + t) * D + h * 256 + d) = pk2(s0, s1);
;   }
;   lbar();
	v_pk_fma_f32 v[42:43], v[42:43], v[68:69], v[66:67] op_sel_hi:[1,0,1]
	v_pk_fma_f32 v[40:41], v[40:41], v[68:69], v[64:65] op_sel_hi:[1,0,1]
	v_pk_fma_f32 v[38:39], v[38:39], v[68:69], v[42:43] op_sel:[0,1,0]
	v_pk_fma_f32 v[36:37], v[36:37], v[68:69], v[40:41] op_sel:[0,1,0]
	v_pk_fma_f32 v[38:39], v[50:51], v[70:71], v[38:39] op_sel_hi:[1,0,1]
	v_pk_fma_f32 v[36:37], v[48:49], v[70:71], v[36:37] op_sel_hi:[1,0,1]
	v_mov_b32_e32 v40, v71
	v_pk_fma_f32 v[38:39], v[46:47], v[40:41], v[38:39] op_sel_hi:[1,0,1]
	v_pk_fma_f32 v[36:37], v[44:45], v[40:41], v[36:37] op_sel_hi:[1,0,1]
	s_waitcnt lgkmcnt(0)
	v_pk_fma_f32 v[38:39], v[58:59], v[84:85], v[38:39] op_sel_hi:[1,0,1]
	v_pk_fma_f32 v[36:37], v[56:57], v[84:85], v[36:37] op_sel_hi:[1,0,1]
	v_pk_fma_f32 v[38:39], v[54:55], v[84:85], v[38:39] op_sel:[0,1,0]
	v_pk_fma_f32 v[36:37], v[52:53], v[84:85], v[36:37] op_sel:[0,1,0]
	v_pk_fma_f32 v[40:41], v[62:63], v[86:87], v[38:39] op_sel_hi:[1,0,1]
	v_pk_fma_f32 v[42:43], v[60:61], v[86:87], v[36:37] op_sel_hi:[1,0,1]
	ds_read_b128 v[36:39], v136 offset:3168
	v_mov_b32_e32 v44, v87
	v_pk_fma_f32 v[40:41], v[34:35], v[44:45], v[40:41] op_sel_hi:[1,0,1]
	v_pk_fma_f32 v[42:43], v[32:33], v[44:45], v[42:43] op_sel_hi:[1,0,1]
	ds_read_b128 v[32:35], v136 offset:3184
	s_waitcnt lgkmcnt(1)
	v_pk_fma_f32 v[12:13], v[12:13], v[36:37], v[42:43] op_sel_hi:[1,0,1]
	v_pk_fma_f32 v[14:15], v[14:15], v[36:37], v[40:41] op_sel_hi:[1,0,1]
	v_pk_fma_f32 v[4:5], v[4:5], v[36:37], v[12:13] op_sel:[0,1,0]
	v_mov_b32_e32 v12, v39
	v_pk_fma_f32 v[4:5], v[20:21], v[38:39], v[4:5] op_sel_hi:[1,0,1]
	v_pk_fma_f32 v[6:7], v[6:7], v[36:37], v[14:15] op_sel:[0,1,0]
	v_pk_fma_f32 v[4:5], v[8:9], v[12:13], v[4:5] op_sel_hi:[1,0,1]
	v_pk_fma_f32 v[6:7], v[22:23], v[38:39], v[6:7] op_sel_hi:[1,0,1]
	s_waitcnt lgkmcnt(0)
	v_pk_fma_f32 v[4:5], v[24:25], v[32:33], v[4:5] op_sel_hi:[1,0,1]
	v_pk_fma_f32 v[6:7], v[10:11], v[12:13], v[6:7] op_sel_hi:[1,0,1]
	v_pk_fma_f32 v[4:5], v[16:17], v[32:33], v[4:5] op_sel:[0,1,0]
	v_pk_fma_f32 v[6:7], v[26:27], v[32:33], v[6:7] op_sel_hi:[1,0,1]
	v_pk_fma_f32 v[4:5], v[28:29], v[34:35], v[4:5] op_sel_hi:[1,0,1]
	v_mov_b32_e32 v8, v35
	v_pk_fma_f32 v[6:7], v[18:19], v[32:33], v[6:7] op_sel:[0,1,0]
	v_pk_fma_f32 v[0:1], v[0:1], v[8:9], v[4:5] op_sel_hi:[1,0,1]
	v_lshlrev_b32_e32 v4, 12, v210
	v_pk_fma_f32 v[6:7], v[30:31], v[34:35], v[6:7] op_sel_hi:[1,0,1]
	v_add3_u32 v4, 16, v4, v144
	v_pk_fma_f32 v[2:3], v[2:3], v[8:9], v[6:7] op_sel_hi:[1,0,1]
	ds_write_b128 v4, v[72:75] offset:4096
	ds_write_b128 v4, v[76:79] offset:5120
	ds_write_b128 v4, v[80:83] offset:6144
	ds_write_b128 v4, v[0:3] offset:7168
	v_lshlrev_b32_e32 v0, 1, v222
	v_ashrrev_i32_e32 v16, 7, v222
	v_and_b32_e32 v17, 0xfe, v0
	v_lshlrev_b32_e32 v0, 10, v16
	v_lshlrev_b32_e32 v1, 2, v17
	s_waitcnt lgkmcnt(0)
	s_barrier
	v_add3_u32 v12, 16, v0, v1
	ds_read2st64_b64 v[0:3], v12 offset0:8 offset1:16
	ds_read2st64_b64 v[4:7], v12 offset0:24 offset1:32
	ds_read2st64_b64 v[8:11], v12 offset0:40 offset1:48
	ds_read2st64_b64 v[12:15], v12 offset0:56 offset1:64
	v_lshlrev_b32_e32 v144, 1, v17
	s_waitcnt lgkmcnt(3)
	v_pk_add_f32 v[0:1], v[0:1], 0 op_sel_hi:[1,0]
	s_cmpk_lt_i32 s38, 0x200
	v_pk_add_f32 v[0:1], v[0:1], v[2:3]
	s_waitcnt lgkmcnt(2)
	v_pk_add_f32 v[0:1], v[0:1], v[4:5]
	s_nop 0
	v_pk_add_f32 v[0:1], v[0:1], v[6:7]
	s_waitcnt lgkmcnt(1)
	v_pk_add_f32 v[0:1], v[0:1], v[8:9]
	s_nop 0
	v_pk_add_f32 v[0:1], v[0:1], v[10:11]
	s_waitcnt lgkmcnt(0)
	v_pk_add_f32 v[0:1], v[0:1], v[12:13]
	s_nop 0
	v_pk_add_f32 v[0:1], v[0:1], v[14:15]
	s_nop 0
	v_cvt_pk_bf16_f32 v2, v0, v1
	v_add_u32_e32 v0, s4, v16
	v_ashrrev_i32_e32 v1, 31, v0
	v_lshlrev_b64 v[0:1], 11, v[0:1]
	v_lshl_add_u64 v[0:1], s[22:23], 0, v[0:1]
	v_lshl_add_u64 v[0:1], v[0:1], 0, s[24:25]
	v_lshl_add_u64 v[0:1], v[0:1], 0, v[144:145]
	global_store_dword v[0:1], v2, off
	s_waitcnt lgkmcnt(0)
	s_barrier
	s_cbranch_scc0 .LBB0_1742
.LBB0_1676:
	s_ashr_i32 s4, s38, 2
	s_ashr_i32 s5, s4, 31
	s_lshl_b64 s[4:5], s[4:5], 18
	s_and_b32 s24, s0, 0x300
	v_mov_b32_e32 v222, v212
	s_or_b32 s4, s4, s24
	s_and_b32 s26, s38, -4
	s_lshl_b32 s6, s24, 2
	s_add_u32 s6, s36, s6
	v_and_b32_e32 v223, 63, v222
	s_addc_u32 s7, s37, 0
	v_lshlrev_b32_e32 v144, 4, v223
	s_ashr_i32 s27, s26, 31
	v_lshl_add_u64 v[48:49], s[6:7], 0, v[144:145]
	s_lshl_b64 s[6:7], s[26:27], 12
	v_lshl_add_u64 v[8:9], v[48:49], 0, s[6:7]
	v_add_co_u32_e32 v10, vcc, s3, v8
	s_or_b32 s6, s26, 1
	s_nop 0
	v_addc_co_u32_e32 v11, vcc, 0, v9, vcc
	global_load_dwordx4 v[0:3], v[8:9], off
	global_load_dwordx4 v[4:7], v[10:11], off
	v_add_co_u32_e32 v10, vcc, s33, v8
	s_ashr_i32 s7, s6, 31
	s_nop 0
	v_addc_co_u32_e32 v11, vcc, 0, v9, vcc
	v_add_co_u32_e32 v12, vcc, s34, v8
	s_lshl_b64 s[6:7], s[6:7], 12
	s_nop 0
	v_addc_co_u32_e32 v13, vcc, 0, v9, vcc
	v_lshl_add_u64 v[24:25], v[48:49], 0, s[6:7]
	v_add_co_u32_e32 v20, vcc, s3, v24
	s_or_b32 s6, s26, 2
	s_nop 0
	v_addc_co_u32_e32 v21, vcc, 0, v25, vcc
	v_add_co_u32_e32 v26, vcc, s33, v24
	s_ashr_i32 s7, s6, 31
	s_nop 0
	v_addc_co_u32_e32 v27, vcc, 0, v25, vcc
	v_add_co_u32_e32 v28, vcc, s34, v24
	s_lshl_b64 s[6:7], s[6:7], 12
	s_nop 0
	v_addc_co_u32_e32 v29, vcc, 0, v25, vcc
	v_lshl_add_u64 v[44:45], v[48:49], 0, s[6:7]
	global_load_dwordx4 v[8:11], v[10:11], off
	s_nop 0
	global_load_dwordx4 v[12:15], v[12:13], off
	s_nop 0
	global_load_dwordx4 v[16:19], v[24:25], off
	s_nop 0
	global_load_dwordx4 v[20:23], v[20:21], off
	v_add_co_u32_e32 v36, vcc, s3, v44
	global_load_dwordx4 v[24:27], v[26:27], off
	s_nop 0
	global_load_dwordx4 v[28:31], v[28:29], off
	v_addc_co_u32_e32 v37, vcc, 0, v45, vcc
	v_add_co_u32_e32 v40, vcc, s33, v44
	global_load_dwordx4 v[32:35], v[44:45], off
	s_nop 0
	global_load_dwordx4 v[36:39], v[36:37], off
	v_addc_co_u32_e32 v41, vcc, 0, v45, vcc
	v_add_co_u32_e32 v44, vcc, s34, v44
	global_load_dwordx4 v[40:43], v[40:41], off
	s_nop 0
	v_addc_co_u32_e32 v45, vcc, 0, v45, vcc
	global_load_dwordx4 v[44:47], v[44:45], off
	s_or_b32 s6, s38, 3
	s_ashr_i32 s7, s6, 31
	s_lshl_b64 s[6:7], s[6:7], 12
	s_lshl_b64 s[28:29], s[4:5], 2
	s_add_u32 s4, s12, s28
	s_addc_u32 s5, s13, s29
	s_waitcnt vmcnt(11)
; DI void attn_sample_item(const Params& p, int item, ldsp lds, int tid_) {
;     ...
;   for (int t = 0; t < 4; ++t) { f32x4 a = {0.f, 0.f, 0.f, 0.f}; const float* pp = (const float*)(p.ws + B_PART) + (size_t)(b * 4 + t) * 1024 + h * 256 + lane * 4;
; #pragma unroll
;     for (int kp = 0; kp < 4; ++kp) a += *(const f32x4*)(pp + (size_t)kp * 512 * 1024);
;     q[t][0] = a[0] * 0.0625f; q[t][1] = a[1] * 0.0625f; q[t][2] = a[2] * 0.0625f; q[t][3] = a[3] * 0.0625f; }
;   const bool b0 = lane & 1, b1 = lane & 2;
;   f32x4 kvA[16], kvB[16];
; #pragma unroll
;   for (int j = 0; j < 16; ++j) kvA[j] = __builtin_nontemporal_load((const f32x4*)(ck + (size_t)(wid * 32 + j) * 1024 + lane * 4));
; #pragma unroll
;   for (int j = 0; j < 16; ++j) kvB[j] = __builtin_nontemporal_load((const f32x4*)(ck + (size_t)(wid * 32 + 16 + j) * 1024 + lane * 4));
	v_pk_add_f32 v[2:3], v[2:3], 0 op_sel_hi:[1,0]
	v_pk_add_f32 v[0:1], v[0:1], 0 op_sel_hi:[1,0]
	s_waitcnt vmcnt(10)
	v_pk_add_f32 v[2:3], v[2:3], v[6:7]
	v_pk_add_f32 v[0:1], v[0:1], v[4:5]
	s_waitcnt vmcnt(9)
	v_pk_add_f32 v[2:3], v[2:3], v[10:11]
	s_waitcnt vmcnt(7)
	v_pk_add_f32 v[4:5], v[18:19], 0 op_sel_hi:[1,0]
	v_pk_add_f32 v[6:7], v[16:17], 0 op_sel_hi:[1,0]
	v_pk_add_f32 v[0:1], v[0:1], v[8:9]
	s_waitcnt vmcnt(6)
	v_pk_add_f32 v[4:5], v[4:5], v[22:23]
	v_pk_add_f32 v[6:7], v[6:7], v[20:21]
	v_pk_add_f32 v[2:3], v[2:3], v[14:15]
	v_pk_add_f32 v[0:1], v[0:1], v[12:13]
	s_waitcnt vmcnt(5)
	v_pk_add_f32 v[4:5], v[4:5], v[26:27]
	v_pk_add_f32 v[6:7], v[6:7], v[24:25]
	v_mul_f32_e32 v228, 0x3d800000, v0
	v_mul_f32_e32 v231, 0x3d800000, v1
	v_mul_f32_e32 v229, 0x3d800000, v2
	v_mul_f32_e32 v225, 0x3d800000, v3
	s_waitcnt vmcnt(4)
	v_pk_add_f32 v[0:1], v[4:5], v[30:31]
	v_pk_add_f32 v[2:3], v[6:7], v[28:29]
	v_mul_f32_e32 v227, 0x3d800000, v0
	v_mul_f32_e32 v226, 0x3d800000, v2
	v_mul_f32_e32 v230, 0x3d800000, v3
	v_mul_f32_e32 v224, 0x3d800000, v1
	s_waitcnt vmcnt(3)
	v_pk_add_f32 v[0:1], v[34:35], 0 op_sel_hi:[1,0]
	v_pk_add_f32 v[2:3], v[32:33], 0 op_sel_hi:[1,0]
	s_waitcnt vmcnt(2)
	v_pk_add_f32 v[0:1], v[0:1], v[38:39]
	v_pk_add_f32 v[2:3], v[2:3], v[36:37]
	s_waitcnt vmcnt(1)
	v_pk_add_f32 v[0:1], v[0:1], v[42:43]
	v_pk_add_f32 v[2:3], v[2:3], v[40:41]
	s_waitcnt vmcnt(0)
	v_pk_add_f32 v[210:211], v[0:1], v[46:47]
	v_pk_add_f32 v[0:1], v[2:3], v[44:45]
	v_mul_f32_e32 v233, 0x3d800000, v210
	v_mul_f32_e32 v232, 0x3d800000, v0
	v_mul_f32_e32 v234, 0x3d800000, v1
	v_lshl_add_u64 v[0:1], v[48:49], 0, s[6:7]
	v_add_co_u32_e32 v2, vcc, s3, v0
	v_ashrrev_i32_e32 v210, 6, v222
	s_nop 0
	v_addc_co_u32_e32 v3, vcc, 0, v1, vcc
	global_load_dwordx4 v[128:131], v[0:1], off
	global_load_dwordx4 v[132:135], v[2:3], off
	v_add_co_u32_e32 v2, vcc, s33, v0
	v_mul_f32_e32 v211, 0x3d800000, v211
	s_nop 0
	v_addc_co_u32_e32 v3, vcc, 0, v1, vcc
	v_add_co_u32_e32 v0, vcc, s34, v0
	v_cmp_lt_i32_e64 s[6:7], v218, v216
	s_nop 0
	v_addc_co_u32_e32 v1, vcc, 0, v1, vcc
	global_load_dwordx4 v[136:139], v[2:3], off
	global_load_dwordx4 v[140:143], v[0:1], off
	v_lshlrev_b32_e32 v0, 5, v210
	v_ashrrev_i32_e32 v1, 31, v0
	v_or_b32_e32 v6, 1, v0
	v_lshl_add_u64 v[2:3], s[4:5], 0, v[144:145]
	v_lshlrev_b64 v[158:159], 12, v[0:1]
	v_ashrrev_i32_e32 v7, 31, v6
	v_lshl_add_u64 v[4:5], v[2:3], 0, v[158:159]
	v_lshlrev_b64 v[162:163], 12, v[6:7]
	v_lshl_add_u64 v[6:7], v[2:3], 0, v[162:163]
	global_load_dwordx4 v[124:127], v[4:5], off nt
	global_load_dwordx4 v[120:123], v[6:7], off nt
	v_or_b32_e32 v4, 2, v0
	v_ashrrev_i32_e32 v5, 31, v4
	v_or_b32_e32 v6, 3, v0
	v_lshlrev_b64 v[164:165], 12, v[4:5]
	v_ashrrev_i32_e32 v7, 31, v6
	v_lshl_add_u64 v[4:5], v[2:3], 0, v[164:165]
	v_lshlrev_b64 v[168:169], 12, v[6:7]
	v_lshl_add_u64 v[6:7], v[2:3], 0, v[168:169]
	global_load_dwordx4 v[116:119], v[4:5], off nt
	global_load_dwordx4 v[112:115], v[6:7], off nt
	v_or_b32_e32 v4, 4, v0
	v_ashrrev_i32_e32 v5, 31, v4
	v_or_b32_e32 v6, 5, v0
	v_lshlrev_b64 v[172:173], 12, v[4:5]
	v_ashrrev_i32_e32 v7, 31, v6
	v_lshl_add_u64 v[4:5], v[2:3], 0, v[172:173]
	v_lshlrev_b64 v[176:177], 12, v[6:7]
	v_lshl_add_u64 v[6:7], v[2:3], 0, v[176:177]
	global_load_dwordx4 v[108:111], v[4:5], off nt
	global_load_dwordx4 v[104:107], v[6:7], off nt
	v_or_b32_e32 v4, 6, v0
	v_ashrrev_i32_e32 v5, 31, v4
	v_or_b32_e32 v6, 7, v0
	v_lshlrev_b64 v[180:181], 12, v[4:5]
	v_ashrrev_i32_e32 v7, 31, v6
	v_lshl_add_u64 v[4:5], v[2:3], 0, v[180:181]
	v_lshlrev_b64 v[184:185], 12, v[6:7]
	v_lshl_add_u64 v[6:7], v[2:3], 0, v[184:185]
	global_load_dwordx4 v[100:103], v[4:5], off nt
	global_load_dwordx4 v[96:99], v[6:7], off nt
	v_or_b32_e32 v4, 8, v0
	v_ashrrev_i32_e32 v5, 31, v4
	v_or_b32_e32 v6, 9, v0
	v_lshlrev_b64 v[188:189], 12, v[4:5]
	v_ashrrev_i32_e32 v7, 31, v6
	v_lshl_add_u64 v[4:5], v[2:3], 0, v[188:189]
	v_lshlrev_b64 v[192:193], 12, v[6:7]
	v_lshl_add_u64 v[6:7], v[2:3], 0, v[192:193]
	global_load_dwordx4 v[92:95], v[4:5], off nt
	global_load_dwordx4 v[88:91], v[6:7], off nt
	v_or_b32_e32 v4, 10, v0
	v_ashrrev_i32_e32 v5, 31, v4
	v_or_b32_e32 v6, 11, v0
	v_lshlrev_b64 v[196:197], 12, v[4:5]
	v_ashrrev_i32_e32 v7, 31, v6
	v_lshl_add_u64 v[4:5], v[2:3], 0, v[196:197]
	v_lshlrev_b64 v[200:201], 12, v[6:7]
	v_lshl_add_u64 v[6:7], v[2:3], 0, v[200:201]
	global_load_dwordx4 v[84:87], v[4:5], off nt
	global_load_dwordx4 v[80:83], v[6:7], off nt
	v_or_b32_e32 v4, 12, v0
	v_ashrrev_i32_e32 v5, 31, v4
	v_or_b32_e32 v6, 13, v0
	v_lshlrev_b64 v[202:203], 12, v[4:5]
	v_ashrrev_i32_e32 v7, 31, v6
	v_lshl_add_u64 v[4:5], v[2:3], 0, v[202:203]
	v_lshlrev_b64 v[204:205], 12, v[6:7]
	v_lshl_add_u64 v[6:7], v[2:3], 0, v[204:205]
	global_load_dwordx4 v[76:79], v[4:5], off nt
	global_load_dwordx4 v[72:75], v[6:7], off nt
	v_or_b32_e32 v4, 14, v0
	v_ashrrev_i32_e32 v5, 31, v4
	v_or_b32_e32 v6, 15, v0
	v_lshlrev_b64 v[206:207], 12, v[4:5]
	v_ashrrev_i32_e32 v7, 31, v6
	v_lshl_add_u64 v[4:5], v[2:3], 0, v[206:207]
	v_lshlrev_b64 v[208:209], 12, v[6:7]
	v_lshl_add_u64 v[6:7], v[2:3], 0, v[208:209]
	global_load_dwordx4 v[68:71], v[4:5], off nt
	global_load_dwordx4 v[64:67], v[6:7], off nt
	v_or_b32_e32 v4, 16, v0
	v_ashrrev_i32_e32 v5, 31, v4
	v_or_b32_e32 v6, 17, v0
	v_lshlrev_b64 v[146:147], 12, v[4:5]
	v_ashrrev_i32_e32 v7, 31, v6
	v_lshl_add_u64 v[4:5], v[2:3], 0, v[146:147]
	v_lshlrev_b64 v[148:149], 12, v[6:7]
	v_lshl_add_u64 v[6:7], v[2:3], 0, v[148:149]
	global_load_dwordx4 v[60:63], v[4:5], off nt
	global_load_dwordx4 v[56:59], v[6:7], off nt
	v_or_b32_e32 v4, 18, v0
	v_ashrrev_i32_e32 v5, 31, v4
	v_or_b32_e32 v6, 19, v0
; DI void attn_sample_item(const Params& p, int item, ldsp lds, int tid_) {
;     ...
;   for (int t = 0; t < 4; ++t) { f32x4 a = {0.f, 0.f, 0.f, 0.f}; const float* pp = (const float*)(p.ws + B_PART) + (size_t)(b * 4 + t) * 1024 + h * 256 + lane * 4;
; #pragma unroll
;     for (int kp = 0; kp < 4; ++kp) a += *(const f32x4*)(pp + (size_t)kp * 512 * 1024);
;     q[t][0] = a[0] * 0.0625f; q[t][1] = a[1] * 0.0625f; q[t][2] = a[2] * 0.0625f; q[t][3] = a[3] * 0.0625f; }
;   const bool b0 = lane & 1, b1 = lane & 2;
;   f32x4 kvA[16], kvB[16];
; #pragma unroll
;   for (int j = 0; j < 16; ++j) kvA[j] = __builtin_nontemporal_load((const f32x4*)(ck + (size_t)(wid * 32 + j) * 1024 + lane * 4));
; #pragma unroll
;   for (int j = 0; j < 16; ++j) kvB[j] = __builtin_nontemporal_load((const f32x4*)(ck + (size_t)(wid * 32 + 16 + j) * 1024 + lane * 4));
	v_lshlrev_b64 v[150:151], 12, v[4:5]
	v_ashrrev_i32_e32 v7, 31, v6
	v_lshl_add_u64 v[4:5], v[2:3], 0, v[150:151]
	v_lshlrev_b64 v[152:153], 12, v[6:7]
	v_lshl_add_u64 v[6:7], v[2:3], 0, v[152:153]
	global_load_dwordx4 v[52:55], v[4:5], off nt
	global_load_dwordx4 v[48:51], v[6:7], off nt
	v_or_b32_e32 v4, 20, v0
	v_ashrrev_i32_e32 v5, 31, v4
	v_or_b32_e32 v6, 21, v0
	v_lshlrev_b64 v[154:155], 12, v[4:5]
	v_ashrrev_i32_e32 v7, 31, v6
	v_lshl_add_u64 v[4:5], v[2:3], 0, v[154:155]
	v_lshlrev_b64 v[156:157], 12, v[6:7]
	v_lshl_add_u64 v[6:7], v[2:3], 0, v[156:157]
	global_load_dwordx4 v[44:47], v[4:5], off nt
	global_load_dwordx4 v[40:43], v[6:7], off nt
	v_or_b32_e32 v4, 22, v0
	v_ashrrev_i32_e32 v5, 31, v4
	v_or_b32_e32 v6, 23, v0
	v_lshlrev_b64 v[160:161], 12, v[4:5]
	v_ashrrev_i32_e32 v7, 31, v6
	v_lshl_add_u64 v[4:5], v[2:3], 0, v[160:161]
	v_lshlrev_b64 v[166:167], 12, v[6:7]
	v_lshl_add_u64 v[6:7], v[2:3], 0, v[166:167]
	global_load_dwordx4 v[36:39], v[4:5], off nt
	global_load_dwordx4 v[32:35], v[6:7], off nt
	v_or_b32_e32 v4, 24, v0
	v_ashrrev_i32_e32 v5, 31, v4
	v_or_b32_e32 v6, 25, v0
	v_lshlrev_b64 v[170:171], 12, v[4:5]
	v_ashrrev_i32_e32 v7, 31, v6
	v_lshl_add_u64 v[4:5], v[2:3], 0, v[170:171]
	v_lshlrev_b64 v[174:175], 12, v[6:7]
	v_lshl_add_u64 v[6:7], v[2:3], 0, v[174:175]
	global_load_dwordx4 v[28:31], v[4:5], off nt
	global_load_dwordx4 v[24:27], v[6:7], off nt
	v_or_b32_e32 v4, 26, v0
	v_ashrrev_i32_e32 v5, 31, v4
	v_or_b32_e32 v6, 27, v0
	v_lshlrev_b64 v[178:179], 12, v[4:5]
	v_ashrrev_i32_e32 v7, 31, v6
	v_lshl_add_u64 v[4:5], v[2:3], 0, v[178:179]
	v_lshlrev_b64 v[182:183], 12, v[6:7]
	v_lshl_add_u64 v[6:7], v[2:3], 0, v[182:183]
	global_load_dwordx4 v[20:23], v[4:5], off nt
	global_load_dwordx4 v[16:19], v[6:7], off nt
	v_or_b32_e32 v4, 28, v0
	v_ashrrev_i32_e32 v5, 31, v4
	v_or_b32_e32 v6, 29, v0
	v_lshlrev_b64 v[186:187], 12, v[4:5]
	v_ashrrev_i32_e32 v7, 31, v6
	v_lshl_add_u64 v[4:5], v[2:3], 0, v[186:187]
	v_lshlrev_b64 v[190:191], 12, v[6:7]
	v_lshl_add_u64 v[6:7], v[2:3], 0, v[190:191]
	global_load_dwordx4 v[12:15], v[4:5], off nt
	global_load_dwordx4 v[8:11], v[6:7], off nt
	v_or_b32_e32 v4, 30, v0
	v_or_b32_e32 v0, 31, v0
	v_ashrrev_i32_e32 v5, 31, v4
	v_ashrrev_i32_e32 v1, 31, v0
	v_lshlrev_b64 v[194:195], 12, v[4:5]
	v_lshlrev_b64 v[198:199], 12, v[0:1]
	v_lshl_add_u64 v[4:5], v[2:3], 0, v[194:195]
	v_lshl_add_u64 v[0:1], v[2:3], 0, v[198:199]
	global_load_dwordx4 v[4:7], v[4:5], off nt
	s_nop 0
	global_load_dwordx4 v[0:3], v[0:1], off nt
	s_waitcnt vmcnt(35)
	v_pk_add_f32 v[128:129], v[128:129], 0 op_sel_hi:[1,0]
	v_pk_add_f32 v[130:131], v[130:131], 0 op_sel_hi:[1,0]
	s_waitcnt vmcnt(34)
	v_pk_add_f32 v[128:129], v[128:129], v[132:133]
	v_pk_add_f32 v[130:131], v[130:131], v[134:135]
	s_waitcnt vmcnt(33)
	v_pk_add_f32 v[128:129], v[128:129], v[136:137]
	v_pk_add_f32 v[130:131], v[130:131], v[138:139]
	s_waitcnt vmcnt(32)
	v_pk_add_f32 v[128:129], v[128:129], v[140:141]
	v_pk_add_f32 v[130:131], v[130:131], v[142:143]
	v_mul_f32_e32 v138, 0x3d800000, v129
	v_mul_f32_e32 v135, 0x3d800000, v128
	v_mul_f32_e32 v134, 0x3d800000, v131
	v_mul_f32_e32 v137, 0x3d800000, v130
	v_lshlrev_b32_e32 v128, 2, v215
	v_lshlrev_b32_e32 v129, 2, v217
	v_lshlrev_b32_e32 v130, 2, v218
	v_lshlrev_b32_e32 v131, 2, v219
	v_lshlrev_b32_e32 v132, 2, v220
	v_lshlrev_b32_e32 v133, 2, v221
	v_lshl_add_u32 v136, v210, 7, 16
	v_and_b32_e32 v139, 3, v223
	v_bfrev_b32_e32 v139, v139
	v_lshrrev_b32_e32 v139, 20, v139
	v_and_b32_e32 v235, -4, v223
	v_add3_u32 v235, v136, v139, v235
	v_mov_b32_e32 v236, v228
	v_mov_b32_e32 v237, v226
	v_mov_b32_e32 v238, v231
	v_mov_b32_e32 v239, v230
	v_mov_b32_e32 v240, v229
	v_mov_b32_e32 v241, v227
	v_mov_b32_e32 v242, v225
	v_mov_b32_e32 v243, v224
	v_mov_b32_e32 v244, v232
	v_mov_b32_e32 v245, v135
	v_mov_b32_e32 v246, v234
	v_mov_b32_e32 v247, v138
	v_mov_b32_e32 v248, v233
	v_mov_b32_e32 v249, v137
	v_mov_b32_e32 v250, v211
	v_mov_b32_e32 v251, v134
	s_mov_b32 vcc_lo, 0x55555555
	s_mov_b32 vcc_hi, 0x55555555
	s_mov_b32 s4, 0x33333333
	s_mov_b32 s5, 0x33333333
	s_mov_b32 s6, 0x0f0f0f0f
	s_mov_b32 s7, 0x0f0f0f0f
	s_mov_b32 s64, 0x00ff00ff
	s_mov_b32 s65, 0x00ff00ff
	s_waitcnt vmcnt(31)
	v_pk_mul_f32 v[252:253], v[236:237], v[124:125] op_sel_hi:[1,0]
	v_pk_mul_f32 v[254:255], v[244:245], v[124:125] op_sel_hi:[1,0]
	v_pk_fma_f32 v[252:253], v[238:239], v[124:125], v[252:253] op_sel:[0,1,0]
	v_pk_fma_f32 v[254:255], v[246:247], v[124:125], v[254:255] op_sel:[0,1,0]
	v_pk_fma_f32 v[252:253], v[240:241], v[126:127], v[252:253] op_sel_hi:[1,0,1]
	v_pk_fma_f32 v[254:255], v[248:249], v[126:127], v[254:255] op_sel_hi:[1,0,1]
	v_pk_fma_f32 v[252:253], v[242:243], v[126:127], v[252:253] op_sel:[0,1,0]
	v_pk_fma_f32 v[254:255], v[250:251], v[126:127], v[254:255] op_sel:[0,1,0]
	s_waitcnt vmcnt(30)
	v_pk_mul_f32 v[140:141], v[236:237], v[120:121] op_sel_hi:[1,0]
	v_pk_mul_f32 v[142:143], v[244:245], v[120:121] op_sel_hi:[1,0]
	v_pk_fma_f32 v[140:141], v[238:239], v[120:121], v[140:141] op_sel:[0,1,0]
	v_pk_fma_f32 v[142:143], v[246:247], v[120:121], v[142:143] op_sel:[0,1,0]
	v_pk_fma_f32 v[140:141], v[240:241], v[122:123], v[140:141] op_sel_hi:[1,0,1]
	v_pk_fma_f32 v[142:143], v[248:249], v[122:123], v[142:143] op_sel_hi:[1,0,1]
	v_pk_fma_f32 v[140:141], v[242:243], v[122:123], v[140:141] op_sel:[0,1,0]
	v_pk_fma_f32 v[142:143], v[250:251], v[122:123], v[142:143] op_sel:[0,1,0]
	v_add_f32_dpp v124, v252, v252 quad_perm:[1,0,3,2] row_mask:0xf bank_mask:0xf
	v_add_f32_dpp v125, v253, v253 quad_perm:[1,0,3,2] row_mask:0xf bank_mask:0xf
	v_add_f32_dpp v126, v254, v254 quad_perm:[1,0,3,2] row_mask:0xf bank_mask:0xf
	v_add_f32_dpp v127, v255, v255 quad_perm:[1,0,3,2] row_mask:0xf bank_mask:0xf
	v_cndmask_b32_e32 v124, v126, v124, vcc
	v_cndmask_b32_e32 v125, v127, v125, vcc
	s_waitcnt vmcnt(29)
	v_pk_mul_f32 v[252:253], v[236:237], v[116:117] op_sel_hi:[1,0]
	v_pk_mul_f32 v[254:255], v[244:245], v[116:117] op_sel_hi:[1,0]
	v_pk_fma_f32 v[252:253], v[238:239], v[116:117], v[252:253] op_sel:[0,1,0]
	v_pk_fma_f32 v[254:255], v[246:247], v[116:117], v[254:255] op_sel:[0,1,0]
	v_pk_fma_f32 v[252:253], v[240:241], v[118:119], v[252:253] op_sel_hi:[1,0,1]
	v_pk_fma_f32 v[254:255], v[248:249], v[118:119], v[254:255] op_sel_hi:[1,0,1]
	v_pk_fma_f32 v[252:253], v[242:243], v[118:119], v[252:253] op_sel:[0,1,0]
	v_pk_fma_f32 v[254:255], v[250:251], v[118:119], v[254:255] op_sel:[0,1,0]
	v_add_f32_dpp v120, v140, v140 quad_perm:[1,0,3,2] row_mask:0xf bank_mask:0xf
	v_add_f32_dpp v121, v141, v141 quad_perm:[1,0,3,2] row_mask:0xf bank_mask:0xf
	v_add_f32_dpp v122, v142, v142 quad_perm:[1,0,3,2] row_mask:0xf bank_mask:0xf
	v_add_f32_dpp v123, v143, v143 quad_perm:[1,0,3,2] row_mask:0xf bank_mask:0xf
	v_cndmask_b32_e32 v120, v122, v120, vcc
	v_cndmask_b32_e32 v121, v123, v121, vcc
	v_add_f32_dpp v126, v124, v124 quad_perm:[2,3,0,1] row_mask:0xf bank_mask:0xf
	v_add_f32_dpp v127, v125, v125 quad_perm:[2,3,0,1] row_mask:0xf bank_mask:0xf
	v_cndmask_b32_e64 v124, v127, v126, s[4:5]
	s_waitcnt vmcnt(28)
	v_pk_mul_f32 v[140:141], v[236:237], v[112:113] op_sel_hi:[1,0]
	v_pk_mul_f32 v[142:143], v[244:245], v[112:113] op_sel_hi:[1,0]
	v_pk_fma_f32 v[140:141], v[238:239], v[112:113], v[140:141] op_sel:[0,1,0]
	v_pk_fma_f32 v[142:143], v[246:247], v[112:113], v[142:143] op_sel:[0,1,0]
	v_pk_fma_f32 v[140:141], v[240:241], v[114:115], v[140:141] op_sel_hi:[1,0,1]
	v_pk_fma_f32 v[142:143], v[248:249], v[114:115], v[142:143] op_sel_hi:[1,0,1]
	v_pk_fma_f32 v[140:141], v[242:243], v[114:115], v[140:141] op_sel:[0,1,0]
	v_pk_fma_f32 v[142:143], v[250:251], v[114:115], v[142:143] op_sel:[0,1,0]
	v_add_f32_dpp v116, v252, v252 quad_perm:[1,0,3,2] row_mask:0xf bank_mask:0xf
	v_add_f32_dpp v117, v253, v253 quad_perm:[1,0,3,2] row_mask:0xf bank_mask:0xf
	v_add_f32_dpp v118, v254, v254 quad_perm:[1,0,3,2] row_mask:0xf bank_mask:0xf
	v_add_f32_dpp v119, v255, v255 quad_perm:[1,0,3,2] row_mask:0xf bank_mask:0xf
	v_cndmask_b32_e32 v116, v118, v116, vcc
	v_cndmask_b32_e32 v117, v119, v117, vcc
	v_add_f32_dpp v122, v120, v120 quad_perm:[2,3,0,1] row_mask:0xf bank_mask:0xf
	v_add_f32_dpp v123, v121, v121 quad_perm:[2,3,0,1] row_mask:0xf bank_mask:0xf
	v_cndmask_b32_e64 v120, v123, v122, s[4:5]
	v_cndmask_b32_e64 v125, v120, v124, s[6:7]
	v_cndmask_b32_e64 v126, v124, v120, s[6:7]
	s_waitcnt vmcnt(27)
	v_pk_mul_f32 v[252:253], v[236:237], v[108:109] op_sel_hi:[1,0]
	v_pk_mul_f32 v[254:255], v[244:245], v[108:109] op_sel_hi:[1,0]
	v_pk_fma_f32 v[252:253], v[238:239], v[108:109], v[252:253] op_sel:[0,1,0]
	v_pk_fma_f32 v[254:255], v[246:247], v[108:109], v[254:255] op_sel:[0,1,0]
	v_pk_fma_f32 v[252:253], v[240:241], v[110:111], v[252:253] op_sel_hi:[1,0,1]
	v_pk_fma_f32 v[254:255], v[248:249], v[110:111], v[254:255] op_sel_hi:[1,0,1]
	v_pk_fma_f32 v[252:253], v[242:243], v[110:111], v[252:253] op_sel:[0,1,0]
	v_pk_fma_f32 v[254:255], v[250:251], v[110:111], v[254:255] op_sel:[0,1,0]
	v_add_f32_dpp v124, v126, v125 row_ror:4 row_mask:0xf bank_mask:0xf
	v_add_f32_dpp v112, v140, v140 quad_perm:[1,0,3,2] row_mask:0xf bank_mask:0xf
	v_add_f32_dpp v113, v141, v141 quad_perm:[1,0,3,2] row_mask:0xf bank_mask:0xf
	v_add_f32_dpp v114, v142, v142 quad_perm:[1,0,3,2] row_mask:0xf bank_mask:0xf
	v_add_f32_dpp v115, v143, v143 quad_perm:[1,0,3,2] row_mask:0xf bank_mask:0xf
	v_cndmask_b32_e32 v112, v114, v112, vcc
	v_cndmask_b32_e32 v113, v115, v113, vcc
	v_add_f32_dpp v118, v116, v116 quad_perm:[2,3,0,1] row_mask:0xf bank_mask:0xf
	v_add_f32_dpp v119, v117, v117 quad_perm:[2,3,0,1] row_mask:0xf bank_mask:0xf
	v_cndmask_b32_e64 v116, v119, v118, s[4:5]
	s_waitcnt vmcnt(26)
	v_pk_mul_f32 v[140:141], v[236:237], v[104:105] op_sel_hi:[1,0]
	v_pk_mul_f32 v[142:143], v[244:245], v[104:105] op_sel_hi:[1,0]
	v_pk_fma_f32 v[140:141], v[238:239], v[104:105], v[140:141] op_sel:[0,1,0]
	v_pk_fma_f32 v[142:143], v[246:247], v[104:105], v[142:143] op_sel:[0,1,0]
	v_pk_fma_f32 v[140:141], v[240:241], v[106:107], v[140:141] op_sel_hi:[1,0,1]
	v_pk_fma_f32 v[142:143], v[248:249], v[106:107], v[142:143] op_sel_hi:[1,0,1]
	v_pk_fma_f32 v[140:141], v[242:243], v[106:107], v[140:141] op_sel:[0,1,0]
	v_pk_fma_f32 v[142:143], v[250:251], v[106:107], v[142:143] op_sel:[0,1,0]
	v_add_f32_dpp v108, v252, v252 quad_perm:[1,0,3,2] row_mask:0xf bank_mask:0xf
	v_add_f32_dpp v109, v253, v253 quad_perm:[1,0,3,2] row_mask:0xf bank_mask:0xf
	v_add_f32_dpp v110, v254, v254 quad_perm:[1,0,3,2] row_mask:0xf bank_mask:0xf
	v_add_f32_dpp v111, v255, v255 quad_perm:[1,0,3,2] row_mask:0xf bank_mask:0xf
	v_cndmask_b32_e32 v108, v110, v108, vcc
	v_cndmask_b32_e32 v109, v111, v109, vcc
	v_add_f32_dpp v114, v112, v112 quad_perm:[2,3,0,1] row_mask:0xf bank_mask:0xf
	v_add_f32_dpp v115, v113, v113 quad_perm:[2,3,0,1] row_mask:0xf bank_mask:0xf
	v_cndmask_b32_e64 v112, v115, v114, s[4:5]
	v_cndmask_b32_e64 v117, v112, v116, s[6:7]
	v_cndmask_b32_e64 v118, v116, v112, s[6:7]
	s_waitcnt vmcnt(25)
	v_pk_mul_f32 v[252:253], v[236:237], v[100:101] op_sel_hi:[1,0]
	v_pk_mul_f32 v[254:255], v[244:245], v[100:101] op_sel_hi:[1,0]
	v_pk_fma_f32 v[252:253], v[238:239], v[100:101], v[252:253] op_sel:[0,1,0]
	v_pk_fma_f32 v[254:255], v[246:247], v[100:101], v[254:255] op_sel:[0,1,0]
	v_pk_fma_f32 v[252:253], v[240:241], v[102:103], v[252:253] op_sel_hi:[1,0,1]
	v_pk_fma_f32 v[254:255], v[248:249], v[102:103], v[254:255] op_sel_hi:[1,0,1]
	v_pk_fma_f32 v[252:253], v[242:243], v[102:103], v[252:253] op_sel:[0,1,0]
	v_pk_fma_f32 v[254:255], v[250:251], v[102:103], v[254:255] op_sel:[0,1,0]
	v_add_f32_dpp v116, v118, v117 row_ror:4 row_mask:0xf bank_mask:0xf
	v_cndmask_b32_e64 v125, v116, v124, s[64:65]
	v_cndmask_b32_e64 v126, v124, v116, s[64:65]
	v_add_f32_dpp v104, v140, v140 quad_perm:[1,0,3,2] row_mask:0xf bank_mask:0xf
	v_add_f32_dpp v105, v141, v141 quad_perm:[1,0,3,2] row_mask:0xf bank_mask:0xf
	v_add_f32_dpp v106, v142, v142 quad_perm:[1,0,3,2] row_mask:0xf bank_mask:0xf
	v_add_f32_dpp v107, v143, v143 quad_perm:[1,0,3,2] row_mask:0xf bank_mask:0xf
	v_cndmask_b32_e32 v104, v106, v104, vcc
	v_cndmask_b32_e32 v105, v107, v105, vcc
	v_add_f32_dpp v110, v108, v108 quad_perm:[2,3,0,1] row_mask:0xf bank_mask:0xf
	v_add_f32_dpp v111, v109, v109 quad_perm:[2,3,0,1] row_mask:0xf bank_mask:0xf
	v_cndmask_b32_e64 v108, v111, v110, s[4:5]
	s_waitcnt vmcnt(24)
	v_pk_mul_f32 v[140:141], v[236:237], v[96:97] op_sel_hi:[1,0]
	v_pk_mul_f32 v[142:143], v[244:245], v[96:97] op_sel_hi:[1,0]
	v_pk_fma_f32 v[140:141], v[238:239], v[96:97], v[140:141] op_sel:[0,1,0]
	v_pk_fma_f32 v[142:143], v[246:247], v[96:97], v[142:143] op_sel:[0,1,0]
	v_pk_fma_f32 v[140:141], v[240:241], v[98:99], v[140:141] op_sel_hi:[1,0,1]
	v_pk_fma_f32 v[142:143], v[248:249], v[98:99], v[142:143] op_sel_hi:[1,0,1]
	v_pk_fma_f32 v[140:141], v[242:243], v[98:99], v[140:141] op_sel:[0,1,0]
	v_pk_fma_f32 v[142:143], v[250:251], v[98:99], v[142:143] op_sel:[0,1,0]
	v_add_f32_dpp v124, v126, v125 row_ror:8 row_mask:0xf bank_mask:0xf
	v_add_f32_dpp v100, v252, v252 quad_perm:[1,0,3,2] row_mask:0xf bank_mask:0xf
	v_add_f32_dpp v101, v253, v253 quad_perm:[1,0,3,2] row_mask:0xf bank_mask:0xf
	v_add_f32_dpp v102, v254, v254 quad_perm:[1,0,3,2] row_mask:0xf bank_mask:0xf
	v_add_f32_dpp v103, v255, v255 quad_perm:[1,0,3,2] row_mask:0xf bank_mask:0xf
	v_cndmask_b32_e32 v100, v102, v100, vcc
	v_cndmask_b32_e32 v101, v103, v101, vcc
	v_add_f32_dpp v106, v104, v104 quad_perm:[2,3,0,1] row_mask:0xf bank_mask:0xf
	v_add_f32_dpp v107, v105, v105 quad_perm:[2,3,0,1] row_mask:0xf bank_mask:0xf
	v_cndmask_b32_e64 v104, v107, v106, s[4:5]
	v_cndmask_b32_e64 v109, v104, v108, s[6:7]
	v_cndmask_b32_e64 v110, v108, v104, s[6:7]
	s_waitcnt vmcnt(23)
	v_pk_mul_f32 v[252:253], v[236:237], v[92:93] op_sel_hi:[1,0]
	v_pk_mul_f32 v[254:255], v[244:245], v[92:93] op_sel_hi:[1,0]
	v_pk_fma_f32 v[252:253], v[238:239], v[92:93], v[252:253] op_sel:[0,1,0]
	v_pk_fma_f32 v[254:255], v[246:247], v[92:93], v[254:255] op_sel:[0,1,0]
	v_pk_fma_f32 v[252:253], v[240:241], v[94:95], v[252:253] op_sel_hi:[1,0,1]
	v_pk_fma_f32 v[254:255], v[248:249], v[94:95], v[254:255] op_sel_hi:[1,0,1]
	v_pk_fma_f32 v[252:253], v[242:243], v[94:95], v[252:253] op_sel:[0,1,0]
	v_pk_fma_f32 v[254:255], v[250:251], v[94:95], v[254:255] op_sel:[0,1,0]
	v_add_f32_dpp v108, v110, v109 row_ror:4 row_mask:0xf bank_mask:0xf
	v_add_f32_dpp v96, v140, v140 quad_perm:[1,0,3,2] row_mask:0xf bank_mask:0xf
	v_add_f32_dpp v97, v141, v141 quad_perm:[1,0,3,2] row_mask:0xf bank_mask:0xf
	v_add_f32_dpp v98, v142, v142 quad_perm:[1,0,3,2] row_mask:0xf bank_mask:0xf
	v_add_f32_dpp v99, v143, v143 quad_perm:[1,0,3,2] row_mask:0xf bank_mask:0xf
	v_cndmask_b32_e32 v96, v98, v96, vcc
	v_cndmask_b32_e32 v97, v99, v97, vcc
	v_add_f32_dpp v102, v100, v100 quad_perm:[2,3,0,1] row_mask:0xf bank_mask:0xf
	v_add_f32_dpp v103, v101, v101 quad_perm:[2,3,0,1] row_mask:0xf bank_mask:0xf
	v_cndmask_b32_e64 v100, v103, v102, s[4:5]
	s_waitcnt vmcnt(22)
	v_pk_mul_f32 v[140:141], v[236:237], v[88:89] op_sel_hi:[1,0]
	v_pk_mul_f32 v[142:143], v[244:245], v[88:89] op_sel_hi:[1,0]
	v_pk_fma_f32 v[140:141], v[238:239], v[88:89], v[140:141] op_sel:[0,1,0]
	v_pk_fma_f32 v[142:143], v[246:247], v[88:89], v[142:143] op_sel:[0,1,0]
	v_pk_fma_f32 v[140:141], v[240:241], v[90:91], v[140:141] op_sel_hi:[1,0,1]
	v_pk_fma_f32 v[142:143], v[248:249], v[90:91], v[142:143] op_sel_hi:[1,0,1]
	v_pk_fma_f32 v[140:141], v[242:243], v[90:91], v[140:141] op_sel:[0,1,0]
	v_pk_fma_f32 v[142:143], v[250:251], v[90:91], v[142:143] op_sel:[0,1,0]
	v_add_f32_dpp v92, v252, v252 quad_perm:[1,0,3,2] row_mask:0xf bank_mask:0xf
	v_add_f32_dpp v93, v253, v253 quad_perm:[1,0,3,2] row_mask:0xf bank_mask:0xf
	v_add_f32_dpp v94, v254, v254 quad_perm:[1,0,3,2] row_mask:0xf bank_mask:0xf
	v_add_f32_dpp v95, v255, v255 quad_perm:[1,0,3,2] row_mask:0xf bank_mask:0xf
	v_cndmask_b32_e32 v92, v94, v92, vcc
	v_cndmask_b32_e32 v93, v95, v93, vcc
	v_add_f32_dpp v98, v96, v96 quad_perm:[2,3,0,1] row_mask:0xf bank_mask:0xf
	v_add_f32_dpp v99, v97, v97 quad_perm:[2,3,0,1] row_mask:0xf bank_mask:0xf
	v_cndmask_b32_e64 v96, v99, v98, s[4:5]
	v_cndmask_b32_e64 v101, v96, v100, s[6:7]
	v_cndmask_b32_e64 v102, v100, v96, s[6:7]
	s_waitcnt vmcnt(21)
	v_pk_mul_f32 v[252:253], v[236:237], v[84:85] op_sel_hi:[1,0]
	v_pk_mul_f32 v[254:255], v[244:245], v[84:85] op_sel_hi:[1,0]
	v_pk_fma_f32 v[252:253], v[238:239], v[84:85], v[252:253] op_sel:[0,1,0]
	v_pk_fma_f32 v[254:255], v[246:247], v[84:85], v[254:255] op_sel:[0,1,0]
	v_pk_fma_f32 v[252:253], v[240:241], v[86:87], v[252:253] op_sel_hi:[1,0,1]
	v_pk_fma_f32 v[254:255], v[248:249], v[86:87], v[254:255] op_sel_hi:[1,0,1]
	v_pk_fma_f32 v[252:253], v[242:243], v[86:87], v[252:253] op_sel:[0,1,0]
	v_pk_fma_f32 v[254:255], v[250:251], v[86:87], v[254:255] op_sel:[0,1,0]
	v_add_f32_dpp v100, v102, v101 row_ror:4 row_mask:0xf bank_mask:0xf
	v_cndmask_b32_e64 v109, v100, v108, s[64:65]
	v_cndmask_b32_e64 v110, v108, v100, s[64:65]
	v_add_f32_dpp v88, v140, v140 quad_perm:[1,0,3,2] row_mask:0xf bank_mask:0xf
	v_add_f32_dpp v89, v141, v141 quad_perm:[1,0,3,2] row_mask:0xf bank_mask:0xf
	v_add_f32_dpp v90, v142, v142 quad_perm:[1,0,3,2] row_mask:0xf bank_mask:0xf
	v_add_f32_dpp v91, v143, v143 quad_perm:[1,0,3,2] row_mask:0xf bank_mask:0xf
	v_cndmask_b32_e32 v88, v90, v88, vcc
	v_cndmask_b32_e32 v89, v91, v89, vcc
	v_add_f32_dpp v94, v92, v92 quad_perm:[2,3,0,1] row_mask:0xf bank_mask:0xf
	v_add_f32_dpp v95, v93, v93 quad_perm:[2,3,0,1] row_mask:0xf bank_mask:0xf
	v_cndmask_b32_e64 v92, v95, v94, s[4:5]
	s_waitcnt vmcnt(20)
	v_pk_mul_f32 v[140:141], v[236:237], v[80:81] op_sel_hi:[1,0]
	v_pk_mul_f32 v[142:143], v[244:245], v[80:81] op_sel_hi:[1,0]
	v_pk_fma_f32 v[140:141], v[238:239], v[80:81], v[140:141] op_sel:[0,1,0]
	v_pk_fma_f32 v[142:143], v[246:247], v[80:81], v[142:143] op_sel:[0,1,0]
	v_pk_fma_f32 v[140:141], v[240:241], v[82:83], v[140:141] op_sel_hi:[1,0,1]
	v_pk_fma_f32 v[142:143], v[248:249], v[82:83], v[142:143] op_sel_hi:[1,0,1]
	v_pk_fma_f32 v[140:141], v[242:243], v[82:83], v[140:141] op_sel:[0,1,0]
	v_pk_fma_f32 v[142:143], v[250:251], v[82:83], v[142:143] op_sel:[0,1,0]
	v_add_f32_dpp v108, v110, v109 row_ror:8 row_mask:0xf bank_mask:0xf
	v_add_f32_dpp v84, v252, v252 quad_perm:[1,0,3,2] row_mask:0xf bank_mask:0xf
	v_add_f32_dpp v85, v253, v253 quad_perm:[1,0,3,2] row_mask:0xf bank_mask:0xf
	v_add_f32_dpp v86, v254, v254 quad_perm:[1,0,3,2] row_mask:0xf bank_mask:0xf
	v_add_f32_dpp v87, v255, v255 quad_perm:[1,0,3,2] row_mask:0xf bank_mask:0xf
	v_cndmask_b32_e32 v84, v86, v84, vcc
	v_cndmask_b32_e32 v85, v87, v85, vcc
	v_add_f32_dpp v90, v88, v88 quad_perm:[2,3,0,1] row_mask:0xf bank_mask:0xf
	v_add_f32_dpp v91, v89, v89 quad_perm:[2,3,0,1] row_mask:0xf bank_mask:0xf
	v_cndmask_b32_e64 v88, v91, v90, s[4:5]
	v_cndmask_b32_e64 v93, v88, v92, s[6:7]
	v_cndmask_b32_e64 v94, v92, v88, s[6:7]
	s_waitcnt vmcnt(19)
	v_pk_mul_f32 v[252:253], v[236:237], v[76:77] op_sel_hi:[1,0]
	v_pk_mul_f32 v[254:255], v[244:245], v[76:77] op_sel_hi:[1,0]
	v_pk_fma_f32 v[252:253], v[238:239], v[76:77], v[252:253] op_sel:[0,1,0]
	v_pk_fma_f32 v[254:255], v[246:247], v[76:77], v[254:255] op_sel:[0,1,0]
	v_pk_fma_f32 v[252:253], v[240:241], v[78:79], v[252:253] op_sel_hi:[1,0,1]
	v_pk_fma_f32 v[254:255], v[248:249], v[78:79], v[254:255] op_sel_hi:[1,0,1]
	v_pk_fma_f32 v[252:253], v[242:243], v[78:79], v[252:253] op_sel:[0,1,0]
	v_pk_fma_f32 v[254:255], v[250:251], v[78:79], v[254:255] op_sel:[0,1,0]
	v_permlane16_swap_b32_e32 v124, v108
	v_add_f32_e32 v124, v124, v108
	v_add_f32_dpp v92, v94, v93 row_ror:4 row_mask:0xf bank_mask:0xf
	v_add_f32_dpp v80, v140, v140 quad_perm:[1,0,3,2] row_mask:0xf bank_mask:0xf
	v_add_f32_dpp v81, v141, v141 quad_perm:[1,0,3,2] row_mask:0xf bank_mask:0xf
	v_add_f32_dpp v82, v142, v142 quad_perm:[1,0,3,2] row_mask:0xf bank_mask:0xf
	v_add_f32_dpp v83, v143, v143 quad_perm:[1,0,3,2] row_mask:0xf bank_mask:0xf
	v_cndmask_b32_e32 v80, v82, v80, vcc
	v_cndmask_b32_e32 v81, v83, v81, vcc
	v_add_f32_dpp v86, v84, v84 quad_perm:[2,3,0,1] row_mask:0xf bank_mask:0xf
	v_add_f32_dpp v87, v85, v85 quad_perm:[2,3,0,1] row_mask:0xf bank_mask:0xf
	v_cndmask_b32_e64 v84, v87, v86, s[4:5]
	s_waitcnt vmcnt(18)
	v_pk_mul_f32 v[140:141], v[236:237], v[72:73] op_sel_hi:[1,0]
	v_pk_mul_f32 v[142:143], v[244:245], v[72:73] op_sel_hi:[1,0]
	v_pk_fma_f32 v[140:141], v[238:239], v[72:73], v[140:141] op_sel:[0,1,0]
	v_pk_fma_f32 v[142:143], v[246:247], v[72:73], v[142:143] op_sel:[0,1,0]
	v_pk_fma_f32 v[140:141], v[240:241], v[74:75], v[140:141] op_sel_hi:[1,0,1]
	v_pk_fma_f32 v[142:143], v[248:249], v[74:75], v[142:143] op_sel_hi:[1,0,1]
	v_pk_fma_f32 v[140:141], v[242:243], v[74:75], v[140:141] op_sel:[0,1,0]
	v_pk_fma_f32 v[142:143], v[250:251], v[74:75], v[142:143] op_sel:[0,1,0]
	v_add_f32_dpp v76, v252, v252 quad_perm:[1,0,3,2] row_mask:0xf bank_mask:0xf
	v_add_f32_dpp v77, v253, v253 quad_perm:[1,0,3,2] row_mask:0xf bank_mask:0xf
	v_add_f32_dpp v78, v254, v254 quad_perm:[1,0,3,2] row_mask:0xf bank_mask:0xf
	v_add_f32_dpp v79, v255, v255 quad_perm:[1,0,3,2] row_mask:0xf bank_mask:0xf
	v_cndmask_b32_e32 v76, v78, v76, vcc
	v_cndmask_b32_e32 v77, v79, v77, vcc
	v_add_f32_dpp v82, v80, v80 quad_perm:[2,3,0,1] row_mask:0xf bank_mask:0xf
	v_add_f32_dpp v83, v81, v81 quad_perm:[2,3,0,1] row_mask:0xf bank_mask:0xf
	v_cndmask_b32_e64 v80, v83, v82, s[4:5]
	v_cndmask_b32_e64 v85, v80, v84, s[6:7]
	v_cndmask_b32_e64 v86, v84, v80, s[6:7]
	s_waitcnt vmcnt(17)
	v_pk_mul_f32 v[252:253], v[236:237], v[68:69] op_sel_hi:[1,0]
	v_pk_mul_f32 v[254:255], v[244:245], v[68:69] op_sel_hi:[1,0]
	v_pk_fma_f32 v[252:253], v[238:239], v[68:69], v[252:253] op_sel:[0,1,0]
	v_pk_fma_f32 v[254:255], v[246:247], v[68:69], v[254:255] op_sel:[0,1,0]
	v_pk_fma_f32 v[252:253], v[240:241], v[70:71], v[252:253] op_sel_hi:[1,0,1]
	v_pk_fma_f32 v[254:255], v[248:249], v[70:71], v[254:255] op_sel_hi:[1,0,1]
	v_pk_fma_f32 v[252:253], v[242:243], v[70:71], v[252:253] op_sel:[0,1,0]
	v_pk_fma_f32 v[254:255], v[250:251], v[70:71], v[254:255] op_sel:[0,1,0]
	v_add_f32_dpp v84, v86, v85 row_ror:4 row_mask:0xf bank_mask:0xf
	v_cndmask_b32_e64 v93, v84, v92, s[64:65]
	v_cndmask_b32_e64 v94, v92, v84, s[64:65]
	v_add_f32_dpp v72, v140, v140 quad_perm:[1,0,3,2] row_mask:0xf bank_mask:0xf
	v_add_f32_dpp v73, v141, v141 quad_perm:[1,0,3,2] row_mask:0xf bank_mask:0xf
	v_add_f32_dpp v74, v142, v142 quad_perm:[1,0,3,2] row_mask:0xf bank_mask:0xf
	v_add_f32_dpp v75, v143, v143 quad_perm:[1,0,3,2] row_mask:0xf bank_mask:0xf
	v_cndmask_b32_e32 v72, v74, v72, vcc
	v_cndmask_b32_e32 v73, v75, v73, vcc
	v_add_f32_dpp v78, v76, v76 quad_perm:[2,3,0,1] row_mask:0xf bank_mask:0xf
	v_add_f32_dpp v79, v77, v77 quad_perm:[2,3,0,1] row_mask:0xf bank_mask:0xf
	v_cndmask_b32_e64 v76, v79, v78, s[4:5]
	s_waitcnt vmcnt(16)
	v_pk_mul_f32 v[140:141], v[236:237], v[64:65] op_sel_hi:[1,0]
	v_pk_mul_f32 v[142:143], v[244:245], v[64:65] op_sel_hi:[1,0]
	v_pk_fma_f32 v[140:141], v[238:239], v[64:65], v[140:141] op_sel:[0,1,0]
	v_pk_fma_f32 v[142:143], v[246:247], v[64:65], v[142:143] op_sel:[0,1,0]
	v_pk_fma_f32 v[140:141], v[240:241], v[66:67], v[140:141] op_sel_hi:[1,0,1]
	v_pk_fma_f32 v[142:143], v[248:249], v[66:67], v[142:143] op_sel_hi:[1,0,1]
	v_pk_fma_f32 v[140:141], v[242:243], v[66:67], v[140:141] op_sel:[0,1,0]
	v_pk_fma_f32 v[142:143], v[250:251], v[66:67], v[142:143] op_sel:[0,1,0]
	v_add_f32_dpp v92, v94, v93 row_ror:8 row_mask:0xf bank_mask:0xf
	v_add_f32_dpp v68, v252, v252 quad_perm:[1,0,3,2] row_mask:0xf bank_mask:0xf
	v_add_f32_dpp v69, v253, v253 quad_perm:[1,0,3,2] row_mask:0xf bank_mask:0xf
	v_add_f32_dpp v70, v254, v254 quad_perm:[1,0,3,2] row_mask:0xf bank_mask:0xf
	v_add_f32_dpp v71, v255, v255 quad_perm:[1,0,3,2] row_mask:0xf bank_mask:0xf
	v_cndmask_b32_e32 v68, v70, v68, vcc
	v_cndmask_b32_e32 v69, v71, v69, vcc
	v_add_f32_dpp v74, v72, v72 quad_perm:[2,3,0,1] row_mask:0xf bank_mask:0xf
	v_add_f32_dpp v75, v73, v73 quad_perm:[2,3,0,1] row_mask:0xf bank_mask:0xf
	v_cndmask_b32_e64 v72, v75, v74, s[4:5]
	v_cndmask_b32_e64 v77, v72, v76, s[6:7]
	v_cndmask_b32_e64 v78, v76, v72, s[6:7]
	s_waitcnt vmcnt(15)
	v_pk_mul_f32 v[252:253], v[236:237], v[60:61] op_sel_hi:[1,0]
	v_pk_mul_f32 v[254:255], v[244:245], v[60:61] op_sel_hi:[1,0]
	v_pk_fma_f32 v[252:253], v[238:239], v[60:61], v[252:253] op_sel:[0,1,0]
	v_pk_fma_f32 v[254:255], v[246:247], v[60:61], v[254:255] op_sel:[0,1,0]
	v_pk_fma_f32 v[252:253], v[240:241], v[62:63], v[252:253] op_sel_hi:[1,0,1]
	v_pk_fma_f32 v[254:255], v[248:249], v[62:63], v[254:255] op_sel_hi:[1,0,1]
	v_pk_fma_f32 v[252:253], v[242:243], v[62:63], v[252:253] op_sel:[0,1,0]
	v_pk_fma_f32 v[254:255], v[250:251], v[62:63], v[254:255] op_sel:[0,1,0]
	v_add_f32_dpp v76, v78, v77 row_ror:4 row_mask:0xf bank_mask:0xf
	v_add_f32_dpp v64, v140, v140 quad_perm:[1,0,3,2] row_mask:0xf bank_mask:0xf
	v_add_f32_dpp v65, v141, v141 quad_perm:[1,0,3,2] row_mask:0xf bank_mask:0xf
	v_add_f32_dpp v66, v142, v142 quad_perm:[1,0,3,2] row_mask:0xf bank_mask:0xf
	v_add_f32_dpp v67, v143, v143 quad_perm:[1,0,3,2] row_mask:0xf bank_mask:0xf
	v_cndmask_b32_e32 v64, v66, v64, vcc
	v_cndmask_b32_e32 v65, v67, v65, vcc
	v_add_f32_dpp v70, v68, v68 quad_perm:[2,3,0,1] row_mask:0xf bank_mask:0xf
	v_add_f32_dpp v71, v69, v69 quad_perm:[2,3,0,1] row_mask:0xf bank_mask:0xf
	v_cndmask_b32_e64 v68, v71, v70, s[4:5]
	s_waitcnt vmcnt(14)
	v_pk_mul_f32 v[140:141], v[236:237], v[56:57] op_sel_hi:[1,0]
	v_pk_mul_f32 v[142:143], v[244:245], v[56:57] op_sel_hi:[1,0]
	v_pk_fma_f32 v[140:141], v[238:239], v[56:57], v[140:141] op_sel:[0,1,0]
	v_pk_fma_f32 v[142:143], v[246:247], v[56:57], v[142:143] op_sel:[0,1,0]
	v_pk_fma_f32 v[140:141], v[240:241], v[58:59], v[140:141] op_sel_hi:[1,0,1]
	v_pk_fma_f32 v[142:143], v[248:249], v[58:59], v[142:143] op_sel_hi:[1,0,1]
	v_pk_fma_f32 v[140:141], v[242:243], v[58:59], v[140:141] op_sel:[0,1,0]
	v_pk_fma_f32 v[142:143], v[250:251], v[58:59], v[142:143] op_sel:[0,1,0]
	v_add_f32_dpp v60, v252, v252 quad_perm:[1,0,3,2] row_mask:0xf bank_mask:0xf
	v_add_f32_dpp v61, v253, v253 quad_perm:[1,0,3,2] row_mask:0xf bank_mask:0xf
	v_add_f32_dpp v62, v254, v254 quad_perm:[1,0,3,2] row_mask:0xf bank_mask:0xf
	v_add_f32_dpp v63, v255, v255 quad_perm:[1,0,3,2] row_mask:0xf bank_mask:0xf
	v_cndmask_b32_e32 v60, v62, v60, vcc
	v_cndmask_b32_e32 v61, v63, v61, vcc
	v_add_f32_dpp v66, v64, v64 quad_perm:[2,3,0,1] row_mask:0xf bank_mask:0xf
	v_add_f32_dpp v67, v65, v65 quad_perm:[2,3,0,1] row_mask:0xf bank_mask:0xf
	v_cndmask_b32_e64 v64, v67, v66, s[4:5]
	v_cndmask_b32_e64 v69, v64, v68, s[6:7]
	v_cndmask_b32_e64 v70, v68, v64, s[6:7]
	s_waitcnt vmcnt(13)
	v_pk_mul_f32 v[252:253], v[236:237], v[52:53] op_sel_hi:[1,0]
	v_pk_mul_f32 v[254:255], v[244:245], v[52:53] op_sel_hi:[1,0]
	v_pk_fma_f32 v[252:253], v[238:239], v[52:53], v[252:253] op_sel:[0,1,0]
	v_pk_fma_f32 v[254:255], v[246:247], v[52:53], v[254:255] op_sel:[0,1,0]
	v_pk_fma_f32 v[252:253], v[240:241], v[54:55], v[252:253] op_sel_hi:[1,0,1]
	v_pk_fma_f32 v[254:255], v[248:249], v[54:55], v[254:255] op_sel_hi:[1,0,1]
	v_pk_fma_f32 v[252:253], v[242:243], v[54:55], v[252:253] op_sel:[0,1,0]
	v_pk_fma_f32 v[254:255], v[250:251], v[54:55], v[254:255] op_sel:[0,1,0]
	v_add_f32_dpp v68, v70, v69 row_ror:4 row_mask:0xf bank_mask:0xf
	v_cndmask_b32_e64 v77, v68, v76, s[64:65]
	v_cndmask_b32_e64 v78, v76, v68, s[64:65]
	v_add_f32_dpp v56, v140, v140 quad_perm:[1,0,3,2] row_mask:0xf bank_mask:0xf
	v_add_f32_dpp v57, v141, v141 quad_perm:[1,0,3,2] row_mask:0xf bank_mask:0xf
	v_add_f32_dpp v58, v142, v142 quad_perm:[1,0,3,2] row_mask:0xf bank_mask:0xf
	v_add_f32_dpp v59, v143, v143 quad_perm:[1,0,3,2] row_mask:0xf bank_mask:0xf
	v_cndmask_b32_e32 v56, v58, v56, vcc
	v_cndmask_b32_e32 v57, v59, v57, vcc
	v_add_f32_dpp v62, v60, v60 quad_perm:[2,3,0,1] row_mask:0xf bank_mask:0xf
	v_add_f32_dpp v63, v61, v61 quad_perm:[2,3,0,1] row_mask:0xf bank_mask:0xf
	v_cndmask_b32_e64 v60, v63, v62, s[4:5]
	s_waitcnt vmcnt(12)
	v_pk_mul_f32 v[140:141], v[236:237], v[48:49] op_sel_hi:[1,0]
	v_pk_mul_f32 v[142:143], v[244:245], v[48:49] op_sel_hi:[1,0]
	v_pk_fma_f32 v[140:141], v[238:239], v[48:49], v[140:141] op_sel:[0,1,0]
	v_pk_fma_f32 v[142:143], v[246:247], v[48:49], v[142:143] op_sel:[0,1,0]
	v_pk_fma_f32 v[140:141], v[240:241], v[50:51], v[140:141] op_sel_hi:[1,0,1]
	v_pk_fma_f32 v[142:143], v[248:249], v[50:51], v[142:143] op_sel_hi:[1,0,1]
	v_pk_fma_f32 v[140:141], v[242:243], v[50:51], v[140:141] op_sel:[0,1,0]
	v_pk_fma_f32 v[142:143], v[250:251], v[50:51], v[142:143] op_sel:[0,1,0]
	v_add_f32_dpp v76, v78, v77 row_ror:8 row_mask:0xf bank_mask:0xf
	v_add_f32_dpp v52, v252, v252 quad_perm:[1,0,3,2] row_mask:0xf bank_mask:0xf
	v_add_f32_dpp v53, v253, v253 quad_perm:[1,0,3,2] row_mask:0xf bank_mask:0xf
	v_add_f32_dpp v54, v254, v254 quad_perm:[1,0,3,2] row_mask:0xf bank_mask:0xf
	v_add_f32_dpp v55, v255, v255 quad_perm:[1,0,3,2] row_mask:0xf bank_mask:0xf
	v_cndmask_b32_e32 v52, v54, v52, vcc
	v_cndmask_b32_e32 v53, v55, v53, vcc
	v_add_f32_dpp v58, v56, v56 quad_perm:[2,3,0,1] row_mask:0xf bank_mask:0xf
	v_add_f32_dpp v59, v57, v57 quad_perm:[2,3,0,1] row_mask:0xf bank_mask:0xf
	v_cndmask_b32_e64 v56, v59, v58, s[4:5]
	v_cndmask_b32_e64 v61, v56, v60, s[6:7]
	v_cndmask_b32_e64 v62, v60, v56, s[6:7]
	s_waitcnt vmcnt(11)
	v_pk_mul_f32 v[252:253], v[236:237], v[44:45] op_sel_hi:[1,0]
	v_pk_mul_f32 v[254:255], v[244:245], v[44:45] op_sel_hi:[1,0]
	v_pk_fma_f32 v[252:253], v[238:239], v[44:45], v[252:253] op_sel:[0,1,0]
	v_pk_fma_f32 v[254:255], v[246:247], v[44:45], v[254:255] op_sel:[0,1,0]
	v_pk_fma_f32 v[252:253], v[240:241], v[46:47], v[252:253] op_sel_hi:[1,0,1]
	v_pk_fma_f32 v[254:255], v[248:249], v[46:47], v[254:255] op_sel_hi:[1,0,1]
	v_pk_fma_f32 v[252:253], v[242:243], v[46:47], v[252:253] op_sel:[0,1,0]
	v_pk_fma_f32 v[254:255], v[250:251], v[46:47], v[254:255] op_sel:[0,1,0]
	v_permlane16_swap_b32_e32 v92, v76
	v_add_f32_e32 v92, v92, v76
	v_add_f32_dpp v60, v62, v61 row_ror:4 row_mask:0xf bank_mask:0xf
	v_add_f32_dpp v48, v140, v140 quad_perm:[1,0,3,2] row_mask:0xf bank_mask:0xf
	v_add_f32_dpp v49, v141, v141 quad_perm:[1,0,3,2] row_mask:0xf bank_mask:0xf
	v_add_f32_dpp v50, v142, v142 quad_perm:[1,0,3,2] row_mask:0xf bank_mask:0xf
	v_add_f32_dpp v51, v143, v143 quad_perm:[1,0,3,2] row_mask:0xf bank_mask:0xf
	v_cndmask_b32_e32 v48, v50, v48, vcc
	v_cndmask_b32_e32 v49, v51, v49, vcc
	v_add_f32_dpp v54, v52, v52 quad_perm:[2,3,0,1] row_mask:0xf bank_mask:0xf
	v_add_f32_dpp v55, v53, v53 quad_perm:[2,3,0,1] row_mask:0xf bank_mask:0xf
	v_cndmask_b32_e64 v52, v55, v54, s[4:5]
	s_waitcnt vmcnt(10)
	v_pk_mul_f32 v[140:141], v[236:237], v[40:41] op_sel_hi:[1,0]
	v_pk_mul_f32 v[142:143], v[244:245], v[40:41] op_sel_hi:[1,0]
	v_pk_fma_f32 v[140:141], v[238:239], v[40:41], v[140:141] op_sel:[0,1,0]
	v_pk_fma_f32 v[142:143], v[246:247], v[40:41], v[142:143] op_sel:[0,1,0]
	v_pk_fma_f32 v[140:141], v[240:241], v[42:43], v[140:141] op_sel_hi:[1,0,1]
	v_pk_fma_f32 v[142:143], v[248:249], v[42:43], v[142:143] op_sel_hi:[1,0,1]
	v_pk_fma_f32 v[140:141], v[242:243], v[42:43], v[140:141] op_sel:[0,1,0]
	v_pk_fma_f32 v[142:143], v[250:251], v[42:43], v[142:143] op_sel:[0,1,0]
	v_permlane32_swap_b32_e32 v124, v92
	v_add_f32_e32 v124, v124, v92
	ds_write_b32 v235, v124
	v_add_f32_dpp v44, v252, v252 quad_perm:[1,0,3,2] row_mask:0xf bank_mask:0xf
	v_add_f32_dpp v45, v253, v253 quad_perm:[1,0,3,2] row_mask:0xf bank_mask:0xf
	v_add_f32_dpp v46, v254, v254 quad_perm:[1,0,3,2] row_mask:0xf bank_mask:0xf
	v_add_f32_dpp v47, v255, v255 quad_perm:[1,0,3,2] row_mask:0xf bank_mask:0xf
	v_cndmask_b32_e32 v44, v46, v44, vcc
	v_cndmask_b32_e32 v45, v47, v45, vcc
	v_add_f32_dpp v50, v48, v48 quad_perm:[2,3,0,1] row_mask:0xf bank_mask:0xf
	v_add_f32_dpp v51, v49, v49 quad_perm:[2,3,0,1] row_mask:0xf bank_mask:0xf
	v_cndmask_b32_e64 v48, v51, v50, s[4:5]
	v_cndmask_b32_e64 v53, v48, v52, s[6:7]
	v_cndmask_b32_e64 v54, v52, v48, s[6:7]
	s_waitcnt vmcnt(9)
	v_pk_mul_f32 v[252:253], v[236:237], v[36:37] op_sel_hi:[1,0]
	v_pk_mul_f32 v[254:255], v[244:245], v[36:37] op_sel_hi:[1,0]
	v_pk_fma_f32 v[252:253], v[238:239], v[36:37], v[252:253] op_sel:[0,1,0]
	v_pk_fma_f32 v[254:255], v[246:247], v[36:37], v[254:255] op_sel:[0,1,0]
	v_pk_fma_f32 v[252:253], v[240:241], v[38:39], v[252:253] op_sel_hi:[1,0,1]
	v_pk_fma_f32 v[254:255], v[248:249], v[38:39], v[254:255] op_sel_hi:[1,0,1]
	v_pk_fma_f32 v[252:253], v[242:243], v[38:39], v[252:253] op_sel:[0,1,0]
	v_pk_fma_f32 v[254:255], v[250:251], v[38:39], v[254:255] op_sel:[0,1,0]
	v_add_f32_dpp v52, v54, v53 row_ror:4 row_mask:0xf bank_mask:0xf
	v_cndmask_b32_e64 v61, v52, v60, s[64:65]
	v_cndmask_b32_e64 v62, v60, v52, s[64:65]
	v_add_f32_dpp v40, v140, v140 quad_perm:[1,0,3,2] row_mask:0xf bank_mask:0xf
	v_add_f32_dpp v41, v141, v141 quad_perm:[1,0,3,2] row_mask:0xf bank_mask:0xf
	v_add_f32_dpp v42, v142, v142 quad_perm:[1,0,3,2] row_mask:0xf bank_mask:0xf
	v_add_f32_dpp v43, v143, v143 quad_perm:[1,0,3,2] row_mask:0xf bank_mask:0xf
	v_cndmask_b32_e32 v40, v42, v40, vcc
	v_cndmask_b32_e32 v41, v43, v41, vcc
	v_add_f32_dpp v46, v44, v44 quad_perm:[2,3,0,1] row_mask:0xf bank_mask:0xf
	v_add_f32_dpp v47, v45, v45 quad_perm:[2,3,0,1] row_mask:0xf bank_mask:0xf
	v_cndmask_b32_e64 v44, v47, v46, s[4:5]
	s_waitcnt vmcnt(8)
	v_pk_mul_f32 v[140:141], v[236:237], v[32:33] op_sel_hi:[1,0]
	v_pk_mul_f32 v[142:143], v[244:245], v[32:33] op_sel_hi:[1,0]
	v_pk_fma_f32 v[140:141], v[238:239], v[32:33], v[140:141] op_sel:[0,1,0]
	v_pk_fma_f32 v[142:143], v[246:247], v[32:33], v[142:143] op_sel:[0,1,0]
	v_pk_fma_f32 v[140:141], v[240:241], v[34:35], v[140:141] op_sel_hi:[1,0,1]
	v_pk_fma_f32 v[142:143], v[248:249], v[34:35], v[142:143] op_sel_hi:[1,0,1]
	v_pk_fma_f32 v[140:141], v[242:243], v[34:35], v[140:141] op_sel:[0,1,0]
	v_pk_fma_f32 v[142:143], v[250:251], v[34:35], v[142:143] op_sel:[0,1,0]
	v_add_f32_dpp v60, v62, v61 row_ror:8 row_mask:0xf bank_mask:0xf
	v_add_f32_dpp v36, v252, v252 quad_perm:[1,0,3,2] row_mask:0xf bank_mask:0xf
	v_add_f32_dpp v37, v253, v253 quad_perm:[1,0,3,2] row_mask:0xf bank_mask:0xf
	v_add_f32_dpp v38, v254, v254 quad_perm:[1,0,3,2] row_mask:0xf bank_mask:0xf
	v_add_f32_dpp v39, v255, v255 quad_perm:[1,0,3,2] row_mask:0xf bank_mask:0xf
	v_cndmask_b32_e32 v36, v38, v36, vcc
	v_cndmask_b32_e32 v37, v39, v37, vcc
	v_add_f32_dpp v42, v40, v40 quad_perm:[2,3,0,1] row_mask:0xf bank_mask:0xf
	v_add_f32_dpp v43, v41, v41 quad_perm:[2,3,0,1] row_mask:0xf bank_mask:0xf
	v_cndmask_b32_e64 v40, v43, v42, s[4:5]
	v_cndmask_b32_e64 v45, v40, v44, s[6:7]
	v_cndmask_b32_e64 v46, v44, v40, s[6:7]
	s_waitcnt vmcnt(7)
	v_pk_mul_f32 v[252:253], v[236:237], v[28:29] op_sel_hi:[1,0]
	v_pk_mul_f32 v[254:255], v[244:245], v[28:29] op_sel_hi:[1,0]
	v_pk_fma_f32 v[252:253], v[238:239], v[28:29], v[252:253] op_sel:[0,1,0]
	v_pk_fma_f32 v[254:255], v[246:247], v[28:29], v[254:255] op_sel:[0,1,0]
	v_pk_fma_f32 v[252:253], v[240:241], v[30:31], v[252:253] op_sel_hi:[1,0,1]
	v_pk_fma_f32 v[254:255], v[248:249], v[30:31], v[254:255] op_sel_hi:[1,0,1]
	v_pk_fma_f32 v[252:253], v[242:243], v[30:31], v[252:253] op_sel:[0,1,0]
	v_pk_fma_f32 v[254:255], v[250:251], v[30:31], v[254:255] op_sel:[0,1,0]
	v_add_f32_dpp v44, v46, v45 row_ror:4 row_mask:0xf bank_mask:0xf
	v_add_f32_dpp v32, v140, v140 quad_perm:[1,0,3,2] row_mask:0xf bank_mask:0xf
	v_add_f32_dpp v33, v141, v141 quad_perm:[1,0,3,2] row_mask:0xf bank_mask:0xf
	v_add_f32_dpp v34, v142, v142 quad_perm:[1,0,3,2] row_mask:0xf bank_mask:0xf
	v_add_f32_dpp v35, v143, v143 quad_perm:[1,0,3,2] row_mask:0xf bank_mask:0xf
	v_cndmask_b32_e32 v32, v34, v32, vcc
	v_cndmask_b32_e32 v33, v35, v33, vcc
	v_add_f32_dpp v38, v36, v36 quad_perm:[2,3,0,1] row_mask:0xf bank_mask:0xf
	v_add_f32_dpp v39, v37, v37 quad_perm:[2,3,0,1] row_mask:0xf bank_mask:0xf
	v_cndmask_b32_e64 v36, v39, v38, s[4:5]
	s_waitcnt vmcnt(6)
	v_pk_mul_f32 v[140:141], v[236:237], v[24:25] op_sel_hi:[1,0]
	v_pk_mul_f32 v[142:143], v[244:245], v[24:25] op_sel_hi:[1,0]
	v_pk_fma_f32 v[140:141], v[238:239], v[24:25], v[140:141] op_sel:[0,1,0]
	v_pk_fma_f32 v[142:143], v[246:247], v[24:25], v[142:143] op_sel:[0,1,0]
	v_pk_fma_f32 v[140:141], v[240:241], v[26:27], v[140:141] op_sel_hi:[1,0,1]
	v_pk_fma_f32 v[142:143], v[248:249], v[26:27], v[142:143] op_sel_hi:[1,0,1]
	v_pk_fma_f32 v[140:141], v[242:243], v[26:27], v[140:141] op_sel:[0,1,0]
	v_pk_fma_f32 v[142:143], v[250:251], v[26:27], v[142:143] op_sel:[0,1,0]
	v_add_f32_dpp v28, v252, v252 quad_perm:[1,0,3,2] row_mask:0xf bank_mask:0xf
	v_add_f32_dpp v29, v253, v253 quad_perm:[1,0,3,2] row_mask:0xf bank_mask:0xf
	v_add_f32_dpp v30, v254, v254 quad_perm:[1,0,3,2] row_mask:0xf bank_mask:0xf
	v_add_f32_dpp v31, v255, v255 quad_perm:[1,0,3,2] row_mask:0xf bank_mask:0xf
	v_cndmask_b32_e32 v28, v30, v28, vcc
	v_cndmask_b32_e32 v29, v31, v29, vcc
	v_add_f32_dpp v34, v32, v32 quad_perm:[2,3,0,1] row_mask:0xf bank_mask:0xf
	v_add_f32_dpp v35, v33, v33 quad_perm:[2,3,0,1] row_mask:0xf bank_mask:0xf
	v_cndmask_b32_e64 v32, v35, v34, s[4:5]
	v_cndmask_b32_e64 v37, v32, v36, s[6:7]
	v_cndmask_b32_e64 v38, v36, v32, s[6:7]
	s_waitcnt vmcnt(5)
	v_pk_mul_f32 v[252:253], v[236:237], v[20:21] op_sel_hi:[1,0]
	v_pk_mul_f32 v[254:255], v[244:245], v[20:21] op_sel_hi:[1,0]
	v_pk_fma_f32 v[252:253], v[238:239], v[20:21], v[252:253] op_sel:[0,1,0]
	v_pk_fma_f32 v[254:255], v[246:247], v[20:21], v[254:255] op_sel:[0,1,0]
	v_pk_fma_f32 v[252:253], v[240:241], v[22:23], v[252:253] op_sel_hi:[1,0,1]
	v_pk_fma_f32 v[254:255], v[248:249], v[22:23], v[254:255] op_sel_hi:[1,0,1]
	v_pk_fma_f32 v[252:253], v[242:243], v[22:23], v[252:253] op_sel:[0,1,0]
	v_pk_fma_f32 v[254:255], v[250:251], v[22:23], v[254:255] op_sel:[0,1,0]
	v_add_f32_dpp v36, v38, v37 row_ror:4 row_mask:0xf bank_mask:0xf
	v_cndmask_b32_e64 v45, v36, v44, s[64:65]
	v_cndmask_b32_e64 v46, v44, v36, s[64:65]
	v_add_f32_dpp v24, v140, v140 quad_perm:[1,0,3,2] row_mask:0xf bank_mask:0xf
	v_add_f32_dpp v25, v141, v141 quad_perm:[1,0,3,2] row_mask:0xf bank_mask:0xf
	v_add_f32_dpp v26, v142, v142 quad_perm:[1,0,3,2] row_mask:0xf bank_mask:0xf
	v_add_f32_dpp v27, v143, v143 quad_perm:[1,0,3,2] row_mask:0xf bank_mask:0xf
	v_cndmask_b32_e32 v24, v26, v24, vcc
	v_cndmask_b32_e32 v25, v27, v25, vcc
	v_add_f32_dpp v30, v28, v28 quad_perm:[2,3,0,1] row_mask:0xf bank_mask:0xf
	v_add_f32_dpp v31, v29, v29 quad_perm:[2,3,0,1] row_mask:0xf bank_mask:0xf
	v_cndmask_b32_e64 v28, v31, v30, s[4:5]
	s_waitcnt vmcnt(4)
	v_pk_mul_f32 v[140:141], v[236:237], v[16:17] op_sel_hi:[1,0]
	v_pk_mul_f32 v[142:143], v[244:245], v[16:17] op_sel_hi:[1,0]
	v_pk_fma_f32 v[140:141], v[238:239], v[16:17], v[140:141] op_sel:[0,1,0]
	v_pk_fma_f32 v[142:143], v[246:247], v[16:17], v[142:143] op_sel:[0,1,0]
	v_pk_fma_f32 v[140:141], v[240:241], v[18:19], v[140:141] op_sel_hi:[1,0,1]
	v_pk_fma_f32 v[142:143], v[248:249], v[18:19], v[142:143] op_sel_hi:[1,0,1]
	v_pk_fma_f32 v[140:141], v[242:243], v[18:19], v[140:141] op_sel:[0,1,0]
	v_pk_fma_f32 v[142:143], v[250:251], v[18:19], v[142:143] op_sel:[0,1,0]
	v_add_f32_dpp v44, v46, v45 row_ror:8 row_mask:0xf bank_mask:0xf
	v_add_f32_dpp v20, v252, v252 quad_perm:[1,0,3,2] row_mask:0xf bank_mask:0xf
	v_add_f32_dpp v21, v253, v253 quad_perm:[1,0,3,2] row_mask:0xf bank_mask:0xf
	v_add_f32_dpp v22, v254, v254 quad_perm:[1,0,3,2] row_mask:0xf bank_mask:0xf
	v_add_f32_dpp v23, v255, v255 quad_perm:[1,0,3,2] row_mask:0xf bank_mask:0xf
	v_cndmask_b32_e32 v20, v22, v20, vcc
	v_cndmask_b32_e32 v21, v23, v21, vcc
	v_add_f32_dpp v26, v24, v24 quad_perm:[2,3,0,1] row_mask:0xf bank_mask:0xf
	v_add_f32_dpp v27, v25, v25 quad_perm:[2,3,0,1] row_mask:0xf bank_mask:0xf
	v_cndmask_b32_e64 v24, v27, v26, s[4:5]
	v_cndmask_b32_e64 v29, v24, v28, s[6:7]
	v_cndmask_b32_e64 v30, v28, v24, s[6:7]
	s_waitcnt vmcnt(3)
	v_pk_mul_f32 v[252:253], v[236:237], v[12:13] op_sel_hi:[1,0]
	v_pk_mul_f32 v[254:255], v[244:245], v[12:13] op_sel_hi:[1,0]
	v_pk_fma_f32 v[252:253], v[238:239], v[12:13], v[252:253] op_sel:[0,1,0]
	v_pk_fma_f32 v[254:255], v[246:247], v[12:13], v[254:255] op_sel:[0,1,0]
	v_pk_fma_f32 v[252:253], v[240:241], v[14:15], v[252:253] op_sel_hi:[1,0,1]
	v_pk_fma_f32 v[254:255], v[248:249], v[14:15], v[254:255] op_sel_hi:[1,0,1]
	v_pk_fma_f32 v[252:253], v[242:243], v[14:15], v[252:253] op_sel:[0,1,0]
	v_pk_fma_f32 v[254:255], v[250:251], v[14:15], v[254:255] op_sel:[0,1,0]
	v_permlane16_swap_b32_e32 v60, v44
	v_add_f32_e32 v60, v60, v44
	v_add_f32_dpp v28, v30, v29 row_ror:4 row_mask:0xf bank_mask:0xf
	v_add_f32_dpp v16, v140, v140 quad_perm:[1,0,3,2] row_mask:0xf bank_mask:0xf
	v_add_f32_dpp v17, v141, v141 quad_perm:[1,0,3,2] row_mask:0xf bank_mask:0xf
	v_add_f32_dpp v18, v142, v142 quad_perm:[1,0,3,2] row_mask:0xf bank_mask:0xf
	v_add_f32_dpp v19, v143, v143 quad_perm:[1,0,3,2] row_mask:0xf bank_mask:0xf
	v_cndmask_b32_e32 v16, v18, v16, vcc
	v_cndmask_b32_e32 v17, v19, v17, vcc
	v_add_f32_dpp v22, v20, v20 quad_perm:[2,3,0,1] row_mask:0xf bank_mask:0xf
	v_add_f32_dpp v23, v21, v21 quad_perm:[2,3,0,1] row_mask:0xf bank_mask:0xf
	v_cndmask_b32_e64 v20, v23, v22, s[4:5]
	s_waitcnt vmcnt(2)
	v_pk_mul_f32 v[140:141], v[236:237], v[8:9] op_sel_hi:[1,0]
	v_pk_mul_f32 v[142:143], v[244:245], v[8:9] op_sel_hi:[1,0]
	v_pk_fma_f32 v[140:141], v[238:239], v[8:9], v[140:141] op_sel:[0,1,0]
	v_pk_fma_f32 v[142:143], v[246:247], v[8:9], v[142:143] op_sel:[0,1,0]
	v_pk_fma_f32 v[140:141], v[240:241], v[10:11], v[140:141] op_sel_hi:[1,0,1]
	v_pk_fma_f32 v[142:143], v[248:249], v[10:11], v[142:143] op_sel_hi:[1,0,1]
	v_pk_fma_f32 v[140:141], v[242:243], v[10:11], v[140:141] op_sel:[0,1,0]
	v_pk_fma_f32 v[142:143], v[250:251], v[10:11], v[142:143] op_sel:[0,1,0]
	v_add_f32_dpp v12, v252, v252 quad_perm:[1,0,3,2] row_mask:0xf bank_mask:0xf
	v_add_f32_dpp v13, v253, v253 quad_perm:[1,0,3,2] row_mask:0xf bank_mask:0xf
	v_add_f32_dpp v14, v254, v254 quad_perm:[1,0,3,2] row_mask:0xf bank_mask:0xf
	v_add_f32_dpp v15, v255, v255 quad_perm:[1,0,3,2] row_mask:0xf bank_mask:0xf
	v_cndmask_b32_e32 v12, v14, v12, vcc
	v_cndmask_b32_e32 v13, v15, v13, vcc
	v_add_f32_dpp v18, v16, v16 quad_perm:[2,3,0,1] row_mask:0xf bank_mask:0xf
	v_add_f32_dpp v19, v17, v17 quad_perm:[2,3,0,1] row_mask:0xf bank_mask:0xf
	v_cndmask_b32_e64 v16, v19, v18, s[4:5]
	v_cndmask_b32_e64 v21, v16, v20, s[6:7]
	v_cndmask_b32_e64 v22, v20, v16, s[6:7]
	s_waitcnt vmcnt(1)
; DI void lbar() { asm volatile("s_waitcnt lgkmcnt(0)" ::: "memory"); __builtin_amdgcn_s_barrier(); asm volatile("" ::: "memory"); }
; DI float wave_sum(float v) { for (int o = 32; o >= 1; o >>= 1) v += __shfl_xor(v, o); return v; }
; DI void attn_sample_item(const Params& p, int item, ldsp lds, int tid_) {
;     ...
;   SC_SCORE(kvA, 0)
;   SC_SCORE(kvB, 1)
;     ...
;   f32x4 vvA[16], vvB[16];
; #pragma unroll
;   for (int j = 0; j < 16; ++j) vvA[j] = __builtin_nontemporal_load((const f32x4*)(cv + (size_t)(wid * 32 + j) * 1024 + lane * 4));
;   lbar();
;   if (wid < 4) {
;     float v[4]; float mx = -1e30f;
; #pragma unroll
;     for (int j = 0; j < 4; ++j) { v[j] = SC[wid * 256 + j * 64 + lane]; mx = fmaxf(mx, v[j]); }
;     for (int o = 32; o >= 1; o >>= 1) mx = fmaxf(mx, __shfl_xor(mx, o));
;     float s = 0.f;
; #pragma unroll
;     for (int j = 0; j < 4; ++j) { v[j] = __expf(v[j] - mx); s += v[j]; }
;     s = wave_sum(s); const float inv = 1.f / s;
; #pragma unroll
;     for (int j = 0; j < 4; ++j) SC[wid * 256 + j * 64 + lane] = v[j] * inv;
;   }
	v_pk_mul_f32 v[252:253], v[236:237], v[4:5] op_sel_hi:[1,0]
	v_pk_mul_f32 v[254:255], v[244:245], v[4:5] op_sel_hi:[1,0]
	v_pk_fma_f32 v[252:253], v[238:239], v[4:5], v[252:253] op_sel:[0,1,0]
	v_pk_fma_f32 v[254:255], v[246:247], v[4:5], v[254:255] op_sel:[0,1,0]
	v_pk_fma_f32 v[252:253], v[240:241], v[6:7], v[252:253] op_sel_hi:[1,0,1]
	v_pk_fma_f32 v[254:255], v[248:249], v[6:7], v[254:255] op_sel_hi:[1,0,1]
	v_pk_fma_f32 v[252:253], v[242:243], v[6:7], v[252:253] op_sel:[0,1,0]
	v_pk_fma_f32 v[254:255], v[250:251], v[6:7], v[254:255] op_sel:[0,1,0]
	v_add_f32_dpp v20, v22, v21 row_ror:4 row_mask:0xf bank_mask:0xf
	v_cndmask_b32_e64 v29, v20, v28, s[64:65]
	v_cndmask_b32_e64 v30, v28, v20, s[64:65]
	v_add_f32_dpp v8, v140, v140 quad_perm:[1,0,3,2] row_mask:0xf bank_mask:0xf
	v_add_f32_dpp v9, v141, v141 quad_perm:[1,0,3,2] row_mask:0xf bank_mask:0xf
	v_add_f32_dpp v10, v142, v142 quad_perm:[1,0,3,2] row_mask:0xf bank_mask:0xf
	v_add_f32_dpp v11, v143, v143 quad_perm:[1,0,3,2] row_mask:0xf bank_mask:0xf
	v_cndmask_b32_e32 v8, v10, v8, vcc
	v_cndmask_b32_e32 v9, v11, v9, vcc
	v_add_f32_dpp v14, v12, v12 quad_perm:[2,3,0,1] row_mask:0xf bank_mask:0xf
	v_add_f32_dpp v15, v13, v13 quad_perm:[2,3,0,1] row_mask:0xf bank_mask:0xf
	v_cndmask_b32_e64 v12, v15, v14, s[4:5]
	s_waitcnt vmcnt(0)
	v_pk_mul_f32 v[140:141], v[236:237], v[0:1] op_sel_hi:[1,0]
	v_pk_mul_f32 v[142:143], v[244:245], v[0:1] op_sel_hi:[1,0]
	v_pk_fma_f32 v[140:141], v[238:239], v[0:1], v[140:141] op_sel:[0,1,0]
	v_pk_fma_f32 v[142:143], v[246:247], v[0:1], v[142:143] op_sel:[0,1,0]
	v_pk_fma_f32 v[140:141], v[240:241], v[2:3], v[140:141] op_sel_hi:[1,0,1]
	v_pk_fma_f32 v[142:143], v[248:249], v[2:3], v[142:143] op_sel_hi:[1,0,1]
	v_pk_fma_f32 v[140:141], v[242:243], v[2:3], v[140:141] op_sel:[0,1,0]
	v_pk_fma_f32 v[142:143], v[250:251], v[2:3], v[142:143] op_sel:[0,1,0]
	v_add_f32_dpp v28, v30, v29 row_ror:8 row_mask:0xf bank_mask:0xf
	v_add_f32_dpp v4, v252, v252 quad_perm:[1,0,3,2] row_mask:0xf bank_mask:0xf
	v_add_f32_dpp v5, v253, v253 quad_perm:[1,0,3,2] row_mask:0xf bank_mask:0xf
	v_add_f32_dpp v6, v254, v254 quad_perm:[1,0,3,2] row_mask:0xf bank_mask:0xf
	v_add_f32_dpp v7, v255, v255 quad_perm:[1,0,3,2] row_mask:0xf bank_mask:0xf
	v_cndmask_b32_e32 v4, v6, v4, vcc
	v_cndmask_b32_e32 v5, v7, v5, vcc
	v_add_f32_dpp v10, v8, v8 quad_perm:[2,3,0,1] row_mask:0xf bank_mask:0xf
	v_add_f32_dpp v11, v9, v9 quad_perm:[2,3,0,1] row_mask:0xf bank_mask:0xf
	v_cndmask_b32_e64 v8, v11, v10, s[4:5]
	v_cndmask_b32_e64 v13, v8, v12, s[6:7]
	v_cndmask_b32_e64 v14, v12, v8, s[6:7]
	s_nop 1
	v_add_f32_dpp v12, v14, v13 row_ror:4 row_mask:0xf bank_mask:0xf
	v_add_f32_dpp v0, v140, v140 quad_perm:[1,0,3,2] row_mask:0xf bank_mask:0xf
	v_add_f32_dpp v1, v141, v141 quad_perm:[1,0,3,2] row_mask:0xf bank_mask:0xf
	v_add_f32_dpp v2, v142, v142 quad_perm:[1,0,3,2] row_mask:0xf bank_mask:0xf
	v_add_f32_dpp v3, v143, v143 quad_perm:[1,0,3,2] row_mask:0xf bank_mask:0xf
	v_cndmask_b32_e32 v0, v2, v0, vcc
	v_cndmask_b32_e32 v1, v3, v1, vcc
	v_add_f32_dpp v6, v4, v4 quad_perm:[2,3,0,1] row_mask:0xf bank_mask:0xf
	v_add_f32_dpp v7, v5, v5 quad_perm:[2,3,0,1] row_mask:0xf bank_mask:0xf
	v_cndmask_b32_e64 v4, v7, v6, s[4:5]
	v_add_f32_dpp v2, v0, v0 quad_perm:[2,3,0,1] row_mask:0xf bank_mask:0xf
	v_add_f32_dpp v3, v1, v1 quad_perm:[2,3,0,1] row_mask:0xf bank_mask:0xf
	v_cndmask_b32_e64 v0, v3, v2, s[4:5]
	v_cndmask_b32_e64 v5, v0, v4, s[6:7]
	v_cndmask_b32_e64 v6, v4, v0, s[6:7]
	s_nop 1
	v_add_f32_dpp v4, v6, v5 row_ror:4 row_mask:0xf bank_mask:0xf
	v_cndmask_b32_e64 v13, v4, v12, s[64:65]
	v_cndmask_b32_e64 v14, v12, v4, s[64:65]
	s_nop 1
	v_add_f32_dpp v12, v14, v13 row_ror:8 row_mask:0xf bank_mask:0xf
	s_nop 1
	v_permlane16_swap_b32_e32 v28, v12
	v_add_f32_e32 v28, v28, v12
	s_nop 1
	v_permlane32_swap_b32_e32 v60, v28
	v_add_f32_e32 v60, v60, v28
	ds_write_b32 v235, v60 offset:64
	v_lshlrev_b32_e32 v2, 2, v223
	s_waitcnt lgkmcnt(0)
	s_barrier
	v_cmp_gt_i32_e32 vcc, 4, v210
	s_and_saveexec_b64 s[4:5], vcc
	s_cbranch_execz .LBB0_1675
	v_lshlrev_b32_e32 v3, 10, v210
	v_add3_u32 v6, 16, v3, v2
	ds_read2st64_b32 v[2:3], v6 offset1:1
	ds_read2st64_b32 v[4:5], v6 offset0:2 offset1:3
	s_waitcnt lgkmcnt(1)
	v_max3_f32 v7, v2, s35, v3
	s_waitcnt lgkmcnt(0)
	v_max3_f32 v7, v7, v4, v5
	ds_bpermute_b32 v8, v133, v7
	s_waitcnt lgkmcnt(0)
	v_max_f32_e32 v8, v8, v8
	v_max_f32_e32 v7, v7, v8
	ds_bpermute_b32 v8, v132, v7
	s_waitcnt lgkmcnt(0)
	v_max_f32_e32 v8, v8, v8
	v_max_f32_e32 v7, v7, v8
	ds_bpermute_b32 v8, v131, v7
	s_waitcnt lgkmcnt(0)
	v_max_f32_e32 v8, v8, v8
	v_max_f32_e32 v7, v7, v8
	ds_bpermute_b32 v8, v130, v7
	s_waitcnt lgkmcnt(0)
	v_max_f32_e32 v8, v8, v8
	v_max_f32_e32 v7, v7, v8
	ds_bpermute_b32 v8, v129, v7
	s_waitcnt lgkmcnt(0)
	v_max_f32_e32 v8, v8, v8
	v_max_f32_e32 v7, v7, v8
	ds_bpermute_b32 v8, v128, v7
	s_waitcnt lgkmcnt(0)
	v_max_f32_e32 v8, v8, v8
	v_max_f32_e32 v7, v7, v8
	v_sub_f32_e32 v2, v2, v7
	v_sub_f32_e32 v3, v3, v7
	v_mul_f32_e32 v2, 0x3fb8aa3b, v2
	v_sub_f32_e32 v4, v4, v7
	v_mul_f32_e32 v3, 0x3fb8aa3b, v3
	v_exp_f32_e32 v2, v2
	v_sub_f32_e32 v5, v5, v7
	v_mul_f32_e32 v4, 0x3fb8aa3b, v4
	v_exp_f32_e32 v3, v3
	v_mul_f32_e32 v5, 0x3fb8aa3b, v5
	v_exp_f32_e32 v4, v4
	v_exp_f32_e32 v5, v5
	v_add_f32_e32 v7, 0, v2
	v_add_f32_e32 v7, v3, v7
	v_add_f32_e32 v7, v4, v7
	v_add_f32_e32 v7, v5, v7
	ds_bpermute_b32 v8, v133, v7
	s_waitcnt lgkmcnt(0)
	v_add_f32_e32 v7, v7, v8
	ds_bpermute_b32 v8, v132, v7
	s_waitcnt lgkmcnt(0)
	v_add_f32_e32 v7, v7, v8
	ds_bpermute_b32 v8, v131, v7
	s_waitcnt lgkmcnt(0)
	v_add_f32_e32 v7, v7, v8
	ds_bpermute_b32 v8, v130, v7
	s_waitcnt lgkmcnt(0)
	v_add_f32_e32 v7, v7, v8
	ds_bpermute_b32 v8, v129, v7
	s_waitcnt lgkmcnt(0)
	v_add_f32_e32 v7, v7, v8
	ds_bpermute_b32 v8, v128, v7
	s_waitcnt lgkmcnt(0)
	v_add_f32_e32 v7, v7, v8
	v_div_scale_f32 v8, s[6:7], v7, v7, 1.0
	v_rcp_f32_e32 v9, v8
	v_div_scale_f32 v10, vcc, 1.0, v7, 1.0
	v_fma_f32 v11, -v8, v9, 1.0
	v_fmac_f32_e32 v9, v11, v9
	v_mul_f32_e32 v11, v10, v9
	v_fma_f32 v12, -v8, v11, v10
	v_fmac_f32_e32 v11, v12, v9
	v_fma_f32 v8, -v8, v11, v10
	v_div_fmas_f32 v8, v8, v9, v11
	v_div_fixup_f32 v7, v8, v7, 1.0
	v_mul_f32_e32 v2, v2, v7
	v_mul_f32_e32 v3, v3, v7
	v_mul_f32_e32 v4, v4, v7
	v_mul_f32_e32 v5, v5, v7
	ds_write2st64_b32 v6, v2, v3 offset1:1
	ds_write2st64_b32 v6, v4, v5 offset0:2 offset1:3
	s_branch .LBB0_1675
